# GEMM k-loops (6 of 256x128): back edge rotated to a head barrier, next-load address arithmetic hoisted above the barriers, on top of v_qklds
# speedup vs baseline: 1.0024x; 1.0024x over previous
.LBB0_207:
	s_ashr_i32 s0, s64, 3
	s_lshr_b32 s1, s0, 28
	s_add_i32 s1, s0, s1
	s_and_b32 s5, s1, -16
	s_and_b32 s4, s64, 1
	s_sub_i32 s26, s0, s5
	s_lshr_b32 s5, s0, 6
	s_mul_i32 s5, s5, 5
	s_add_i32 s26, s26, s5
	s_and_b32 s26, s26, 15
	s_lshl_b32 s0, s1, 6
	s_lshl_b32 s1, s64, 7
	s_lshl_b32 s26, s26, 1
	s_and_b32 s0, s0, 0xfffffc00
	s_and_b32 s1, s1, 0x300
	s_or_b32 s26, s26, s4
	s_or_b32 s4, s0, s1
	s_ashr_i32 s5, s4, 31
	s_lshl_b32 s0, s26, 7
	s_lshl_b64 s[52:53], s[4:5], 11
	s_add_u32 s52, s3, s52
	s_addc_u32 s53, s34, s53
	s_ashr_i32 s1, s0, 31
	v_mov_b32_e32 v34, v220
	s_lshl_b64 s[54:55], s[0:1], 11
	s_add_u32 s54, s72, s54
	v_ashrrev_i32_e32 v24, 2, v34
	v_ashrrev_i32_e32 v25, 31, v24
	s_addc_u32 s55, s73, s55
	v_lshlrev_b64 v[0:1], 11, v[24:25]
	v_lshlrev_b32_e32 v4, 4, v34
	v_lshl_add_u64 v[2:3], s[54:55], 0, v[0:1]
	v_lshl_add_u64 v[0:1], s[52:53], 0, v[0:1]
	v_and_b32_e32 v152, 48, v4
	v_lshl_add_u64 v[154:155], v[0:1], 0, v[152:153]
	v_add_co_u32_e32 v26, vcc, s35, v154
	v_lshl_add_u64 v[156:157], v[2:3], 0, v[152:153]
	s_nop 0
	v_addc_co_u32_e32 v27, vcc, 0, v155, vcc
	v_add_co_u32_e32 v28, vcc, s36, v154
	global_load_dwordx4 v[0:3], v[154:155], off
	s_nop 0
	v_addc_co_u32_e32 v29, vcc, 0, v155, vcc
	v_add_co_u32_e32 v30, vcc, s37, v154
	global_load_dwordx4 v[4:7], v[26:27], off
	global_load_dwordx4 v[8:11], v[28:29], off
	v_addc_co_u32_e32 v31, vcc, 0, v155, vcc
	v_add_co_u32_e32 v32, vcc, s35, v156
	global_load_dwordx4 v[12:15], v[30:31], off
	global_load_dwordx4 v[16:19], v[156:157], off
	v_addc_co_u32_e32 v33, vcc, 0, v157, vcc
	global_load_dwordx4 v[20:23], v[32:33], off
	global_load_dwordx4 v[128:131], v[154:155], off offset:64
	global_load_dwordx4 v[136:139], v[26:27], off offset:64
	global_load_dwordx4 v[140:143], v[28:29], off offset:64
	global_load_dwordx4 v[144:147], v[30:31], off offset:64
	global_load_dwordx4 v[132:135], v[156:157], off offset:64
	global_load_dwordx4 v[148:151], v[32:33], off offset:64
	v_lshrrev_b32_e32 v35, 4, v34
	v_lshrrev_b32_e32 v36, 2, v34
	v_sub_u32_e32 v39, 0, v35
	v_sub_u32_e32 v36, 0, v36
	v_and_b32_e32 v37, 0x3ffff8f, v34
	v_lshlrev_b32_e32 v38, 6, v34
	v_xor_b32_e32 v34, v34, v39
	v_xor_b32_e32 v35, v35, v36
	v_lshlrev_b32_e32 v34, 4, v34
	v_lshlrev_b32_e32 v35, 4, v35
	v_mov_b32_e32 v25, 0x4000
	v_and_b32_e32 v40, 0x1000, v38
	v_and_b32_e32 v34, 48, v34
	v_and_b32_e32 v35, 48, v35
	v_and_b32_e32 v41, 0x3c0, v38
	v_and_b32_e32 v38, 0xffffe3c0, v38
	v_lshl_add_u32 v25, v37, 6, v25
	v_lshl_or_b32 v152, v24, 6, v34
	v_or_b32_e32 v24, v35, v40
	s_mov_b32 s1, -2
	v_or3_b32 v175, v40, v41, v35
	v_add_u32_e32 v176, v35, v38
	v_add_u32_e32 v177, v35, v25
	v_add_u32_e32 v178, v24, v41
	v_lshl_add_u64 v[158:159], v[154:155], 0, s[22:23]
	v_lshl_add_u64 v[160:161], v[154:155], 0, s[24:25]
	v_lshl_add_u64 v[162:163], v[154:155], 0, s[28:29]
	v_lshl_add_u64 v[164:165], v[156:157], 0, s[22:23]
	s_mov_b32 s5, s31
	v_mov_b32_e32 v64, 0
	v_mov_b32_e32 v65, v153
	v_mov_b32_e32 v66, v153
	v_mov_b32_e32 v67, v153
	v_mov_b32_e32 v68, 0
	v_mov_b32_e32 v69, v153
	v_mov_b32_e32 v70, v153
	v_mov_b32_e32 v71, v153
	v_mov_b32_e32 v72, 0
	v_mov_b32_e32 v73, v153
	v_mov_b32_e32 v74, v153
	v_mov_b32_e32 v75, v153
	v_mov_b32_e32 v76, 0
	v_mov_b32_e32 v77, v153
	v_mov_b32_e32 v78, v153
	v_mov_b32_e32 v79, v153
	v_mov_b32_e32 v80, 0
	s_waitcnt vmcnt(11)
	ds_write_b128 v152, v[0:3]
	s_waitcnt vmcnt(10)
	ds_write_b128 v152, v[4:7] offset:4096
	s_waitcnt vmcnt(9)
	ds_write_b128 v152, v[8:11] offset:8192
	s_waitcnt vmcnt(8)
	ds_write_b128 v152, v[12:15] offset:12288
	s_waitcnt vmcnt(7)
	ds_write_b128 v152, v[16:19] offset:32768
	s_waitcnt vmcnt(6)
	ds_write_b128 v152, v[20:23] offset:36864
	v_mov_b32_e32 v0, 0
	v_mov_b32_e32 v1, v153
	v_mov_b32_e32 v2, v153
	v_mov_b32_e32 v3, v153
	v_mov_b32_e32 v4, 0
	v_mov_b32_e32 v5, v153
	v_mov_b32_e32 v6, v153
	v_mov_b32_e32 v7, v153
	v_mov_b32_e32 v8, 0
	v_mov_b32_e32 v9, v153
	v_mov_b32_e32 v10, v153
	v_mov_b32_e32 v11, v153
	v_mov_b32_e32 v12, 0
	v_mov_b32_e32 v13, v153
	v_mov_b32_e32 v14, v153
	v_mov_b32_e32 v15, v153
	v_mov_b32_e32 v16, 0
	v_mov_b32_e32 v17, v153
	v_mov_b32_e32 v18, v153
	v_mov_b32_e32 v19, v153
	v_mov_b32_e32 v20, 0
	v_mov_b32_e32 v21, v153
	v_mov_b32_e32 v22, v153
	v_mov_b32_e32 v23, v153
	v_mov_b32_e32 v81, v153
	v_mov_b32_e32 v82, v153
	v_mov_b32_e32 v83, v153
	v_mov_b32_e32 v84, 0
	v_mov_b32_e32 v85, v153
	v_mov_b32_e32 v86, v153
	v_mov_b32_e32 v87, v153
	v_mov_b32_e32 v24, 0
	v_mov_b32_e32 v25, v153
	v_mov_b32_e32 v26, v153
	v_mov_b32_e32 v27, v153
	v_mov_b32_e32 v28, 0
	v_mov_b32_e32 v29, v153
	v_mov_b32_e32 v30, v153
	v_mov_b32_e32 v31, v153
	v_mov_b32_e32 v88, 0
	v_mov_b32_e32 v89, v153
	v_mov_b32_e32 v90, v153
	v_mov_b32_e32 v91, v153
	v_mov_b32_e32 v92, 0
	v_mov_b32_e32 v93, v153
	v_mov_b32_e32 v94, v153
	v_mov_b32_e32 v95, v153
	v_mov_b32_e32 v32, 0
	v_mov_b32_e32 v33, v153
	v_mov_b32_e32 v34, v153
	v_mov_b32_e32 v35, v153
	v_mov_b32_e32 v36, 0
	v_mov_b32_e32 v37, v153
	v_mov_b32_e32 v38, v153
	v_mov_b32_e32 v39, v153
	v_mov_b32_e32 v96, 0
	v_mov_b32_e32 v97, v153
	v_mov_b32_e32 v98, v153
	v_mov_b32_e32 v99, v153
	v_mov_b32_e32 v100, 0
	v_mov_b32_e32 v101, v153
	v_mov_b32_e32 v102, v153
	v_mov_b32_e32 v103, v153
	v_mov_b32_e32 v40, 0
	v_mov_b32_e32 v41, v153
	v_mov_b32_e32 v42, v153
	v_mov_b32_e32 v43, v153
	v_mov_b32_e32 v44, 0
	v_mov_b32_e32 v45, v153
	v_mov_b32_e32 v46, v153
	v_mov_b32_e32 v47, v153
	v_mov_b32_e32 v104, 0
	v_mov_b32_e32 v105, v153
	v_mov_b32_e32 v106, v153
	v_mov_b32_e32 v107, v153
	v_mov_b32_e32 v108, 0
	v_mov_b32_e32 v109, v153
	v_mov_b32_e32 v110, v153
	v_mov_b32_e32 v111, v153
	v_mov_b32_e32 v48, 0
	v_mov_b32_e32 v49, v153
	v_mov_b32_e32 v50, v153
	v_mov_b32_e32 v51, v153
	v_mov_b32_e32 v52, 0
	v_mov_b32_e32 v53, v153
	v_mov_b32_e32 v54, v153
	v_mov_b32_e32 v55, v153
	v_mov_b32_e32 v112, 0
	v_mov_b32_e32 v113, v153
	v_mov_b32_e32 v114, v153
	v_mov_b32_e32 v115, v153
	v_mov_b32_e32 v116, 0
	v_mov_b32_e32 v117, v153
	v_mov_b32_e32 v118, v153
	v_mov_b32_e32 v119, v153
	v_mov_b32_e32 v56, 0
	v_mov_b32_e32 v57, v153
	v_mov_b32_e32 v58, v153
	v_mov_b32_e32 v59, v153
	v_mov_b32_e32 v60, 0
	v_mov_b32_e32 v61, v153
	v_mov_b32_e32 v62, v153
	v_mov_b32_e32 v63, v153
	v_mov_b32_e32 v120, 0
	v_mov_b32_e32 v121, v153
	v_mov_b32_e32 v122, v153
	v_mov_b32_e32 v123, v153
	v_mov_b32_e32 v124, 0
	v_mov_b32_e32 v125, v153
	v_mov_b32_e32 v126, v153
	v_mov_b32_e32 v127, v153
	s_waitcnt lgkmcnt(0)
	s_add_i32 s27, s5, 64
	s_min_u32 s30, s27, 0x3e0
	s_lshl_b32 s30, s30, 1
	v_lshl_add_u64 v[180:181], v[154:155], 0, s[30:31]
	v_lshl_add_u64 v[184:185], v[158:159], 0, s[30:31]
	v_lshl_add_u64 v[188:189], v[160:161], 0, s[30:31]
	v_lshl_add_u64 v[192:193], v[162:163], 0, s[30:31]
	v_lshl_add_u64 v[196:197], v[156:157], 0, s[30:31]
	v_lshl_add_u64 v[200:201], v[164:165], 0, s[30:31]
.Lrot_5:
	s_barrier
.LBB0_208:
	global_load_dwordx4 v[180:183], v[180:181], off
	ds_read_b128 v[204:207], v178 offset:32768
	global_load_dwordx4 v[184:187], v[184:185], off
	ds_read_b128 v[208:211], v178 offset:33792
	global_load_dwordx4 v[188:191], v[188:189], off
	ds_read_b128 v[212:215], v178 offset:34816
	global_load_dwordx4 v[192:195], v[192:193], off
	ds_read_b128 v[216:219], v178 offset:35840
	global_load_dwordx4 v[196:199], v[196:197], off
	ds_read_b128 v[222:225], v176
	global_load_dwordx4 v[200:203], v[200:201], off
	ds_read_b128 v[226:229], v176 offset:1024
	ds_read_b128 v[230:233], v176 offset:2048
	ds_read_b128 v[234:237], v176 offset:3072
	ds_read_b128 v[238:241], v176 offset:4096
	ds_read_b128 v[242:245], v176 offset:5120
	ds_read_b128 v[246:249], v176 offset:6144
	ds_read_b128 v[250:253], v176 offset:7168
	s_setprio 1
	s_waitcnt lgkmcnt(7)
	v_mfma_f32_16x16x32_bf16 v[124:127], v[222:225], v[204:207], v[124:127]
	v_mfma_f32_16x16x32_bf16 v[120:123], v[222:225], v[208:211], v[120:123]
	v_mfma_f32_16x16x32_bf16 v[60:63], v[222:225], v[212:215], v[60:63]
	v_mfma_f32_16x16x32_bf16 v[56:59], v[222:225], v[216:219], v[56:59]
	s_waitcnt vmcnt(11)
	ds_write_b128 v152, v[128:131] offset:16384
	s_waitcnt lgkmcnt(7)
	v_mfma_f32_16x16x32_bf16 v[116:119], v[226:229], v[204:207], v[116:119]
	v_mfma_f32_16x16x32_bf16 v[112:115], v[226:229], v[208:211], v[112:115]
	v_mfma_f32_16x16x32_bf16 v[52:55], v[226:229], v[212:215], v[52:55]
	v_mfma_f32_16x16x32_bf16 v[48:51], v[226:229], v[216:219], v[48:51]
	s_waitcnt vmcnt(9)
	ds_write_b128 v152, v[136:139] offset:20480
	s_waitcnt lgkmcnt(7)
	v_mfma_f32_16x16x32_bf16 v[108:111], v[230:233], v[204:207], v[108:111]
	v_mfma_f32_16x16x32_bf16 v[104:107], v[230:233], v[208:211], v[104:107]
	v_mfma_f32_16x16x32_bf16 v[44:47], v[230:233], v[212:215], v[44:47]
	v_mfma_f32_16x16x32_bf16 v[40:43], v[230:233], v[216:219], v[40:43]
	s_waitcnt vmcnt(8)
	ds_write_b128 v152, v[140:143] offset:24576
	s_waitcnt lgkmcnt(7)
	v_mfma_f32_16x16x32_bf16 v[100:103], v[234:237], v[204:207], v[100:103]
	v_mfma_f32_16x16x32_bf16 v[96:99], v[234:237], v[208:211], v[96:99]
	v_mfma_f32_16x16x32_bf16 v[36:39], v[234:237], v[212:215], v[36:39]
	v_mfma_f32_16x16x32_bf16 v[32:35], v[234:237], v[216:219], v[32:35]
	s_waitcnt vmcnt(7)
	ds_write_b128 v152, v[144:147] offset:28672
	s_waitcnt lgkmcnt(7)
	v_mfma_f32_16x16x32_bf16 v[92:95], v[238:241], v[204:207], v[92:95]
	v_mfma_f32_16x16x32_bf16 v[88:91], v[238:241], v[208:211], v[88:91]
	v_mfma_f32_16x16x32_bf16 v[28:31], v[238:241], v[212:215], v[28:31]
	v_mfma_f32_16x16x32_bf16 v[24:27], v[238:241], v[216:219], v[24:27]
	s_waitcnt vmcnt(7)
	ds_write_b128 v152, v[132:135] offset:40960
	s_waitcnt lgkmcnt(7)
	v_mfma_f32_16x16x32_bf16 v[84:87], v[242:245], v[204:207], v[84:87]
	v_mfma_f32_16x16x32_bf16 v[80:83], v[242:245], v[208:211], v[80:83]
	v_mfma_f32_16x16x32_bf16 v[20:23], v[242:245], v[212:215], v[20:23]
	v_mfma_f32_16x16x32_bf16 v[16:19], v[242:245], v[216:219], v[16:19]
	s_waitcnt vmcnt(6)
	ds_write_b128 v152, v[148:151] offset:45056
	s_waitcnt lgkmcnt(7)
	v_mfma_f32_16x16x32_bf16 v[76:79], v[246:249], v[204:207], v[76:79]
	v_mfma_f32_16x16x32_bf16 v[72:75], v[246:249], v[208:211], v[72:75]
	v_mfma_f32_16x16x32_bf16 v[12:15], v[246:249], v[212:215], v[12:15]
	v_mfma_f32_16x16x32_bf16 v[8:11], v[246:249], v[216:219], v[8:11]
	s_waitcnt lgkmcnt(6)
	v_mfma_f32_16x16x32_bf16 v[68:71], v[250:253], v[204:207], v[68:71]
	v_mfma_f32_16x16x32_bf16 v[64:67], v[250:253], v[208:211], v[64:67]
	v_mfma_f32_16x16x32_bf16 v[4:7], v[250:253], v[212:215], v[4:7]
	v_mfma_f32_16x16x32_bf16 v[0:3], v[250:253], v[216:219], v[0:3]
	s_setprio 0
	s_min_u32 s5, s5, 0x380
	s_lshl_b32 s30, s5, 1
	s_mov_b32 s53, s31
	s_add_i32 s52, s30, 0xc0
	v_lshl_add_u64 v[128:129], v[154:155], 0, s[30:31]
	v_lshl_add_u64 v[132:133], v[156:157], 0, s[30:31]
	v_lshl_add_u64 v[136:137], v[158:159], 0, s[52:53]
	v_lshl_add_u64 v[140:141], v[160:161], 0, s[52:53]
	v_lshl_add_u64 v[144:145], v[162:163], 0, s[52:53]
	v_lshl_add_u64 v[148:149], v[164:165], 0, s[52:53]
	s_waitcnt lgkmcnt(0)
	s_barrier
	global_load_dwordx4 v[128:131], v[128:129], off offset:192
	ds_read_b128 v[204:207], v175 offset:40960
	global_load_dwordx4 v[132:135], v[132:133], off offset:192
	ds_read_b128 v[208:211], v175 offset:41984
	global_load_dwordx4 v[136:139], v[136:137], off
	ds_read_b128 v[212:215], v175 offset:43008
	global_load_dwordx4 v[140:143], v[140:141], off
	ds_read_b128 v[216:219], v175 offset:44032
	global_load_dwordx4 v[144:147], v[144:145], off
	ds_read_b128 v[222:225], v177
	global_load_dwordx4 v[148:151], v[148:149], off
	ds_read_b128 v[226:229], v177 offset:1024
	ds_read_b128 v[230:233], v177 offset:2048
	ds_read_b128 v[234:237], v177 offset:3072
	ds_read_b128 v[238:241], v177 offset:4096
	ds_read_b128 v[242:245], v177 offset:5120
	ds_read_b128 v[246:249], v177 offset:6144
	ds_read_b128 v[250:253], v177 offset:7168
	s_setprio 1
	s_waitcnt lgkmcnt(7)
	v_mfma_f32_16x16x32_bf16 v[124:127], v[222:225], v[204:207], v[124:127]
	v_mfma_f32_16x16x32_bf16 v[120:123], v[222:225], v[208:211], v[120:123]
	v_mfma_f32_16x16x32_bf16 v[60:63], v[222:225], v[212:215], v[60:63]
	v_mfma_f32_16x16x32_bf16 v[56:59], v[222:225], v[216:219], v[56:59]
	s_waitcnt vmcnt(11)
	ds_write_b128 v152, v[180:183]
	s_waitcnt lgkmcnt(7)
	v_mfma_f32_16x16x32_bf16 v[116:119], v[226:229], v[204:207], v[116:119]
	v_mfma_f32_16x16x32_bf16 v[112:115], v[226:229], v[208:211], v[112:115]
	v_mfma_f32_16x16x32_bf16 v[52:55], v[226:229], v[212:215], v[52:55]
	v_mfma_f32_16x16x32_bf16 v[48:51], v[226:229], v[216:219], v[48:51]
	s_waitcnt vmcnt(10)
	ds_write_b128 v152, v[184:187] offset:4096
	s_waitcnt lgkmcnt(7)
	v_mfma_f32_16x16x32_bf16 v[108:111], v[230:233], v[204:207], v[108:111]
	v_mfma_f32_16x16x32_bf16 v[104:107], v[230:233], v[208:211], v[104:107]
	v_mfma_f32_16x16x32_bf16 v[44:47], v[230:233], v[212:215], v[44:47]
	v_mfma_f32_16x16x32_bf16 v[40:43], v[230:233], v[216:219], v[40:43]
	s_waitcnt vmcnt(9)
	ds_write_b128 v152, v[188:191] offset:8192
	s_waitcnt lgkmcnt(7)
	v_mfma_f32_16x16x32_bf16 v[100:103], v[234:237], v[204:207], v[100:103]
	v_mfma_f32_16x16x32_bf16 v[96:99], v[234:237], v[208:211], v[96:99]
	v_mfma_f32_16x16x32_bf16 v[36:39], v[234:237], v[212:215], v[36:39]
	v_mfma_f32_16x16x32_bf16 v[32:35], v[234:237], v[216:219], v[32:35]
	s_waitcnt vmcnt(8)
	ds_write_b128 v152, v[192:195] offset:12288
	s_waitcnt lgkmcnt(7)
	v_mfma_f32_16x16x32_bf16 v[92:95], v[238:241], v[204:207], v[92:95]
	v_mfma_f32_16x16x32_bf16 v[88:91], v[238:241], v[208:211], v[88:91]
	v_mfma_f32_16x16x32_bf16 v[28:31], v[238:241], v[212:215], v[28:31]
	v_mfma_f32_16x16x32_bf16 v[24:27], v[238:241], v[216:219], v[24:27]
	s_waitcnt vmcnt(7)
	ds_write_b128 v152, v[196:199] offset:32768
	s_waitcnt lgkmcnt(7)
	v_mfma_f32_16x16x32_bf16 v[84:87], v[242:245], v[204:207], v[84:87]
	v_mfma_f32_16x16x32_bf16 v[80:83], v[242:245], v[208:211], v[80:83]
	v_mfma_f32_16x16x32_bf16 v[20:23], v[242:245], v[212:215], v[20:23]
	v_mfma_f32_16x16x32_bf16 v[16:19], v[242:245], v[216:219], v[16:19]
	s_waitcnt vmcnt(6)
	ds_write_b128 v152, v[200:203] offset:36864
	s_waitcnt lgkmcnt(7)
	v_mfma_f32_16x16x32_bf16 v[76:79], v[246:249], v[204:207], v[76:79]
	v_mfma_f32_16x16x32_bf16 v[72:75], v[246:249], v[208:211], v[72:75]
	v_mfma_f32_16x16x32_bf16 v[12:15], v[246:249], v[212:215], v[12:15]
	v_mfma_f32_16x16x32_bf16 v[8:11], v[246:249], v[216:219], v[8:11]
	s_waitcnt lgkmcnt(6)
	v_mfma_f32_16x16x32_bf16 v[68:71], v[250:253], v[204:207], v[68:71]
	v_mfma_f32_16x16x32_bf16 v[64:67], v[250:253], v[208:211], v[64:67]
	v_mfma_f32_16x16x32_bf16 v[4:7], v[250:253], v[212:215], v[4:7]
	v_mfma_f32_16x16x32_bf16 v[0:3], v[250:253], v[216:219], v[0:3]
	s_setprio 0
	s_add_i32 s1, s1, 2
	s_mov_b32 s5, s27
	s_add_i32 s27, s5, 64
	s_min_u32 s30, s27, 0x3e0
	s_lshl_b32 s30, s30, 1
	v_lshl_add_u64 v[180:181], v[154:155], 0, s[30:31]
	v_lshl_add_u64 v[184:185], v[158:159], 0, s[30:31]
	v_lshl_add_u64 v[188:189], v[160:161], 0, s[30:31]
	v_lshl_add_u64 v[192:193], v[162:163], 0, s[30:31]
	v_lshl_add_u64 v[196:197], v[156:157], 0, s[30:31]
	v_lshl_add_u64 v[200:201], v[164:165], 0, s[30:31]
	s_cmp_lt_u32 s1, 30
	s_waitcnt lgkmcnt(0)
	s_cbranch_scc1 .Lrot_5
	s_barrier
	s_waitcnt vmcnt(5)
	v_mov_b32_e32 v128, v220
	s_cmp_gt_i32 s26, 15
	v_and_b32_e32 v158, 15, v128
	v_and_b32_e32 v160, 64, v128
	v_and_b32_e32 v129, 0xffffff80, v128
	v_lshrrev_b32_e32 v128, 2, v128
	v_add_u32_e32 v130, s4, v129
	v_and_b32_e32 v159, 12, v128
	s_waitcnt vmcnt(3)
	v_or_b32_e32 v136, v130, v159
	v_ashrrev_i32_e32 v128, 14, v130
	s_waitcnt vmcnt(0)
	v_or_b32_e32 v150, 16, v136
	v_or_b32_e32 v148, 32, v136
	v_or_b32_e32 v146, 48, v136
	v_or_b32_e32 v142, 64, v136
	v_or_b32_e32 v140, 0x50, v136
	v_or_b32_e32 v138, 0x60, v136
	v_or_b32_e32 v134, 0x70, v136
	s_mov_b64 s[4:5], -1
	v_ashrrev_i32_e32 v137, 31, v136
	v_lshlrev_b32_e32 v132, 1, v159
	v_mov_b32_e32 v250, s0
	v_and_b32_e32 v250, 0x80, v250
	v_add_u32_e32 v250, v250, v160
	v_mul_u32_u24_e32 v250, 30, v250
	v_lshrrev_b32_e32 v251, 3, v158
	v_mul_u32_u24_e32 v251, 0xf0, v251
	v_add_u32_e32 v250, v250, v251
	v_lshrrev_b32_e32 v251, 2, v159
	v_mul_u32_u24_e32 v251, 0x7c0, v251
	v_sub_u32_e32 v250, v250, v251
	v_ashrrev_i32_e32 v251, 31, v250
	v_and_b32_e32 v252, 8, v159
	v_lshlrev_b32_e32 v252, 5, v252
	v_and_b32_e32 v253, 4, v159
	v_lshl_or_b32 v252, v253, 1, v252
	v_lshl_or_b32 v252, v158, 4, v252
	v_mov_b32_e32 v253, 0
	v_ashrrev_i32_e32 v129, 31, v128
	v_ashrrev_i32_e32 v151, 31, v150
	v_ashrrev_i32_e32 v149, 31, v148
	v_ashrrev_i32_e32 v147, 31, v146
	v_ashrrev_i32_e32 v143, 31, v142
	v_ashrrev_i32_e32 v141, 31, v140
	v_ashrrev_i32_e32 v139, 31, v138
	v_ashrrev_i32_e32 v135, 31, v134
	s_cbranch_scc0 .LBB0_211
	v_lshl_add_u64 v[144:145], v[136:137], 2, s[8:9]
	global_load_dwordx4 v[162:165], v[144:145], off
	s_add_i32 s1, s0, 0xfffff800
	s_and_b32 s5, s0, 0x180
	s_ashr_i32 s4, s1, 9
	v_or_b32_e32 v154, s5, v160
	s_ashr_i32 s5, s4, 31
	v_lshlrev_b64 v[144:145], 9, v[128:129]
	s_lshl_b64 s[4:5], s[4:5], 7
	v_lshrrev_b32_e32 v152, 7, v130
	v_lshl_add_u64 v[130:131], v[144:145], 0, s[4:5]
	v_and_or_b32 v130, v152, s38, v130
	v_lshlrev_b64 v[130:131], 16, v[130:131]
	v_mov_b32_e32 v133, v153
	v_lshl_or_b32 v130, v154, 7, v130
	v_lshl_add_u64 v[178:179], s[12:13], 0, v[252:253]
	v_mov_b32_e32 v145, v131
	v_mov_b32_e32 v181, v131
	v_lshlrev_b64 v[156:157], 1, v[130:131]
	v_or_b32_e32 v144, 0x800, v130
	v_or_b32_e32 v180, 0x1000, v130
	v_or_b32_e32 v130, 0x1800, v130
	v_lshl_add_u64 v[182:183], v[178:179], 0, v[156:157]
	v_lshlrev_b64 v[154:155], 1, v[144:145]
	v_lshlrev_b64 v[144:145], 1, v[180:181]
	v_lshlrev_b64 v[130:131], 1, v[130:131]
	v_lshl_add_u64 v[176:177], v[150:151], 2, s[8:9]
	v_lshl_add_u64 v[180:181], v[178:179], 0, v[154:155]
	v_lshl_add_u64 v[184:185], v[178:179], 0, v[144:145]
	v_lshl_add_u64 v[178:179], v[178:179], 0, v[130:131]
	s_waitcnt vmcnt(0)
	v_mul_f32_e32 v133, v124, v162
	v_mul_f32_e32 v152, v125, v163
	v_mul_f32_e32 v161, v126, v164
	v_mul_f32_e32 v175, v127, v165
	v_mul_f32_e32 v186, v120, v162
	v_mul_f32_e32 v187, v121, v163
	v_mul_f32_e32 v188, v122, v164
	v_mul_f32_e32 v189, v123, v165
	v_mul_f32_e32 v190, v60, v162
	v_mul_f32_e32 v191, v61, v163
	v_mul_f32_e32 v194, v56, v162
	v_mul_f32_e32 v195, v57, v163
	v_cvt_pk_bf16_f32 v162, v133, v152
	v_cvt_pk_bf16_f32 v163, v161, v175
	v_mul_f32_e32 v192, v62, v164
	v_mul_f32_e32 v193, v63, v165
	v_mul_f32_e32 v196, v58, v164
	v_mul_f32_e32 v197, v59, v165
	v_cvt_pk_bf16_f32 v164, v186, v187
	v_cvt_pk_bf16_f32 v165, v188, v189
	v_cvt_pk_bf16_f32 v186, v190, v191
	v_cvt_pk_bf16_f32 v187, v192, v193
	v_cvt_pk_bf16_f32 v188, v194, v195
	v_cvt_pk_bf16_f32 v189, v196, v197
	global_store_dwordx2 v[182:183], v[162:163], off
	global_store_dwordx2 v[180:181], v[164:165], off
	global_store_dwordx2 v[184:185], v[186:187], off
	global_store_dwordx2 v[178:179], v[188:189], off
	global_load_dwordx4 v[162:165], v[176:177], off
	v_bitop3_b32 v133, v136, 28, 16 bitop3:0xc8
	v_lshlrev_b32_e32 v152, 1, v133
	v_lshl_add_u64 v[178:179], s[12:13], 0, v[252:253]
	v_lshl_add_u64 v[180:181], v[178:179], 0, v[156:157]
	v_lshl_add_u64 v[176:177], v[148:149], 2, s[8:9]
	v_lshl_add_u64 v[182:183], v[178:179], 0, v[154:155]
	v_lshl_add_u64 v[184:185], v[178:179], 0, v[144:145]
	v_lshl_add_u64 v[178:179], v[178:179], 0, v[130:131]
	s_waitcnt vmcnt(0)
	v_mul_f32_e32 v133, v116, v162
	v_mul_f32_e32 v152, v117, v163
	v_mul_f32_e32 v161, v118, v164
	v_mul_f32_e32 v175, v119, v165
	v_mul_f32_e32 v186, v112, v162
	v_mul_f32_e32 v187, v113, v163
	v_mul_f32_e32 v188, v114, v164
	v_mul_f32_e32 v189, v115, v165
	global_load_dwordx4 v[116:119], v[176:177], off
	v_mul_f32_e32 v190, v52, v162
	v_mul_f32_e32 v191, v53, v163
	v_mul_f32_e32 v194, v48, v162
	v_mul_f32_e32 v195, v49, v163
	v_cvt_pk_bf16_f32 v162, v133, v152
	v_cvt_pk_bf16_f32 v163, v161, v175
	v_mul_f32_e32 v192, v54, v164
	v_mul_f32_e32 v193, v55, v165
	v_mul_f32_e32 v196, v50, v164
	v_mul_f32_e32 v197, v51, v165
	v_cvt_pk_bf16_f32 v164, v186, v187
	v_cvt_pk_bf16_f32 v165, v188, v189
	v_cvt_pk_bf16_f32 v186, v190, v191
	v_cvt_pk_bf16_f32 v187, v192, v193
	v_cvt_pk_bf16_f32 v188, v194, v195
	v_cvt_pk_bf16_f32 v189, v196, v197
	global_store_dwordx2 v[180:181], v[162:163], off offset:512
	global_store_dwordx2 v[182:183], v[164:165], off offset:512
	global_store_dwordx2 v[184:185], v[186:187], off offset:512
	global_store_dwordx2 v[178:179], v[188:189], off offset:512
	v_bitop3_b32 v133, v136, 44, 32 bitop3:0xc8
	v_lshlrev_b32_e32 v152, 1, v133
	v_lshl_add_u64 v[178:179], s[12:13], 0, v[252:253]
	v_lshl_add_u64 v[180:181], v[178:179], 0, v[156:157]
	v_lshl_add_u64 v[176:177], v[146:147], 2, s[8:9]
	global_load_dwordx4 v[112:115], v[176:177], off
	v_lshl_add_u64 v[182:183], v[178:179], 0, v[154:155]
	v_lshl_add_u64 v[184:185], v[178:179], 0, v[144:145]
	v_lshl_add_u64 v[178:179], v[178:179], 0, v[130:131]
	s_waitcnt vmcnt(5)
	v_mov_b32_e32 v162, v116
	v_mov_b32_e32 v163, v117
	v_mov_b32_e32 v164, v118
	v_mov_b32_e32 v165, v119
	v_mul_f32_e32 v133, v108, v162
	v_mul_f32_e32 v152, v109, v163
	v_mul_f32_e32 v161, v110, v164
	v_mul_f32_e32 v175, v111, v165
	v_mul_f32_e32 v186, v104, v162
	v_mul_f32_e32 v187, v105, v163
	v_mul_f32_e32 v188, v106, v164
	v_mul_f32_e32 v189, v107, v165
	v_mul_f32_e32 v190, v44, v162
	v_mul_f32_e32 v191, v45, v163
	v_mul_f32_e32 v194, v40, v162
	v_mul_f32_e32 v195, v41, v163
	v_cvt_pk_bf16_f32 v162, v133, v152
	v_cvt_pk_bf16_f32 v163, v161, v175
	v_mul_f32_e32 v192, v46, v164
	v_mul_f32_e32 v193, v47, v165
	v_mul_f32_e32 v196, v42, v164
	v_mul_f32_e32 v197, v43, v165
	v_cvt_pk_bf16_f32 v164, v186, v187
	v_cvt_pk_bf16_f32 v165, v188, v189
	v_cvt_pk_bf16_f32 v186, v190, v191
	v_cvt_pk_bf16_f32 v187, v192, v193
	v_cvt_pk_bf16_f32 v188, v194, v195
	v_cvt_pk_bf16_f32 v189, v196, v197
	global_store_dwordx2 v[180:181], v[162:163], off offset:1024
	global_store_dwordx2 v[182:183], v[164:165], off offset:1024
	global_store_dwordx2 v[184:185], v[186:187], off offset:1024
	global_store_dwordx2 v[178:179], v[188:189], off offset:1024
	v_bitop3_b32 v133, v136, 60, 48 bitop3:0xc8
	v_lshlrev_b32_e32 v152, 1, v133
	v_lshl_add_u64 v[178:179], s[12:13], 0, v[252:253]
	v_lshl_add_u64 v[180:181], v[178:179], 0, v[156:157]
	v_lshl_add_u64 v[176:177], v[142:143], 2, s[8:9]
	global_load_dwordx4 v[116:119], v[176:177], off
	v_lshl_add_u64 v[182:183], v[178:179], 0, v[154:155]
	v_lshl_add_u64 v[184:185], v[178:179], 0, v[144:145]
	v_lshl_add_u64 v[178:179], v[178:179], 0, v[130:131]
	s_waitcnt vmcnt(5)
	v_mov_b32_e32 v162, v112
	v_mov_b32_e32 v163, v113
	v_mov_b32_e32 v164, v114
	v_mov_b32_e32 v165, v115
	v_mul_f32_e32 v133, v100, v162
	v_mul_f32_e32 v152, v101, v163
	v_mul_f32_e32 v161, v102, v164
	v_mul_f32_e32 v175, v103, v165
	v_mul_f32_e32 v186, v96, v162
	v_mul_f32_e32 v187, v97, v163
	v_mul_f32_e32 v188, v98, v164
	v_mul_f32_e32 v189, v99, v165
	v_mul_f32_e32 v190, v36, v162
	v_mul_f32_e32 v191, v37, v163
	v_mul_f32_e32 v194, v32, v162
	v_mul_f32_e32 v195, v33, v163
	v_cvt_pk_bf16_f32 v162, v133, v152
	v_cvt_pk_bf16_f32 v163, v161, v175
	v_mul_f32_e32 v192, v38, v164
	v_mul_f32_e32 v193, v39, v165
	v_mul_f32_e32 v196, v34, v164
	v_mul_f32_e32 v197, v35, v165
	v_cvt_pk_bf16_f32 v164, v186, v187
	v_cvt_pk_bf16_f32 v165, v188, v189
	v_cvt_pk_bf16_f32 v186, v190, v191
	v_cvt_pk_bf16_f32 v187, v192, v193
	v_cvt_pk_bf16_f32 v188, v194, v195
	v_cvt_pk_bf16_f32 v189, v196, v197
	global_store_dwordx2 v[180:181], v[162:163], off offset:1536
	global_store_dwordx2 v[182:183], v[164:165], off offset:1536
	global_store_dwordx2 v[184:185], v[186:187], off offset:1536
	global_store_dwordx2 v[178:179], v[188:189], off offset:1536
	v_bitop3_b32 v133, v136, s39, 64 bitop3:0xc8
	v_lshlrev_b32_e32 v152, 1, v133
	v_lshl_add_u64 v[178:179], s[12:13], 0, v[252:253]
	v_lshl_add_u64 v[180:181], v[178:179], 0, v[156:157]
	v_lshl_add_u64 v[176:177], v[140:141], 2, s[8:9]
	global_load_dwordx4 v[112:115], v[176:177], off
	v_lshl_add_u64 v[182:183], v[178:179], 0, v[154:155]
	v_lshl_add_u64 v[184:185], v[178:179], 0, v[144:145]
	v_lshl_add_u64 v[178:179], v[178:179], 0, v[130:131]
	s_waitcnt vmcnt(5)
	v_mov_b32_e32 v162, v116
	v_mov_b32_e32 v163, v117
	v_mov_b32_e32 v164, v118
	v_mov_b32_e32 v165, v119
	v_mul_f32_e32 v133, v92, v162
	v_mul_f32_e32 v152, v93, v163
	v_mul_f32_e32 v161, v94, v164
	v_mul_f32_e32 v175, v95, v165
	v_mul_f32_e32 v186, v88, v162
	v_mul_f32_e32 v187, v89, v163
	v_mul_f32_e32 v188, v90, v164
	v_mul_f32_e32 v189, v91, v165
	v_mul_f32_e32 v190, v28, v162
	v_mul_f32_e32 v191, v29, v163
	v_mul_f32_e32 v194, v24, v162
	v_mul_f32_e32 v195, v25, v163
	v_cvt_pk_bf16_f32 v162, v133, v152
	v_cvt_pk_bf16_f32 v163, v161, v175
	v_mul_f32_e32 v192, v30, v164
	v_mul_f32_e32 v193, v31, v165
	v_mul_f32_e32 v196, v26, v164
	v_mul_f32_e32 v197, v27, v165
	v_cvt_pk_bf16_f32 v164, v186, v187
	v_cvt_pk_bf16_f32 v165, v188, v189
	v_cvt_pk_bf16_f32 v186, v190, v191
	v_cvt_pk_bf16_f32 v187, v192, v193
	v_cvt_pk_bf16_f32 v188, v194, v195
	v_cvt_pk_bf16_f32 v189, v196, v197
	global_store_dwordx2 v[180:181], v[162:163], off offset:2048
	global_store_dwordx2 v[182:183], v[164:165], off offset:2048
	global_store_dwordx2 v[184:185], v[186:187], off offset:2048
	global_store_dwordx2 v[178:179], v[188:189], off offset:2048
	v_bitop3_b32 v133, v136, s40, v166 bitop3:0xc8
	v_lshlrev_b32_e32 v152, 1, v133
	v_lshl_add_u64 v[178:179], s[12:13], 0, v[252:253]
	v_lshl_add_u64 v[180:181], v[178:179], 0, v[156:157]
	v_lshl_add_u64 v[176:177], v[138:139], 2, s[8:9]
	global_load_dwordx4 v[116:119], v[176:177], off
	v_lshl_add_u64 v[182:183], v[178:179], 0, v[154:155]
	v_lshl_add_u64 v[184:185], v[178:179], 0, v[144:145]
	v_lshl_add_u64 v[178:179], v[178:179], 0, v[130:131]
	s_waitcnt vmcnt(5)
	v_mov_b32_e32 v162, v112
	v_mov_b32_e32 v163, v113
	v_mov_b32_e32 v164, v114
	v_mov_b32_e32 v165, v115
	v_mul_f32_e32 v133, v84, v162
	v_mul_f32_e32 v152, v85, v163
	v_mul_f32_e32 v161, v86, v164
	v_mul_f32_e32 v175, v87, v165
	v_mul_f32_e32 v186, v80, v162
	v_mul_f32_e32 v187, v81, v163
	v_mul_f32_e32 v188, v82, v164
	v_mul_f32_e32 v189, v83, v165
	v_mul_f32_e32 v190, v20, v162
	v_mul_f32_e32 v191, v21, v163
	v_mul_f32_e32 v194, v16, v162
	v_mul_f32_e32 v195, v17, v163
	v_cvt_pk_bf16_f32 v162, v133, v152
	v_cvt_pk_bf16_f32 v163, v161, v175
	v_mul_f32_e32 v192, v22, v164
	v_mul_f32_e32 v193, v23, v165
	v_mul_f32_e32 v196, v18, v164
	v_mul_f32_e32 v197, v19, v165
	v_cvt_pk_bf16_f32 v164, v186, v187
	v_cvt_pk_bf16_f32 v165, v188, v189
	v_cvt_pk_bf16_f32 v186, v190, v191
	v_cvt_pk_bf16_f32 v187, v192, v193
	v_cvt_pk_bf16_f32 v188, v194, v195
	v_cvt_pk_bf16_f32 v189, v196, v197
	global_store_dwordx2 v[180:181], v[162:163], off offset:2560
	global_store_dwordx2 v[182:183], v[164:165], off offset:2560
	global_store_dwordx2 v[184:185], v[186:187], off offset:2560
	global_store_dwordx2 v[178:179], v[188:189], off offset:2560
	v_bitop3_b32 v133, v136, s41, v167 bitop3:0xc8
	v_lshlrev_b32_e32 v152, 1, v133
	v_lshl_add_u64 v[178:179], s[12:13], 0, v[252:253]
	v_lshl_add_u64 v[180:181], v[178:179], 0, v[156:157]
	v_lshl_add_u64 v[176:177], v[134:135], 2, s[8:9]
	global_load_dwordx4 v[112:115], v[176:177], off
	v_lshl_add_u64 v[182:183], v[178:179], 0, v[154:155]
	v_lshl_add_u64 v[184:185], v[178:179], 0, v[144:145]
	v_lshl_add_u64 v[178:179], v[178:179], 0, v[130:131]
	s_waitcnt vmcnt(5)
	v_mov_b32_e32 v162, v116
	v_mov_b32_e32 v163, v117
	v_mov_b32_e32 v164, v118
	v_mov_b32_e32 v165, v119
	v_mul_f32_e32 v133, v76, v162
	v_mul_f32_e32 v152, v77, v163
	v_mul_f32_e32 v161, v78, v164
	v_mul_f32_e32 v175, v79, v165
	v_mul_f32_e32 v186, v72, v162
	v_mul_f32_e32 v187, v73, v163
	v_mul_f32_e32 v188, v74, v164
	v_mul_f32_e32 v189, v75, v165
	v_mul_f32_e32 v190, v12, v162
	v_mul_f32_e32 v191, v13, v163
	v_mul_f32_e32 v194, v8, v162
	v_mul_f32_e32 v195, v9, v163
	v_cvt_pk_bf16_f32 v162, v133, v152
	v_cvt_pk_bf16_f32 v163, v161, v175
	v_mul_f32_e32 v192, v14, v164
	v_mul_f32_e32 v193, v15, v165
	v_mul_f32_e32 v196, v10, v164
	v_mul_f32_e32 v197, v11, v165
	v_cvt_pk_bf16_f32 v164, v186, v187
	v_cvt_pk_bf16_f32 v165, v188, v189
	v_cvt_pk_bf16_f32 v186, v190, v191
	v_cvt_pk_bf16_f32 v187, v192, v193
	v_cvt_pk_bf16_f32 v188, v194, v195
	v_cvt_pk_bf16_f32 v189, v196, v197
	global_store_dwordx2 v[180:181], v[162:163], off offset:3072
	global_store_dwordx2 v[182:183], v[164:165], off offset:3072
	global_store_dwordx2 v[184:185], v[186:187], off offset:3072
	global_store_dwordx2 v[178:179], v[188:189], off offset:3072
	v_bitop3_b32 v133, v136, s42, v168 bitop3:0xc8
	v_lshlrev_b32_e32 v152, 1, v133
	v_lshl_add_u64 v[176:177], s[12:13], 0, v[252:253]
	v_lshl_add_u64 v[156:157], v[176:177], 0, v[156:157]
	v_lshl_add_u64 v[154:155], v[176:177], 0, v[154:155]
	v_lshl_add_u64 v[144:145], v[176:177], 0, v[144:145]
	v_lshl_add_u64 v[130:131], v[176:177], 0, v[130:131]
	s_waitcnt vmcnt(4)
	v_mov_b32_e32 v162, v112
	v_mov_b32_e32 v163, v113
	v_mov_b32_e32 v164, v114
	v_mov_b32_e32 v165, v115
	v_mul_f32_e32 v133, v68, v162
	v_mul_f32_e32 v152, v69, v163
	v_mul_f32_e32 v161, v70, v164
	v_mul_f32_e32 v175, v71, v165
	v_mul_f32_e32 v176, v64, v162
	v_mul_f32_e32 v177, v65, v163
	v_mul_f32_e32 v178, v66, v164
	v_mul_f32_e32 v179, v67, v165
	v_mul_f32_e32 v180, v4, v162
	v_mul_f32_e32 v181, v5, v163
	v_mul_f32_e32 v184, v0, v162
	v_mul_f32_e32 v185, v1, v163
	v_cvt_pk_bf16_f32 v162, v133, v152
	v_cvt_pk_bf16_f32 v163, v161, v175
	v_mul_f32_e32 v182, v6, v164
	v_mul_f32_e32 v183, v7, v165
	v_mul_f32_e32 v186, v2, v164
	v_mul_f32_e32 v187, v3, v165
	v_cvt_pk_bf16_f32 v164, v176, v177
	v_cvt_pk_bf16_f32 v165, v178, v179
	v_cvt_pk_bf16_f32 v176, v180, v181
	v_cvt_pk_bf16_f32 v177, v182, v183
	v_cvt_pk_bf16_f32 v178, v184, v185
	v_cvt_pk_bf16_f32 v179, v186, v187
	global_store_dwordx2 v[156:157], v[162:163], off offset:3584
	global_store_dwordx2 v[154:155], v[164:165], off offset:3584
	global_store_dwordx2 v[144:145], v[176:177], off offset:3584
	global_store_dwordx2 v[130:131], v[178:179], off offset:3584
	s_cbranch_execnz .LBB0_206
	s_branch .LBB0_212

.LBB0_502:
	s_ashr_i32 s14, s34, 3
	s_lshr_b32 s28, s14, 28
	s_add_i32 s28, s14, s28
	s_and_b32 s29, s28, -16
	s_sub_i32 s33, s14, s29
	s_lshl_b32 s14, s28, 7
	s_lshl_b32 s28, s34, 8
	s_and_b32 s14, s14, 0xfffff800
	s_and_b32 s28, s28, 0x700
	s_or_b32 s28, s14, s28
	s_ashr_i32 s29, s28, 31
	s_lshl_b32 s35, s33, 7
	s_lshl_b64 s[36:37], s[28:29], 11
	s_add_u32 s36, s3, s36
	s_addc_u32 s37, s4, s37
	s_add_i32 s14, s35, 0x1000
	v_mov_b32_e32 v36, v220
	s_lshl_b64 s[38:39], s[14:15], 11
	s_add_u32 s38, s72, s38
	v_ashrrev_i32_e32 v26, 2, v36
	v_ashrrev_i32_e32 v27, 31, v26
	s_addc_u32 s39, s73, s39
	v_lshlrev_b64 v[0:1], 11, v[26:27]
	v_lshlrev_b32_e32 v4, 4, v36
	v_lshl_add_u64 v[2:3], s[38:39], 0, v[0:1]
	v_lshl_add_u64 v[0:1], s[36:37], 0, v[0:1]
	v_and_b32_e32 v152, 48, v4
	v_lshl_add_u64 v[154:155], v[0:1], 0, v[152:153]
	v_add_co_u32_e32 v28, vcc, s27, v154
	v_lshl_add_u64 v[156:157], v[2:3], 0, v[152:153]
	s_nop 0
	v_addc_co_u32_e32 v29, vcc, 0, v155, vcc
	v_add_co_u32_e32 v30, vcc, s30, v154
	global_load_dwordx4 v[2:5], v[154:155], off
	s_nop 0
	v_addc_co_u32_e32 v31, vcc, 0, v155, vcc
	v_add_co_u32_e32 v32, vcc, s31, v154
	global_load_dwordx4 v[6:9], v[28:29], off
	s_nop 0
	v_addc_co_u32_e32 v33, vcc, 0, v155, vcc
	v_add_co_u32_e32 v34, vcc, s27, v156
	global_load_dwordx4 v[10:13], v[30:31], off
	s_nop 0
	v_addc_co_u32_e32 v35, vcc, 0, v157, vcc
	global_load_dwordx4 v[14:17], v[32:33], off
	global_load_dwordx4 v[18:21], v[156:157], off
	global_load_dwordx4 v[22:25], v[34:35], off
	global_load_dwordx4 v[44:47], v[154:155], off offset:64
	global_load_dwordx4 v[60:63], v[28:29], off offset:64
	global_load_dwordx4 v[68:71], v[30:31], off offset:64
	global_load_dwordx4 v[140:143], v[32:33], off offset:64
	global_load_dwordx4 v[52:55], v[156:157], off offset:64
	global_load_dwordx4 v[144:147], v[34:35], off offset:64
	v_lshrrev_b32_e32 v27, 4, v36
	v_lshrrev_b32_e32 v37, 2, v36
	v_sub_u32_e32 v40, 0, v27
	v_sub_u32_e32 v37, 0, v37
	v_and_b32_e32 v38, 0x3ffff8f, v36
	v_lshlrev_b32_e32 v39, 6, v36
	v_xor_b32_e32 v36, v36, v40
	v_xor_b32_e32 v27, v27, v37
	v_lshlrev_b32_e32 v36, 4, v36
	v_lshlrev_b32_e32 v27, 4, v27
	v_and_b32_e32 v41, 0x1000, v39
	v_and_b32_e32 v36, 48, v36
	v_and_b32_e32 v27, 48, v27
	v_and_b32_e32 v42, 0x3c0, v39
	v_and_b32_e32 v39, 0xffffe3c0, v39
	v_lshl_add_u32 v38, v38, 6, v194
	v_lshl_or_b32 v152, v26, 6, v36
	v_or_b32_e32 v26, v27, v41
	s_mov_b32 s29, -2
	s_mov_b32 s36, s15
	v_mov_b32_e32 v0, 0
	v_mov_b32_e32 v1, v153
	v_or3_b32 v166, v41, v42, v27
	v_add_u32_e32 v167, v27, v39
	v_add_u32_e32 v168, v27, v38
	v_add_u32_e32 v169, v26, v42
	v_lshl_add_u64 v[158:159], v[154:155], 0, s[16:17]
	v_lshl_add_u64 v[160:161], v[154:155], 0, s[22:23]
	v_lshl_add_u64 v[162:163], v[154:155], 0, s[24:25]
	v_lshl_add_u64 v[164:165], v[156:157], 0, s[16:17]
	v_mov_b32_e32 v26, v153
	v_mov_b32_e32 v27, v153
	v_mov_b32_e32 v28, 0
	v_mov_b32_e32 v29, v153
	v_mov_b32_e32 v30, v153
	v_mov_b32_e32 v31, v153
	v_mov_b32_e32 v32, 0
	v_mov_b32_e32 v33, v153
	v_mov_b32_e32 v34, v153
	v_mov_b32_e32 v35, v153
	v_mov_b32_e32 v36, 0
	v_mov_b32_e32 v37, v153
	v_mov_b32_e32 v38, v153
	v_mov_b32_e32 v39, v153
	v_mov_b32_e32 v40, 0
	v_mov_b32_e32 v41, v153
	v_mov_b32_e32 v42, v153
	v_mov_b32_e32 v43, v153
	v_mov_b32_e32 v48, 0
	s_waitcnt vmcnt(11)
	ds_write_b128 v152, v[2:5]
	s_waitcnt vmcnt(10)
	ds_write_b128 v152, v[6:9] offset:4096
	s_waitcnt vmcnt(9)
	ds_write_b128 v152, v[10:13] offset:8192
	s_waitcnt vmcnt(8)
	ds_write_b128 v152, v[14:17] offset:12288
	s_waitcnt vmcnt(7)
	ds_write_b128 v152, v[18:21] offset:32768
	s_waitcnt vmcnt(6)
	ds_write_b128 v152, v[22:25] offset:36864
	v_mov_b32_e32 v2, v153
	v_mov_b32_e32 v3, v153
	v_mov_b32_e32 v4, 0
	v_mov_b32_e32 v5, v153
	v_mov_b32_e32 v6, v153
	v_mov_b32_e32 v7, v153
	v_mov_b32_e32 v8, 0
	v_mov_b32_e32 v9, v153
	v_mov_b32_e32 v10, v153
	v_mov_b32_e32 v11, v153
	v_mov_b32_e32 v12, 0
	v_mov_b32_e32 v13, v153
	v_mov_b32_e32 v14, v153
	v_mov_b32_e32 v15, v153
	v_mov_b32_e32 v16, 0
	v_mov_b32_e32 v17, v153
	v_mov_b32_e32 v18, v153
	v_mov_b32_e32 v19, v153
	v_mov_b32_e32 v20, 0
	v_mov_b32_e32 v21, v153
	v_mov_b32_e32 v22, v153
	v_mov_b32_e32 v23, v153
	v_mov_b32_e32 v24, 0
	v_mov_b32_e32 v25, v153
	v_mov_b32_e32 v49, v153
	v_mov_b32_e32 v50, v153
	v_mov_b32_e32 v51, v153
	v_mov_b32_e32 v56, 0
	v_mov_b32_e32 v57, v153
	v_mov_b32_e32 v58, v153
	v_mov_b32_e32 v59, v153
	v_mov_b32_e32 v64, 0
	v_mov_b32_e32 v65, v153
	v_mov_b32_e32 v66, v153
	v_mov_b32_e32 v67, v153
	v_mov_b32_e32 v72, 0
	v_mov_b32_e32 v73, v153
	v_mov_b32_e32 v74, v153
	v_mov_b32_e32 v75, v153
	v_mov_b32_e32 v76, 0
	v_mov_b32_e32 v77, v153
	v_mov_b32_e32 v78, v153
	v_mov_b32_e32 v79, v153
	v_mov_b32_e32 v80, 0
	v_mov_b32_e32 v81, v153
	v_mov_b32_e32 v82, v153
	v_mov_b32_e32 v83, v153
	v_mov_b32_e32 v84, 0
	v_mov_b32_e32 v85, v153
	v_mov_b32_e32 v86, v153
	v_mov_b32_e32 v87, v153
	v_mov_b32_e32 v88, 0
	v_mov_b32_e32 v89, v153
	v_mov_b32_e32 v90, v153
	v_mov_b32_e32 v91, v153
	v_mov_b32_e32 v92, 0
	v_mov_b32_e32 v93, v153
	v_mov_b32_e32 v94, v153
	v_mov_b32_e32 v95, v153
	v_mov_b32_e32 v96, 0
	v_mov_b32_e32 v97, v153
	v_mov_b32_e32 v98, v153
	v_mov_b32_e32 v99, v153
	v_mov_b32_e32 v100, 0
	v_mov_b32_e32 v101, v153
	v_mov_b32_e32 v102, v153
	v_mov_b32_e32 v103, v153
	v_mov_b32_e32 v104, 0
	v_mov_b32_e32 v105, v153
	v_mov_b32_e32 v106, v153
	v_mov_b32_e32 v107, v153
	v_mov_b32_e32 v108, 0
	v_mov_b32_e32 v109, v153
	v_mov_b32_e32 v110, v153
	v_mov_b32_e32 v111, v153
	v_mov_b32_e32 v112, 0
	v_mov_b32_e32 v113, v153
	v_mov_b32_e32 v114, v153
	v_mov_b32_e32 v115, v153
	v_mov_b32_e32 v116, 0
	v_mov_b32_e32 v117, v153
	v_mov_b32_e32 v118, v153
	v_mov_b32_e32 v119, v153
	v_mov_b32_e32 v120, 0
	v_mov_b32_e32 v121, v153
	v_mov_b32_e32 v122, v153
	v_mov_b32_e32 v123, v153
	v_mov_b32_e32 v124, 0
	v_mov_b32_e32 v125, v153
	v_mov_b32_e32 v126, v153
	v_mov_b32_e32 v127, v153
	v_mov_b32_e32 v128, 0
	v_mov_b32_e32 v129, v153
	v_mov_b32_e32 v130, v153
	v_mov_b32_e32 v131, v153
	v_mov_b32_e32 v132, 0
	v_mov_b32_e32 v133, v153
	v_mov_b32_e32 v134, v153
	v_mov_b32_e32 v135, v153
	v_mov_b32_e32 v136, 0
	v_mov_b32_e32 v137, v153
	v_mov_b32_e32 v138, v153
	v_mov_b32_e32 v139, v153
	v_mov_b32_e32 v148, 0
	v_mov_b32_e32 v149, v153
	v_mov_b32_e32 v150, v153
	v_mov_b32_e32 v151, v153
	s_waitcnt lgkmcnt(0)
	s_add_i32 s37, s36, 64
	s_min_u32 s14, s37, 0x3e0
	s_lshl_b32 s14, s14, 1
	v_lshl_add_u64 v[170:171], v[154:155], 0, s[14:15]
	v_lshl_add_u64 v[174:175], v[158:159], 0, s[14:15]
	v_lshl_add_u64 v[178:179], v[160:161], 0, s[14:15]
	v_lshl_add_u64 v[182:183], v[162:163], 0, s[14:15]
	v_lshl_add_u64 v[186:187], v[156:157], 0, s[14:15]
	v_lshl_add_u64 v[190:191], v[164:165], 0, s[14:15]

.LBB0_503:
	global_load_dwordx4 v[170:173], v[170:171], off
	ds_read_b128 v[196:199], v169 offset:32768
	global_load_dwordx4 v[174:177], v[174:175], off
	ds_read_b128 v[200:203], v169 offset:33792
	global_load_dwordx4 v[178:181], v[178:179], off
	ds_read_b128 v[204:207], v169 offset:34816
	global_load_dwordx4 v[182:185], v[182:183], off
	ds_read_b128 v[208:211], v169 offset:35840
	global_load_dwordx4 v[186:189], v[186:187], off
	ds_read_b128 v[212:215], v167
	global_load_dwordx4 v[190:193], v[190:191], off
	ds_read_b128 v[216:219], v167 offset:1024
	ds_read_b128 v[222:225], v167 offset:2048
	ds_read_b128 v[226:229], v167 offset:3072
	ds_read_b128 v[230:233], v167 offset:4096
	ds_read_b128 v[234:237], v167 offset:5120
	ds_read_b128 v[238:241], v167 offset:6144
	ds_read_b128 v[242:245], v167 offset:7168
	s_setprio 1
	s_waitcnt lgkmcnt(7)
	v_mfma_f32_16x16x32_bf16 v[148:151], v[196:199], v[212:215], v[148:151]
	v_mfma_f32_16x16x32_bf16 v[136:139], v[200:203], v[212:215], v[136:139]
	v_mfma_f32_16x16x32_bf16 v[132:135], v[204:207], v[212:215], v[132:135]
	v_mfma_f32_16x16x32_bf16 v[128:131], v[208:211], v[212:215], v[128:131]
	s_waitcnt vmcnt(11)
	ds_write_b128 v152, v[44:47] offset:16384
	s_waitcnt lgkmcnt(7)
	v_mfma_f32_16x16x32_bf16 v[124:127], v[196:199], v[216:219], v[124:127]
	v_mfma_f32_16x16x32_bf16 v[120:123], v[200:203], v[216:219], v[120:123]
	v_mfma_f32_16x16x32_bf16 v[116:119], v[204:207], v[216:219], v[116:119]
	v_mfma_f32_16x16x32_bf16 v[112:115], v[208:211], v[216:219], v[112:115]
	s_waitcnt vmcnt(9)
	ds_write_b128 v152, v[60:63] offset:20480
	s_waitcnt lgkmcnt(7)
	v_mfma_f32_16x16x32_bf16 v[108:111], v[196:199], v[222:225], v[108:111]
	v_mfma_f32_16x16x32_bf16 v[104:107], v[200:203], v[222:225], v[104:107]
	v_mfma_f32_16x16x32_bf16 v[100:103], v[204:207], v[222:225], v[100:103]
	v_mfma_f32_16x16x32_bf16 v[96:99], v[208:211], v[222:225], v[96:99]
	s_waitcnt vmcnt(8)
	ds_write_b128 v152, v[68:71] offset:24576
	s_waitcnt lgkmcnt(7)
	v_mfma_f32_16x16x32_bf16 v[92:95], v[196:199], v[226:229], v[92:95]
	v_mfma_f32_16x16x32_bf16 v[88:91], v[200:203], v[226:229], v[88:91]
	v_mfma_f32_16x16x32_bf16 v[84:87], v[204:207], v[226:229], v[84:87]
	v_mfma_f32_16x16x32_bf16 v[80:83], v[208:211], v[226:229], v[80:83]
	s_waitcnt vmcnt(7)
	ds_write_b128 v152, v[140:143] offset:28672
	s_waitcnt lgkmcnt(7)
	v_mfma_f32_16x16x32_bf16 v[76:79], v[196:199], v[230:233], v[76:79]
	v_mfma_f32_16x16x32_bf16 v[72:75], v[200:203], v[230:233], v[72:75]
	v_mfma_f32_16x16x32_bf16 v[64:67], v[204:207], v[230:233], v[64:67]
	v_mfma_f32_16x16x32_bf16 v[56:59], v[208:211], v[230:233], v[56:59]
	s_waitcnt vmcnt(7)
	ds_write_b128 v152, v[52:55] offset:40960
	s_waitcnt lgkmcnt(7)
	v_mfma_f32_16x16x32_bf16 v[48:51], v[196:199], v[234:237], v[48:51]
	v_mfma_f32_16x16x32_bf16 v[40:43], v[200:203], v[234:237], v[40:43]
	v_mfma_f32_16x16x32_bf16 v[36:39], v[204:207], v[234:237], v[36:39]
	v_mfma_f32_16x16x32_bf16 v[32:35], v[208:211], v[234:237], v[32:35]
	s_waitcnt vmcnt(6)
	ds_write_b128 v152, v[144:147] offset:45056
	s_waitcnt lgkmcnt(7)
	v_mfma_f32_16x16x32_bf16 v[28:31], v[196:199], v[238:241], v[28:31]
	v_mfma_f32_16x16x32_bf16 v[24:27], v[200:203], v[238:241], v[24:27]
	v_mfma_f32_16x16x32_bf16 v[20:23], v[204:207], v[238:241], v[20:23]
	v_mfma_f32_16x16x32_bf16 v[16:19], v[208:211], v[238:241], v[16:19]
	s_waitcnt lgkmcnt(6)
	v_mfma_f32_16x16x32_bf16 v[12:15], v[196:199], v[242:245], v[12:15]
	v_mfma_f32_16x16x32_bf16 v[8:11], v[200:203], v[242:245], v[8:11]
	v_mfma_f32_16x16x32_bf16 v[4:7], v[204:207], v[242:245], v[4:7]
	v_mfma_f32_16x16x32_bf16 v[0:3], v[208:211], v[242:245], v[0:3]
	s_setprio 0
	s_min_u32 s14, s36, 0x380
	s_lshl_b32 s14, s14, 1
	s_mov_b32 s39, s15
	s_add_i32 s38, s14, 0xc0
	v_lshl_add_u64 v[44:45], v[154:155], 0, s[14:15]
	v_lshl_add_u64 v[52:53], v[156:157], 0, s[14:15]
	v_lshl_add_u64 v[60:61], v[158:159], 0, s[38:39]
	v_lshl_add_u64 v[68:69], v[160:161], 0, s[38:39]
	v_lshl_add_u64 v[140:141], v[162:163], 0, s[38:39]
	v_lshl_add_u64 v[144:145], v[164:165], 0, s[38:39]
	s_waitcnt lgkmcnt(0)
	s_barrier
	global_load_dwordx4 v[44:47], v[44:45], off offset:192
	ds_read_b128 v[196:199], v166 offset:40960
	global_load_dwordx4 v[52:55], v[52:53], off offset:192
	ds_read_b128 v[200:203], v166 offset:41984
	global_load_dwordx4 v[60:63], v[60:61], off
	ds_read_b128 v[204:207], v166 offset:43008
	global_load_dwordx4 v[68:71], v[68:69], off
	ds_read_b128 v[208:211], v166 offset:44032
	global_load_dwordx4 v[140:143], v[140:141], off
	ds_read_b128 v[212:215], v168
	global_load_dwordx4 v[144:147], v[144:145], off
	ds_read_b128 v[216:219], v168 offset:1024
	ds_read_b128 v[222:225], v168 offset:2048
	ds_read_b128 v[226:229], v168 offset:3072
	ds_read_b128 v[230:233], v168 offset:4096
	ds_read_b128 v[234:237], v168 offset:5120
	ds_read_b128 v[238:241], v168 offset:6144
	ds_read_b128 v[242:245], v168 offset:7168
	s_setprio 1
	s_waitcnt lgkmcnt(7)
	v_mfma_f32_16x16x32_bf16 v[148:151], v[196:199], v[212:215], v[148:151]
	v_mfma_f32_16x16x32_bf16 v[136:139], v[200:203], v[212:215], v[136:139]
	v_mfma_f32_16x16x32_bf16 v[132:135], v[204:207], v[212:215], v[132:135]
	v_mfma_f32_16x16x32_bf16 v[128:131], v[208:211], v[212:215], v[128:131]
	s_waitcnt vmcnt(11)
	ds_write_b128 v152, v[170:173]
	s_waitcnt lgkmcnt(7)
	v_mfma_f32_16x16x32_bf16 v[124:127], v[196:199], v[216:219], v[124:127]
	v_mfma_f32_16x16x32_bf16 v[120:123], v[200:203], v[216:219], v[120:123]
	v_mfma_f32_16x16x32_bf16 v[116:119], v[204:207], v[216:219], v[116:119]
	v_mfma_f32_16x16x32_bf16 v[112:115], v[208:211], v[216:219], v[112:115]
	s_waitcnt vmcnt(10)
	ds_write_b128 v152, v[174:177] offset:4096
	s_waitcnt lgkmcnt(7)
	v_mfma_f32_16x16x32_bf16 v[108:111], v[196:199], v[222:225], v[108:111]
	v_mfma_f32_16x16x32_bf16 v[104:107], v[200:203], v[222:225], v[104:107]
	v_mfma_f32_16x16x32_bf16 v[100:103], v[204:207], v[222:225], v[100:103]
	v_mfma_f32_16x16x32_bf16 v[96:99], v[208:211], v[222:225], v[96:99]
	s_waitcnt vmcnt(9)
	ds_write_b128 v152, v[178:181] offset:8192
	s_waitcnt lgkmcnt(7)
	v_mfma_f32_16x16x32_bf16 v[92:95], v[196:199], v[226:229], v[92:95]
	v_mfma_f32_16x16x32_bf16 v[88:91], v[200:203], v[226:229], v[88:91]
	v_mfma_f32_16x16x32_bf16 v[84:87], v[204:207], v[226:229], v[84:87]
	v_mfma_f32_16x16x32_bf16 v[80:83], v[208:211], v[226:229], v[80:83]
	s_waitcnt vmcnt(8)
	ds_write_b128 v152, v[182:185] offset:12288
	s_waitcnt lgkmcnt(7)
	v_mfma_f32_16x16x32_bf16 v[76:79], v[196:199], v[230:233], v[76:79]
	v_mfma_f32_16x16x32_bf16 v[72:75], v[200:203], v[230:233], v[72:75]
	v_mfma_f32_16x16x32_bf16 v[64:67], v[204:207], v[230:233], v[64:67]
	v_mfma_f32_16x16x32_bf16 v[56:59], v[208:211], v[230:233], v[56:59]
	s_waitcnt vmcnt(7)
	ds_write_b128 v152, v[186:189] offset:32768
	s_waitcnt lgkmcnt(7)
	v_mfma_f32_16x16x32_bf16 v[48:51], v[196:199], v[234:237], v[48:51]
	v_mfma_f32_16x16x32_bf16 v[40:43], v[200:203], v[234:237], v[40:43]
	v_mfma_f32_16x16x32_bf16 v[36:39], v[204:207], v[234:237], v[36:39]
	v_mfma_f32_16x16x32_bf16 v[32:35], v[208:211], v[234:237], v[32:35]
	s_waitcnt vmcnt(6)
	ds_write_b128 v152, v[190:193] offset:36864
	s_waitcnt lgkmcnt(7)
	v_mfma_f32_16x16x32_bf16 v[28:31], v[196:199], v[238:241], v[28:31]
	v_mfma_f32_16x16x32_bf16 v[24:27], v[200:203], v[238:241], v[24:27]
	v_mfma_f32_16x16x32_bf16 v[20:23], v[204:207], v[238:241], v[20:23]
	v_mfma_f32_16x16x32_bf16 v[16:19], v[208:211], v[238:241], v[16:19]
	s_waitcnt lgkmcnt(6)
	v_mfma_f32_16x16x32_bf16 v[12:15], v[196:199], v[242:245], v[12:15]
	v_mfma_f32_16x16x32_bf16 v[8:11], v[200:203], v[242:245], v[8:11]
	v_mfma_f32_16x16x32_bf16 v[4:7], v[204:207], v[242:245], v[4:7]
	v_mfma_f32_16x16x32_bf16 v[0:3], v[208:211], v[242:245], v[0:3]
	s_setprio 0
	s_add_i32 s29, s29, 2
	s_mov_b32 s36, s37
	s_add_i32 s37, s36, 64
	s_min_u32 s14, s37, 0x3e0
	s_lshl_b32 s14, s14, 1
	v_lshl_add_u64 v[170:171], v[154:155], 0, s[14:15]
	v_lshl_add_u64 v[174:175], v[158:159], 0, s[14:15]
	v_lshl_add_u64 v[178:179], v[160:161], 0, s[14:15]
	v_lshl_add_u64 v[182:183], v[162:163], 0, s[14:15]
	v_lshl_add_u64 v[186:187], v[156:157], 0, s[14:15]
	v_lshl_add_u64 v[190:191], v[164:165], 0, s[14:15]
	s_cmp_lt_u32 s29, 30
	s_waitcnt lgkmcnt(0)
	s_cbranch_scc1 .Lrot_4
	s_barrier
	s_waitcnt vmcnt(1)
	v_mov_b32_e32 v142, v220
	v_readlane_b32 s36, v254, 6
	v_and_b32_e32 v45, 0xffffff80, v142
	v_add_u32_e32 v143, s28, v45
	v_lshrrev_b32_e32 v45, 2, v142
	v_and_b32_e32 v44, 64, v142
	v_and_b32_e32 v45, 12, v45
	s_ashr_i32 s28, s33, 2
	v_or3_b32 v140, v44, v45, s35
	s_ashr_i32 s29, s28, 31
	v_ashrrev_i32_e32 v141, 31, v140
	v_readlane_b32 s44, v254, 14
	v_readlane_b32 s45, v254, 15
	s_waitcnt vmcnt(0)
	v_and_or_b32 v144, v142, 15, v143
	s_lshl_b64 s[28:29], s[28:29], 3
	v_lshl_add_u64 v[44:45], v[140:141], 2, s[44:45]
	s_add_u32 s28, s5, s28
	v_lshlrev_b64 v[140:141], 1, v[140:141]
	v_ashrrev_i32_e32 v145, 31, v144
	s_addc_u32 s29, s26, s29
	v_lshl_add_u64 v[142:143], s[70:71], 0, v[140:141]
	v_lshl_add_u64 v[146:147], v[144:145], 2, s[6:7]
	v_lshlrev_b64 v[154:155], 5, v[144:145]
	v_lshlrev_b64 v[190:191], 12, v[144:145]
	global_load_dwordx4 v[68:71], v[44:45], off
	global_load_dwordx4 v[60:63], v[44:45], off offset:64
	global_load_dwordx4 v[52:55], v[44:45], off offset:128
	s_nop 0
	global_load_dwordx4 v[44:47], v[44:45], off offset:192
	v_lshl_add_u64 v[154:155], s[28:29], 0, v[154:155]
	global_load_dword v202, v[146:147], off
	global_load_dwordx2 v[184:185], v[154:155], off
	v_lshl_add_u64 v[146:147], v[142:143], 0, v[190:191]
	global_load_dwordx2 v[196:197], v[146:147], off
	global_load_dwordx2 v[198:199], v[146:147], off offset:32
	global_load_dwordx2 v[200:201], v[146:147], off offset:64
	global_load_dwordx2 v[192:193], v[146:147], off offset:96
	v_or_b32_e32 v146, 16, v144
	v_ashrrev_i32_e32 v147, 31, v146
	v_lshlrev_b64 v[188:189], 12, v[146:147]
	v_lshl_add_u64 v[154:155], v[146:147], 2, s[6:7]
	v_lshlrev_b64 v[156:157], 5, v[146:147]
	v_lshl_add_u64 v[146:147], v[142:143], 0, v[188:189]
	v_lshl_add_u64 v[156:157], s[28:29], 0, v[156:157]
	global_load_dword v195, v[154:155], off
	global_load_dwordx2 v[172:173], v[156:157], off
	global_load_dwordx2 v[186:187], v[146:147], off
	global_load_dwordx2 v[182:183], v[146:147], off offset:32
	global_load_dwordx2 v[180:181], v[146:147], off offset:64
	global_load_dwordx2 v[178:179], v[146:147], off offset:96
	v_or_b32_e32 v146, 32, v144
	v_ashrrev_i32_e32 v147, 31, v146
	v_lshl_add_u64 v[154:155], v[146:147], 2, s[6:7]
	v_lshlrev_b64 v[156:157], 5, v[146:147]
	v_lshl_add_u64 v[156:157], s[28:29], 0, v[156:157]
	global_load_dword v152, v[154:155], off
	global_load_dwordx2 v[160:161], v[156:157], off
	v_or_b32_e32 v154, 48, v144
	v_lshlrev_b64 v[176:177], 12, v[146:147]
	v_ashrrev_i32_e32 v155, 31, v154
	v_lshl_add_u64 v[146:147], v[142:143], 0, v[176:177]
	v_lshlrev_b64 v[156:157], 5, v[154:155]
	v_lshlrev_b64 v[164:165], 12, v[154:155]
	global_load_dwordx2 v[174:175], v[146:147], off
	global_load_dwordx2 v[170:171], v[146:147], off offset:32
	global_load_dwordx2 v[168:169], v[146:147], off offset:64
	global_load_dwordx2 v[166:167], v[146:147], off offset:96
	v_lshl_add_u64 v[146:147], v[154:155], 2, s[6:7]
	v_lshl_add_u64 v[156:157], s[28:29], 0, v[156:157]
	v_lshl_add_u64 v[154:155], v[142:143], 0, v[164:165]
	global_load_dword v145, v[146:147], off
	s_nop 0
	global_load_dwordx2 v[146:147], v[156:157], off
	global_load_dwordx2 v[162:163], v[154:155], off
	global_load_dwordx2 v[158:159], v[154:155], off offset:32
	s_nop 0
	global_load_dwordx2 v[156:157], v[154:155], off offset:64
	s_nop 0
	global_load_dwordx2 v[154:155], v[154:155], off offset:96
	v_readlane_b32 s37, v254, 7
	v_readlane_b32 s38, v254, 8
	v_readlane_b32 s39, v254, 9
	v_readlane_b32 s40, v254, 10
	v_readlane_b32 s41, v254, 11
	v_readlane_b32 s42, v254, 12
	v_readlane_b32 s43, v254, 13
	v_readlane_b32 s46, v254, 16
	v_readlane_b32 s47, v254, 17
	v_readlane_b32 s48, v254, 18
	v_readlane_b32 s49, v254, 19
	v_readlane_b32 s50, v254, 20
	v_readlane_b32 s51, v254, 21
	v_lshl_add_u64 v[140:141], s[8:9], 0, v[140:141]
	s_waitcnt vmcnt(23)
	v_mul_f32_e32 v148, v148, v202
	v_mul_f32_e32 v205, 0xbfb8aa3b, v148
	v_exp_f32_e32 v205, v205
	v_mul_f32_e32 v149, v149, v202
	v_mul_f32_e32 v206, 0xbfb8aa3b, v149
	v_exp_f32_e32 v206, v206
	v_add_f32_e32 v205, 1.0, v205
	v_rcp_f32_e32 v205, v205
	s_waitcnt vmcnt(21)
	v_lshlrev_b32_e32 v203, 16, v196
	v_mul_f32_e32 v150, v150, v202
	v_sub_f32_e32 v203, v203, v184
	v_mul_f32_e32 v148, v148, v205
	v_add_f32_e32 v205, 1.0, v206
	v_rcp_f32_e32 v205, v205
	v_mul_f32_e32 v148, v148, v203
	v_mul_f32_e32 v203, 0xbfb8aa3b, v150
	v_exp_f32_e32 v203, v203
	v_and_b32_e32 v196, 0xffff0000, v196
	v_mul_f32_e32 v151, v151, v202
	v_mul_f32_e32 v149, v149, v205
	v_sub_f32_e32 v196, v196, v184
	v_mul_f32_e32 v149, v149, v196
	v_add_f32_e32 v196, 1.0, v203
	v_mul_f32_e32 v203, 0xbfb8aa3b, v151
	v_exp_f32_e32 v203, v203
	v_rcp_f32_e32 v196, v196
	v_lshlrev_b32_e32 v204, 16, v197
	v_and_b32_e32 v197, 0xffff0000, v197
	v_add_f32_e32 v203, 1.0, v203
	v_rcp_f32_e32 v203, v203
	v_mul_f32_e32 v150, v150, v196
	v_sub_f32_e32 v196, v204, v184
	v_mul_f32_e32 v150, v150, v196
	v_mul_f32_e32 v151, v151, v203
	v_sub_f32_e32 v196, v197, v184
	v_mul_f32_e32 v151, v151, v196
	v_mul_f32_e32 v148, v185, v148
	v_mul_f32_e32 v149, v185, v149
	v_mul_f32_e32 v151, v185, v151
	v_mul_f32_e32 v148, v68, v148
	v_mul_f32_e32 v149, v69, v149
	v_mul_f32_e32 v150, v185, v150
	v_mul_f32_e32 v151, v71, v151
	v_mul_f32_e32 v136, v136, v202
	v_mul_f32_e32 v150, v70, v150
	v_cvt_pk_bf16_f32 v148, v148, v149
	v_cvt_pk_bf16_f32 v149, v150, v151
	v_mul_f32_e32 v151, 0xbfb8aa3b, v136
	v_exp_f32_e32 v151, v151
	v_mul_f32_e32 v137, v137, v202
	v_mul_f32_e32 v197, 0xbfb8aa3b, v137
	v_exp_f32_e32 v197, v197
	v_add_f32_e32 v151, 1.0, v151
	v_rcp_f32_e32 v151, v151
	v_lshl_add_u64 v[190:191], v[140:141], 0, v[190:191]
	global_store_dwordx2 v[190:191], v[148:149], off
	s_waitcnt vmcnt(21)
	v_lshlrev_b32_e32 v148, 16, v198
	v_mul_f32_e32 v136, v136, v151
	v_add_f32_e32 v151, 1.0, v197
	v_rcp_f32_e32 v151, v151
	v_and_b32_e32 v149, 0xffff0000, v198
	v_mul_f32_e32 v138, v138, v202
	v_sub_f32_e32 v148, v148, v184
	v_mul_f32_e32 v139, v139, v202
	v_mul_f32_e32 v136, v136, v148
	v_mul_f32_e32 v137, v137, v151
	v_mul_f32_e32 v148, 0xbfb8aa3b, v138
	v_sub_f32_e32 v149, v149, v184
	v_exp_f32_e32 v148, v148
	v_mul_f32_e32 v137, v137, v149
	v_mul_f32_e32 v149, 0xbfb8aa3b, v139
	v_exp_f32_e32 v149, v149
	v_add_f32_e32 v148, 1.0, v148
	v_rcp_f32_e32 v148, v148
	v_lshlrev_b32_e32 v150, 16, v199
	v_add_f32_e32 v149, 1.0, v149
	v_rcp_f32_e32 v149, v149
	v_and_b32_e32 v196, 0xffff0000, v199
	v_mul_f32_e32 v138, v138, v148
	v_sub_f32_e32 v148, v150, v184
	v_mul_f32_e32 v138, v138, v148
	v_mul_f32_e32 v139, v139, v149
	v_sub_f32_e32 v148, v196, v184
	v_mul_f32_e32 v139, v139, v148
	v_mul_f32_e32 v136, v185, v136
	v_mul_f32_e32 v137, v185, v137
	v_mul_f32_e32 v139, v185, v139
	v_mul_f32_e32 v136, v60, v136
	v_mul_f32_e32 v137, v61, v137
	v_mul_f32_e32 v138, v185, v138
	v_mul_f32_e32 v139, v63, v139
	v_mul_f32_e32 v132, v132, v202
	v_mul_f32_e32 v138, v62, v138
	v_cvt_pk_bf16_f32 v136, v136, v137
	v_cvt_pk_bf16_f32 v137, v138, v139
	v_mul_f32_e32 v139, 0xbfb8aa3b, v132
	v_exp_f32_e32 v139, v139
	v_mul_f32_e32 v133, v133, v202
	v_mul_f32_e32 v149, 0xbfb8aa3b, v133
	v_exp_f32_e32 v149, v149
	v_add_f32_e32 v139, 1.0, v139
	v_rcp_f32_e32 v139, v139
	global_store_dwordx2 v[190:191], v[136:137], off offset:32
	s_waitcnt vmcnt(21)
	v_lshlrev_b32_e32 v136, 16, v200
	v_and_b32_e32 v137, 0xffff0000, v200
	v_mul_f32_e32 v132, v132, v139
	v_add_f32_e32 v139, 1.0, v149
	v_rcp_f32_e32 v139, v139
	v_mul_f32_e32 v134, v134, v202
	v_sub_f32_e32 v136, v136, v184
	v_mul_f32_e32 v135, v135, v202
	v_mul_f32_e32 v132, v132, v136
	v_mul_f32_e32 v133, v133, v139
	v_mul_f32_e32 v136, 0xbfb8aa3b, v134
	v_sub_f32_e32 v137, v137, v184
	v_exp_f32_e32 v136, v136
	v_mul_f32_e32 v133, v133, v137
	v_mul_f32_e32 v137, 0xbfb8aa3b, v135
	v_exp_f32_e32 v137, v137
	v_add_f32_e32 v136, 1.0, v136
	v_rcp_f32_e32 v136, v136
	v_lshlrev_b32_e32 v138, 16, v201
	v_add_f32_e32 v137, 1.0, v137
	v_rcp_f32_e32 v137, v137
	v_and_b32_e32 v148, 0xffff0000, v201
	v_mul_f32_e32 v134, v134, v136
	v_sub_f32_e32 v136, v138, v184
	v_mul_f32_e32 v134, v134, v136
	v_mul_f32_e32 v135, v135, v137
	v_sub_f32_e32 v136, v148, v184
	v_mul_f32_e32 v135, v135, v136
	v_mul_f32_e32 v132, v185, v132
	v_mul_f32_e32 v133, v185, v133
	v_mul_f32_e32 v135, v185, v135
	v_mul_f32_e32 v132, v52, v132
	v_mul_f32_e32 v133, v53, v133
	v_mul_f32_e32 v134, v185, v134
	v_mul_f32_e32 v135, v55, v135
	v_mul_f32_e32 v128, v128, v202
	v_mul_f32_e32 v134, v54, v134
	v_cvt_pk_bf16_f32 v132, v132, v133
	v_cvt_pk_bf16_f32 v133, v134, v135
	v_mul_f32_e32 v135, 0xbfb8aa3b, v128
	v_exp_f32_e32 v135, v135
	v_mul_f32_e32 v129, v129, v202
	v_mul_f32_e32 v137, 0xbfb8aa3b, v129
	v_exp_f32_e32 v137, v137
	v_add_f32_e32 v135, 1.0, v135
	v_rcp_f32_e32 v135, v135
	global_store_dwordx2 v[190:191], v[132:133], off offset:64
	s_waitcnt vmcnt(21)
	v_and_b32_e32 v133, 0xffff0000, v192
	v_mul_f32_e32 v131, v131, v202
	v_mul_f32_e32 v128, v128, v135
	v_add_f32_e32 v135, 1.0, v137
	v_rcp_f32_e32 v135, v135
	v_sub_f32_e32 v133, v133, v184
	v_lshlrev_b32_e32 v132, 16, v192
	v_mul_f32_e32 v130, v130, v202
	v_mul_f32_e32 v129, v129, v135
	v_mul_f32_e32 v129, v129, v133
	v_mul_f32_e32 v133, 0xbfb8aa3b, v131
	v_exp_f32_e32 v133, v133
	v_sub_f32_e32 v132, v132, v184
	v_mul_f32_e32 v128, v128, v132
	v_mul_f32_e32 v132, 0xbfb8aa3b, v130
	v_add_f32_e32 v133, 1.0, v133
	v_rcp_f32_e32 v133, v133
	s_waitcnt vmcnt(20)
	v_mul_f32_e32 v124, v124, v195
	v_exp_f32_e32 v132, v132
	v_mul_f32_e32 v125, v125, v195
	v_mul_f32_e32 v131, v131, v133
	v_mul_f32_e32 v133, 0xbfb8aa3b, v124
	v_exp_f32_e32 v133, v133
	v_add_f32_e32 v132, 1.0, v132
	v_rcp_f32_e32 v132, v132
	v_mul_f32_e32 v135, 0xbfb8aa3b, v125
	v_add_f32_e32 v133, 1.0, v133
	v_rcp_f32_e32 v133, v133
	v_exp_f32_e32 v135, v135
	v_lshlrev_b32_e32 v134, 16, v193
	v_and_b32_e32 v136, 0xffff0000, v193
	v_mul_f32_e32 v130, v130, v132
	v_sub_f32_e32 v132, v134, v184
	v_mul_f32_e32 v130, v130, v132
	v_sub_f32_e32 v132, v136, v184
	v_mul_f32_e32 v124, v124, v133
	v_add_f32_e32 v133, 1.0, v135
	v_mul_f32_e32 v128, v185, v128
	v_mul_f32_e32 v129, v185, v129
	v_mul_f32_e32 v130, v185, v130
	v_mul_f32_e32 v131, v131, v132
	v_rcp_f32_e32 v133, v133
	v_mul_f32_e32 v128, v44, v128
	v_mul_f32_e32 v129, v45, v129
	v_mul_f32_e32 v130, v46, v130
	v_mul_f32_e32 v131, v185, v131
	v_mul_f32_e32 v131, v47, v131
	v_cvt_pk_bf16_f32 v128, v128, v129
	v_cvt_pk_bf16_f32 v129, v130, v131
	s_waitcnt vmcnt(18)
	v_lshlrev_b32_e32 v130, 16, v186
	v_and_b32_e32 v131, 0xffff0000, v186
	v_mul_f32_e32 v126, v126, v195
	v_sub_f32_e32 v130, v130, v172
	v_mul_f32_e32 v127, v127, v195
	v_mul_f32_e32 v124, v124, v130
	v_mul_f32_e32 v125, v125, v133
	v_mul_f32_e32 v130, 0xbfb8aa3b, v126
	v_sub_f32_e32 v131, v131, v172
	v_exp_f32_e32 v130, v130
	v_mul_f32_e32 v125, v125, v131
	v_mul_f32_e32 v131, 0xbfb8aa3b, v127
	v_exp_f32_e32 v131, v131
	v_add_f32_e32 v130, 1.0, v130
	v_rcp_f32_e32 v130, v130
	v_lshlrev_b32_e32 v132, 16, v187
	v_add_f32_e32 v131, 1.0, v131
	v_rcp_f32_e32 v131, v131
	v_and_b32_e32 v134, 0xffff0000, v187
	v_mul_f32_e32 v126, v126, v130
	v_sub_f32_e32 v130, v132, v172
	v_mul_f32_e32 v126, v126, v130
	v_mul_f32_e32 v127, v127, v131
	v_sub_f32_e32 v130, v134, v172
	v_mul_f32_e32 v127, v127, v130
	v_mul_f32_e32 v124, v173, v124
	v_mul_f32_e32 v125, v173, v125
	v_mul_f32_e32 v127, v173, v127
	v_mul_f32_e32 v124, v68, v124
	v_mul_f32_e32 v125, v69, v125
	v_mul_f32_e32 v126, v173, v126
	v_mul_f32_e32 v127, v71, v127
	v_mul_f32_e32 v120, v120, v195
	v_mul_f32_e32 v126, v70, v126
	v_cvt_pk_bf16_f32 v124, v124, v125
	v_cvt_pk_bf16_f32 v125, v126, v127
	v_mul_f32_e32 v127, 0xbfb8aa3b, v120
	v_exp_f32_e32 v127, v127
	v_mul_f32_e32 v121, v121, v195
	v_mul_f32_e32 v131, 0xbfb8aa3b, v121
	v_exp_f32_e32 v131, v131
	v_add_f32_e32 v127, 1.0, v127
	v_rcp_f32_e32 v127, v127
	global_store_dwordx2 v[190:191], v[128:129], off offset:96
	v_lshl_add_u64 v[128:129], v[140:141], 0, v[188:189]
	global_store_dwordx2 v[128:129], v[124:125], off
	v_mul_f32_e32 v120, v120, v127
	v_add_f32_e32 v127, 1.0, v131
	v_rcp_f32_e32 v127, v127
	s_waitcnt vmcnt(19)
	v_lshlrev_b32_e32 v124, 16, v182
	v_and_b32_e32 v125, 0xffff0000, v182
	v_mul_f32_e32 v122, v122, v195
	v_sub_f32_e32 v124, v124, v172
	v_mul_f32_e32 v123, v123, v195
	v_mul_f32_e32 v120, v120, v124
	v_mul_f32_e32 v121, v121, v127
	v_mul_f32_e32 v124, 0xbfb8aa3b, v122
	v_sub_f32_e32 v125, v125, v172
	v_exp_f32_e32 v124, v124
	v_mul_f32_e32 v121, v121, v125
	v_mul_f32_e32 v125, 0xbfb8aa3b, v123
	v_exp_f32_e32 v125, v125
	v_add_f32_e32 v124, 1.0, v124
	v_rcp_f32_e32 v124, v124
	v_lshlrev_b32_e32 v126, 16, v183
	v_add_f32_e32 v125, 1.0, v125
	v_rcp_f32_e32 v125, v125
	v_and_b32_e32 v130, 0xffff0000, v183
	v_mul_f32_e32 v122, v122, v124
	v_sub_f32_e32 v124, v126, v172
	v_mul_f32_e32 v122, v122, v124
	v_mul_f32_e32 v123, v123, v125
	v_sub_f32_e32 v124, v130, v172
	v_mul_f32_e32 v123, v123, v124
	v_mul_f32_e32 v120, v173, v120
	v_mul_f32_e32 v121, v173, v121
	v_mul_f32_e32 v123, v173, v123
	v_mul_f32_e32 v120, v60, v120
	v_mul_f32_e32 v121, v61, v121
	v_mul_f32_e32 v122, v173, v122
	v_mul_f32_e32 v123, v63, v123
	v_mul_f32_e32 v116, v116, v195
	v_mul_f32_e32 v122, v62, v122
	v_cvt_pk_bf16_f32 v120, v120, v121
	v_cvt_pk_bf16_f32 v121, v122, v123
	v_mul_f32_e32 v123, 0xbfb8aa3b, v116
	v_exp_f32_e32 v123, v123
	v_mul_f32_e32 v117, v117, v195
	v_mul_f32_e32 v125, 0xbfb8aa3b, v117
	v_exp_f32_e32 v125, v125
	v_add_f32_e32 v123, 1.0, v123
	v_rcp_f32_e32 v123, v123
	global_store_dwordx2 v[128:129], v[120:121], off offset:32
	s_waitcnt vmcnt(19)
	v_lshlrev_b32_e32 v120, 16, v180
	v_and_b32_e32 v121, 0xffff0000, v180
	v_mul_f32_e32 v116, v116, v123
	v_add_f32_e32 v123, 1.0, v125
	v_rcp_f32_e32 v123, v123
	v_mul_f32_e32 v118, v118, v195
	v_sub_f32_e32 v120, v120, v172
	v_mul_f32_e32 v119, v119, v195
	v_mul_f32_e32 v116, v116, v120
	v_mul_f32_e32 v117, v117, v123
	v_mul_f32_e32 v120, 0xbfb8aa3b, v118
	v_sub_f32_e32 v121, v121, v172
	v_exp_f32_e32 v120, v120
	v_mul_f32_e32 v117, v117, v121
	v_mul_f32_e32 v121, 0xbfb8aa3b, v119
	v_exp_f32_e32 v121, v121
	v_add_f32_e32 v120, 1.0, v120
	v_rcp_f32_e32 v120, v120
	v_lshlrev_b32_e32 v122, 16, v181
	v_add_f32_e32 v121, 1.0, v121
	v_rcp_f32_e32 v121, v121
	v_and_b32_e32 v124, 0xffff0000, v181
	v_mul_f32_e32 v118, v118, v120
	v_sub_f32_e32 v120, v122, v172
	v_mul_f32_e32 v118, v118, v120
	v_mul_f32_e32 v119, v119, v121
	v_sub_f32_e32 v120, v124, v172
	v_mul_f32_e32 v119, v119, v120
	v_mul_f32_e32 v116, v173, v116
	v_mul_f32_e32 v117, v173, v117
	v_mul_f32_e32 v119, v173, v119
	v_mul_f32_e32 v116, v52, v116
	v_mul_f32_e32 v117, v53, v117
	v_mul_f32_e32 v118, v173, v118
	v_mul_f32_e32 v119, v55, v119
	v_mul_f32_e32 v112, v112, v195
	v_mul_f32_e32 v118, v54, v118
	v_cvt_pk_bf16_f32 v116, v116, v117
	v_cvt_pk_bf16_f32 v117, v118, v119
	v_mul_f32_e32 v119, 0xbfb8aa3b, v112
	v_exp_f32_e32 v119, v119
	v_mul_f32_e32 v113, v113, v195
	v_mul_f32_e32 v121, 0xbfb8aa3b, v113
	v_exp_f32_e32 v121, v121
	v_add_f32_e32 v119, 1.0, v119
	v_rcp_f32_e32 v119, v119
	global_store_dwordx2 v[128:129], v[116:117], off offset:64
	s_waitcnt vmcnt(19)
	v_and_b32_e32 v117, 0xffff0000, v178
	v_mul_f32_e32 v115, v115, v195
	v_mul_f32_e32 v112, v112, v119
	v_add_f32_e32 v119, 1.0, v121
	v_rcp_f32_e32 v119, v119
	v_sub_f32_e32 v117, v117, v172
	v_lshlrev_b32_e32 v116, 16, v178
	v_mul_f32_e32 v114, v114, v195
	v_mul_f32_e32 v113, v113, v119
	v_mul_f32_e32 v113, v113, v117
	v_mul_f32_e32 v117, 0xbfb8aa3b, v115
	v_exp_f32_e32 v117, v117
	v_sub_f32_e32 v116, v116, v172
	v_mul_f32_e32 v112, v112, v116
	v_mul_f32_e32 v116, 0xbfb8aa3b, v114
	v_add_f32_e32 v117, 1.0, v117
	v_rcp_f32_e32 v117, v117
	s_waitcnt vmcnt(18)
	v_mul_f32_e32 v108, v108, v152
	v_exp_f32_e32 v116, v116
	v_mul_f32_e32 v109, v109, v152
	v_mul_f32_e32 v115, v115, v117
	v_mul_f32_e32 v117, 0xbfb8aa3b, v108
	v_exp_f32_e32 v117, v117
	v_add_f32_e32 v116, 1.0, v116
	v_rcp_f32_e32 v116, v116
	v_mul_f32_e32 v119, 0xbfb8aa3b, v109
	v_add_f32_e32 v117, 1.0, v117
	v_rcp_f32_e32 v117, v117
	v_exp_f32_e32 v119, v119
	v_lshlrev_b32_e32 v118, 16, v179
	v_and_b32_e32 v120, 0xffff0000, v179
	v_mul_f32_e32 v114, v114, v116
	v_sub_f32_e32 v116, v118, v172
	v_mul_f32_e32 v114, v114, v116
	v_sub_f32_e32 v116, v120, v172
	v_mul_f32_e32 v108, v108, v117
	v_add_f32_e32 v117, 1.0, v119
	v_mul_f32_e32 v112, v173, v112
	v_mul_f32_e32 v113, v173, v113
	v_mul_f32_e32 v114, v173, v114
	v_mul_f32_e32 v115, v115, v116
	v_rcp_f32_e32 v117, v117
	v_mul_f32_e32 v112, v44, v112
	v_mul_f32_e32 v113, v45, v113
	v_mul_f32_e32 v114, v46, v114
	v_mul_f32_e32 v115, v173, v115
	v_mul_f32_e32 v115, v47, v115
	v_cvt_pk_bf16_f32 v112, v112, v113
	v_cvt_pk_bf16_f32 v113, v114, v115
	s_waitcnt vmcnt(16)
	v_lshlrev_b32_e32 v114, 16, v174
	v_and_b32_e32 v115, 0xffff0000, v174
	v_mul_f32_e32 v110, v110, v152
	v_sub_f32_e32 v114, v114, v160
	v_mul_f32_e32 v111, v111, v152
	v_mul_f32_e32 v108, v108, v114
	v_mul_f32_e32 v109, v109, v117
	v_mul_f32_e32 v114, 0xbfb8aa3b, v110
	v_sub_f32_e32 v115, v115, v160
	v_exp_f32_e32 v114, v114
	v_mul_f32_e32 v109, v109, v115
	v_mul_f32_e32 v115, 0xbfb8aa3b, v111
	v_exp_f32_e32 v115, v115
	v_add_f32_e32 v114, 1.0, v114
	v_rcp_f32_e32 v114, v114
	v_lshlrev_b32_e32 v116, 16, v175
	v_add_f32_e32 v115, 1.0, v115
	v_rcp_f32_e32 v115, v115
	v_and_b32_e32 v118, 0xffff0000, v175
	v_mul_f32_e32 v110, v110, v114
	v_sub_f32_e32 v114, v116, v160
	v_mul_f32_e32 v110, v110, v114
	v_mul_f32_e32 v111, v111, v115
	v_sub_f32_e32 v114, v118, v160
	v_mul_f32_e32 v111, v111, v114
	v_mul_f32_e32 v108, v161, v108
	v_mul_f32_e32 v109, v161, v109
	v_mul_f32_e32 v111, v161, v111
	v_mul_f32_e32 v108, v68, v108
	v_mul_f32_e32 v109, v69, v109
	v_mul_f32_e32 v110, v161, v110
	v_mul_f32_e32 v111, v71, v111
	v_mul_f32_e32 v104, v104, v152
	v_mul_f32_e32 v110, v70, v110
	v_cvt_pk_bf16_f32 v108, v108, v109
	v_cvt_pk_bf16_f32 v109, v110, v111
	v_mul_f32_e32 v111, 0xbfb8aa3b, v104
	v_exp_f32_e32 v111, v111
	v_mul_f32_e32 v105, v105, v152
	v_mul_f32_e32 v115, 0xbfb8aa3b, v105
	v_exp_f32_e32 v115, v115
	v_add_f32_e32 v111, 1.0, v111
	v_rcp_f32_e32 v111, v111
	global_store_dwordx2 v[128:129], v[112:113], off offset:96
	v_lshl_add_u64 v[112:113], v[140:141], 0, v[176:177]
	global_store_dwordx2 v[112:113], v[108:109], off
	v_mul_f32_e32 v104, v104, v111
	v_add_f32_e32 v111, 1.0, v115
	v_rcp_f32_e32 v111, v111
	s_waitcnt vmcnt(17)
	v_lshlrev_b32_e32 v108, 16, v170
	v_and_b32_e32 v109, 0xffff0000, v170
	v_mul_f32_e32 v106, v106, v152
	v_sub_f32_e32 v108, v108, v160
	v_mul_f32_e32 v107, v107, v152
	v_mul_f32_e32 v104, v104, v108
	v_mul_f32_e32 v105, v105, v111
	v_mul_f32_e32 v108, 0xbfb8aa3b, v106
	v_sub_f32_e32 v109, v109, v160
	v_exp_f32_e32 v108, v108
	v_mul_f32_e32 v105, v105, v109
	v_mul_f32_e32 v109, 0xbfb8aa3b, v107
	v_exp_f32_e32 v109, v109
	v_add_f32_e32 v108, 1.0, v108
	v_rcp_f32_e32 v108, v108
	v_lshlrev_b32_e32 v110, 16, v171
	v_add_f32_e32 v109, 1.0, v109
	v_rcp_f32_e32 v109, v109
	v_and_b32_e32 v114, 0xffff0000, v171
	v_mul_f32_e32 v106, v106, v108
	v_sub_f32_e32 v108, v110, v160
	v_mul_f32_e32 v106, v106, v108
	v_mul_f32_e32 v107, v107, v109
	v_sub_f32_e32 v108, v114, v160
	v_mul_f32_e32 v107, v107, v108
	v_mul_f32_e32 v104, v161, v104
	v_mul_f32_e32 v105, v161, v105
	v_mul_f32_e32 v107, v161, v107
	v_mul_f32_e32 v104, v60, v104
	v_mul_f32_e32 v105, v61, v105
	v_mul_f32_e32 v106, v161, v106
	v_mul_f32_e32 v107, v63, v107
	v_mul_f32_e32 v100, v100, v152
	v_mul_f32_e32 v106, v62, v106
	v_cvt_pk_bf16_f32 v104, v104, v105
	v_cvt_pk_bf16_f32 v105, v106, v107
	v_mul_f32_e32 v107, 0xbfb8aa3b, v100
	v_exp_f32_e32 v107, v107
	v_mul_f32_e32 v101, v101, v152
	v_mul_f32_e32 v109, 0xbfb8aa3b, v101
	v_exp_f32_e32 v109, v109
	v_add_f32_e32 v107, 1.0, v107
	v_rcp_f32_e32 v107, v107
	global_store_dwordx2 v[112:113], v[104:105], off offset:32
	s_waitcnt vmcnt(17)
	v_lshlrev_b32_e32 v104, 16, v168
	v_and_b32_e32 v105, 0xffff0000, v168
	v_mul_f32_e32 v100, v100, v107
	v_add_f32_e32 v107, 1.0, v109
	v_rcp_f32_e32 v107, v107
	v_mul_f32_e32 v102, v102, v152
	v_sub_f32_e32 v104, v104, v160
	v_mul_f32_e32 v103, v103, v152
	v_mul_f32_e32 v100, v100, v104
	v_mul_f32_e32 v101, v101, v107
	v_mul_f32_e32 v104, 0xbfb8aa3b, v102
	v_sub_f32_e32 v105, v105, v160
	v_exp_f32_e32 v104, v104
	v_mul_f32_e32 v101, v101, v105
	v_mul_f32_e32 v105, 0xbfb8aa3b, v103
	v_exp_f32_e32 v105, v105
	v_add_f32_e32 v104, 1.0, v104
	v_rcp_f32_e32 v104, v104
	v_lshlrev_b32_e32 v106, 16, v169
	v_add_f32_e32 v105, 1.0, v105
	v_rcp_f32_e32 v105, v105
	v_and_b32_e32 v108, 0xffff0000, v169
	v_mul_f32_e32 v102, v102, v104
	v_sub_f32_e32 v104, v106, v160
	v_mul_f32_e32 v102, v102, v104
	v_mul_f32_e32 v103, v103, v105
	v_sub_f32_e32 v104, v108, v160
	v_mul_f32_e32 v103, v103, v104
	v_mul_f32_e32 v100, v161, v100
	v_mul_f32_e32 v101, v161, v101
	v_mul_f32_e32 v103, v161, v103
	v_mul_f32_e32 v100, v52, v100
	v_mul_f32_e32 v101, v53, v101
	v_mul_f32_e32 v102, v161, v102
	v_mul_f32_e32 v103, v55, v103
	v_mul_f32_e32 v96, v96, v152
	v_mul_f32_e32 v102, v54, v102
	v_cvt_pk_bf16_f32 v100, v100, v101
	v_cvt_pk_bf16_f32 v101, v102, v103
	v_mul_f32_e32 v103, 0xbfb8aa3b, v96
	v_exp_f32_e32 v103, v103
	v_mul_f32_e32 v97, v97, v152
	v_mul_f32_e32 v105, 0xbfb8aa3b, v97
	v_exp_f32_e32 v105, v105
	v_add_f32_e32 v103, 1.0, v103
	v_rcp_f32_e32 v103, v103
	global_store_dwordx2 v[112:113], v[100:101], off offset:64
	s_waitcnt vmcnt(17)
	v_and_b32_e32 v101, 0xffff0000, v166
	v_mul_f32_e32 v99, v99, v152
	v_mul_f32_e32 v96, v96, v103
	v_add_f32_e32 v103, 1.0, v105
	v_rcp_f32_e32 v103, v103
	v_sub_f32_e32 v101, v101, v160
	v_lshlrev_b32_e32 v100, 16, v166
	v_mul_f32_e32 v98, v98, v152
	v_mul_f32_e32 v97, v97, v103
	v_mul_f32_e32 v97, v97, v101
	v_mul_f32_e32 v101, 0xbfb8aa3b, v99
	v_exp_f32_e32 v101, v101
	v_sub_f32_e32 v100, v100, v160
	v_mul_f32_e32 v96, v96, v100
	v_mul_f32_e32 v100, 0xbfb8aa3b, v98
	v_add_f32_e32 v101, 1.0, v101
	v_rcp_f32_e32 v101, v101
	s_waitcnt vmcnt(16)
	v_mul_f32_e32 v92, v92, v145
	v_exp_f32_e32 v100, v100
	v_mul_f32_e32 v93, v93, v145
	v_mul_f32_e32 v99, v99, v101
	v_mul_f32_e32 v101, 0xbfb8aa3b, v92
	v_exp_f32_e32 v101, v101
	v_add_f32_e32 v100, 1.0, v100
	v_rcp_f32_e32 v100, v100
	v_mul_f32_e32 v103, 0xbfb8aa3b, v93
	v_add_f32_e32 v101, 1.0, v101
	v_rcp_f32_e32 v101, v101
	v_exp_f32_e32 v103, v103
	v_lshlrev_b32_e32 v102, 16, v167
	v_and_b32_e32 v104, 0xffff0000, v167
	v_mul_f32_e32 v98, v98, v100
	v_sub_f32_e32 v100, v102, v160
	v_mul_f32_e32 v98, v98, v100
	v_sub_f32_e32 v100, v104, v160
	v_mul_f32_e32 v92, v92, v101
	v_add_f32_e32 v101, 1.0, v103
	v_mul_f32_e32 v96, v161, v96
	v_mul_f32_e32 v97, v161, v97
	v_mul_f32_e32 v98, v161, v98
	v_mul_f32_e32 v99, v99, v100
	v_rcp_f32_e32 v101, v101
	v_mul_f32_e32 v96, v44, v96
	v_mul_f32_e32 v97, v45, v97
	v_mul_f32_e32 v98, v46, v98
	v_mul_f32_e32 v99, v161, v99
	v_mul_f32_e32 v99, v47, v99
	v_cvt_pk_bf16_f32 v96, v96, v97
	v_cvt_pk_bf16_f32 v97, v98, v99
	s_waitcnt vmcnt(14)
	v_lshlrev_b32_e32 v98, 16, v162
	v_and_b32_e32 v99, 0xffff0000, v162
	v_mul_f32_e32 v94, v94, v145
	v_sub_f32_e32 v98, v98, v146
	v_mul_f32_e32 v95, v95, v145
	v_mul_f32_e32 v92, v92, v98
	v_mul_f32_e32 v93, v93, v101
	v_mul_f32_e32 v98, 0xbfb8aa3b, v94
	v_sub_f32_e32 v99, v99, v146
	v_exp_f32_e32 v98, v98
	v_mul_f32_e32 v93, v93, v99
	v_mul_f32_e32 v99, 0xbfb8aa3b, v95
	v_exp_f32_e32 v99, v99
	v_add_f32_e32 v98, 1.0, v98
	v_rcp_f32_e32 v98, v98
	v_lshlrev_b32_e32 v100, 16, v163
	v_add_f32_e32 v99, 1.0, v99
	v_rcp_f32_e32 v99, v99
	v_and_b32_e32 v102, 0xffff0000, v163
	v_mul_f32_e32 v94, v94, v98
	v_sub_f32_e32 v98, v100, v146
	v_mul_f32_e32 v94, v94, v98
	v_mul_f32_e32 v95, v95, v99
	v_sub_f32_e32 v98, v102, v146
	v_mul_f32_e32 v95, v95, v98
	v_mul_f32_e32 v92, v147, v92
	v_mul_f32_e32 v93, v147, v93
	v_mul_f32_e32 v95, v147, v95
	v_mul_f32_e32 v92, v68, v92
	v_mul_f32_e32 v93, v69, v93
	v_mul_f32_e32 v94, v147, v94
	v_mul_f32_e32 v95, v71, v95
	v_mul_f32_e32 v88, v88, v145
	v_mul_f32_e32 v94, v70, v94
	v_cvt_pk_bf16_f32 v92, v92, v93
	v_cvt_pk_bf16_f32 v93, v94, v95
	v_mul_f32_e32 v95, 0xbfb8aa3b, v88
	v_exp_f32_e32 v95, v95
	v_mul_f32_e32 v89, v89, v145
	v_mul_f32_e32 v99, 0xbfb8aa3b, v89
	v_exp_f32_e32 v99, v99
	v_add_f32_e32 v95, 1.0, v95
	v_rcp_f32_e32 v95, v95
	global_store_dwordx2 v[112:113], v[96:97], off offset:96
	v_lshl_add_u64 v[96:97], v[140:141], 0, v[164:165]
	global_store_dwordx2 v[96:97], v[92:93], off
	v_mul_f32_e32 v88, v88, v95
	v_add_f32_e32 v95, 1.0, v99
	v_rcp_f32_e32 v95, v95
	s_waitcnt vmcnt(15)
	v_lshlrev_b32_e32 v92, 16, v158
	v_and_b32_e32 v93, 0xffff0000, v158
	v_mul_f32_e32 v90, v90, v145
	v_sub_f32_e32 v92, v92, v146
	v_mul_f32_e32 v91, v91, v145
	v_mul_f32_e32 v88, v88, v92
	v_mul_f32_e32 v89, v89, v95
	v_mul_f32_e32 v92, 0xbfb8aa3b, v90
	v_sub_f32_e32 v93, v93, v146
	v_exp_f32_e32 v92, v92
	v_mul_f32_e32 v89, v89, v93
	v_mul_f32_e32 v93, 0xbfb8aa3b, v91
	v_exp_f32_e32 v93, v93
	v_add_f32_e32 v92, 1.0, v92
	v_rcp_f32_e32 v92, v92
	v_lshlrev_b32_e32 v94, 16, v159
	v_add_f32_e32 v93, 1.0, v93
	v_rcp_f32_e32 v93, v93
	v_and_b32_e32 v98, 0xffff0000, v159
	v_mul_f32_e32 v90, v90, v92
	v_sub_f32_e32 v92, v94, v146
	v_mul_f32_e32 v90, v90, v92
	v_mul_f32_e32 v91, v91, v93
	v_sub_f32_e32 v92, v98, v146
	v_mul_f32_e32 v91, v91, v92
	v_mul_f32_e32 v88, v147, v88
	v_mul_f32_e32 v89, v147, v89
	v_mul_f32_e32 v91, v147, v91
	v_mul_f32_e32 v88, v60, v88
	v_mul_f32_e32 v89, v61, v89
	v_mul_f32_e32 v90, v147, v90
	v_mul_f32_e32 v91, v63, v91
	v_mul_f32_e32 v84, v84, v145
	v_mul_f32_e32 v90, v62, v90
	v_cvt_pk_bf16_f32 v88, v88, v89
	v_cvt_pk_bf16_f32 v89, v90, v91
	v_mul_f32_e32 v91, 0xbfb8aa3b, v84
	v_exp_f32_e32 v91, v91
	v_mul_f32_e32 v85, v85, v145
	v_mul_f32_e32 v93, 0xbfb8aa3b, v85
	v_exp_f32_e32 v93, v93
	v_add_f32_e32 v91, 1.0, v91
	v_rcp_f32_e32 v91, v91
	global_store_dwordx2 v[96:97], v[88:89], off offset:32
	s_waitcnt vmcnt(15)
	v_lshlrev_b32_e32 v88, 16, v156
	v_and_b32_e32 v89, 0xffff0000, v156
	v_mul_f32_e32 v84, v84, v91
	v_add_f32_e32 v91, 1.0, v93
	v_rcp_f32_e32 v91, v91
	v_mul_f32_e32 v86, v86, v145
	v_sub_f32_e32 v88, v88, v146
	v_mul_f32_e32 v87, v87, v145
	v_mul_f32_e32 v84, v84, v88
	v_mul_f32_e32 v85, v85, v91
	v_mul_f32_e32 v88, 0xbfb8aa3b, v86
	v_sub_f32_e32 v89, v89, v146
	v_exp_f32_e32 v88, v88
	v_mul_f32_e32 v85, v85, v89
	v_mul_f32_e32 v89, 0xbfb8aa3b, v87
	v_exp_f32_e32 v89, v89
	v_add_f32_e32 v88, 1.0, v88
	v_rcp_f32_e32 v88, v88
	v_lshlrev_b32_e32 v90, 16, v157
	v_add_f32_e32 v89, 1.0, v89
	v_rcp_f32_e32 v89, v89
	v_and_b32_e32 v92, 0xffff0000, v157
	v_mul_f32_e32 v86, v86, v88
	v_sub_f32_e32 v88, v90, v146
	v_mul_f32_e32 v86, v86, v88
	v_mul_f32_e32 v87, v87, v89
	v_sub_f32_e32 v88, v92, v146
	v_mul_f32_e32 v87, v87, v88
	v_mul_f32_e32 v84, v147, v84
	v_mul_f32_e32 v85, v147, v85
	v_mul_f32_e32 v87, v147, v87
	v_mul_f32_e32 v84, v52, v84
	v_mul_f32_e32 v85, v53, v85
	v_mul_f32_e32 v86, v147, v86
	v_mul_f32_e32 v87, v55, v87
	v_mul_f32_e32 v80, v80, v145
	v_mul_f32_e32 v86, v54, v86
	v_cvt_pk_bf16_f32 v84, v84, v85
	v_cvt_pk_bf16_f32 v85, v86, v87
	v_mul_f32_e32 v87, 0xbfb8aa3b, v80
	v_exp_f32_e32 v87, v87
	v_mul_f32_e32 v81, v81, v145
	v_mul_f32_e32 v89, 0xbfb8aa3b, v81
	v_exp_f32_e32 v89, v89
	v_add_f32_e32 v87, 1.0, v87
	v_rcp_f32_e32 v87, v87
	global_store_dwordx2 v[96:97], v[84:85], off offset:64
	s_waitcnt vmcnt(15)
	v_lshlrev_b32_e32 v84, 16, v154
	v_and_b32_e32 v85, 0xffff0000, v154
	v_mul_f32_e32 v80, v80, v87
	v_add_f32_e32 v87, 1.0, v89
	v_rcp_f32_e32 v87, v87
	v_mul_f32_e32 v82, v82, v145
	v_sub_f32_e32 v84, v84, v146
	v_mul_f32_e32 v83, v83, v145
	v_mul_f32_e32 v80, v80, v84
	v_mul_f32_e32 v81, v81, v87
	v_mul_f32_e32 v84, 0xbfb8aa3b, v82
	v_sub_f32_e32 v85, v85, v146
	v_exp_f32_e32 v84, v84
	v_mul_f32_e32 v81, v81, v85
	v_mul_f32_e32 v85, 0xbfb8aa3b, v83
	v_exp_f32_e32 v85, v85
	v_add_f32_e32 v84, 1.0, v84
	v_rcp_f32_e32 v84, v84
	v_lshlrev_b32_e32 v86, 16, v155
	v_add_f32_e32 v85, 1.0, v85
	v_rcp_f32_e32 v85, v85
	v_and_b32_e32 v88, 0xffff0000, v155
	v_mul_f32_e32 v82, v82, v84
	v_sub_f32_e32 v84, v86, v146
	v_mul_f32_e32 v82, v82, v84
	v_mul_f32_e32 v83, v83, v85
	v_sub_f32_e32 v84, v88, v146
	v_mul_f32_e32 v80, v147, v80
	v_mul_f32_e32 v81, v147, v81
	v_mul_f32_e32 v83, v83, v84
	v_mul_f32_e32 v80, v44, v80
	v_mul_f32_e32 v81, v45, v81
	v_mul_f32_e32 v82, v147, v82
	v_mul_f32_e32 v83, v147, v83
	v_mul_f32_e32 v82, v46, v82
	v_mul_f32_e32 v83, v47, v83
	v_cvt_pk_bf16_f32 v80, v80, v81
	v_cvt_pk_bf16_f32 v81, v82, v83
	global_store_dwordx2 v[96:97], v[80:81], off offset:96
	v_or_b32_e32 v80, 64, v144
	v_ashrrev_i32_e32 v81, 31, v80
	v_lshlrev_b64 v[118:119], 12, v[80:81]
	v_lshl_add_u64 v[82:83], v[80:81], 2, s[6:7]
	v_lshlrev_b64 v[84:85], 5, v[80:81]
	v_lshl_add_u64 v[80:81], v[142:143], 0, v[118:119]
	v_lshl_add_u64 v[84:85], s[28:29], 0, v[84:85]
	global_load_dword v125, v[82:83], off
	global_load_dwordx2 v[112:113], v[84:85], off
	global_load_dwordx2 v[126:127], v[80:81], off
	global_load_dwordx2 v[128:129], v[80:81], off offset:32
	global_load_dwordx2 v[130:131], v[80:81], off offset:64
	global_load_dwordx2 v[120:121], v[80:81], off offset:96
	v_or_b32_e32 v80, 0x50, v144
	v_ashrrev_i32_e32 v81, 31, v80
	v_lshlrev_b64 v[116:117], 12, v[80:81]
	v_lshl_add_u64 v[82:83], v[80:81], 2, s[6:7]
	v_lshlrev_b64 v[84:85], 5, v[80:81]
	v_lshl_add_u64 v[80:81], v[142:143], 0, v[116:117]
	v_lshl_add_u64 v[84:85], s[28:29], 0, v[84:85]
	global_load_dword v124, v[82:83], off
	global_load_dwordx2 v[100:101], v[84:85], off
	global_load_dwordx2 v[114:115], v[80:81], off
	global_load_dwordx2 v[110:111], v[80:81], off offset:32
	global_load_dwordx2 v[108:109], v[80:81], off offset:64
	global_load_dwordx2 v[106:107], v[80:81], off offset:96
	v_or_b32_e32 v80, 0x60, v144
	v_ashrrev_i32_e32 v81, 31, v80
	v_lshl_add_u64 v[82:83], v[80:81], 2, s[6:7]
	v_lshlrev_b64 v[84:85], 5, v[80:81]
	v_lshl_add_u64 v[84:85], s[28:29], 0, v[84:85]
	global_load_dword v123, v[82:83], off
	global_load_dwordx2 v[88:89], v[84:85], off
	v_or_b32_e32 v82, 0x70, v144
	v_lshlrev_b64 v[104:105], 12, v[80:81]
	v_ashrrev_i32_e32 v83, 31, v82
	v_lshl_add_u64 v[80:81], v[142:143], 0, v[104:105]
	v_lshlrev_b64 v[84:85], 5, v[82:83]
	v_lshlrev_b64 v[92:93], 12, v[82:83]
	global_load_dwordx2 v[102:103], v[80:81], off
	global_load_dwordx2 v[98:99], v[80:81], off offset:32
	global_load_dwordx2 v[96:97], v[80:81], off offset:64
	global_load_dwordx2 v[94:95], v[80:81], off offset:96
	v_lshl_add_u64 v[80:81], v[82:83], 2, s[6:7]
	v_lshl_add_u64 v[84:85], s[28:29], 0, v[84:85]
	v_lshl_add_u64 v[82:83], v[142:143], 0, v[92:93]
	global_load_dword v122, v[80:81], off
	s_nop 0
	global_load_dwordx2 v[80:81], v[84:85], off
	global_load_dwordx2 v[90:91], v[82:83], off
	global_load_dwordx2 v[86:87], v[82:83], off offset:32
	s_nop 0
	global_load_dwordx2 v[84:85], v[82:83], off offset:64
	s_nop 0
	global_load_dwordx2 v[82:83], v[82:83], off offset:96
	s_waitcnt vmcnt(23)
	v_mul_f32_e32 v76, v76, v125
	v_mul_f32_e32 v134, 0xbfb8aa3b, v76
	v_exp_f32_e32 v134, v134
	v_mul_f32_e32 v77, v77, v125
	v_mul_f32_e32 v135, 0xbfb8aa3b, v77
	v_exp_f32_e32 v135, v135
	v_add_f32_e32 v134, 1.0, v134
	v_rcp_f32_e32 v134, v134
	s_waitcnt vmcnt(21)
	v_lshlrev_b32_e32 v132, 16, v126
	v_mul_f32_e32 v78, v78, v125
	v_sub_f32_e32 v132, v132, v112
	v_mul_f32_e32 v76, v76, v134
	v_add_f32_e32 v134, 1.0, v135
	v_rcp_f32_e32 v134, v134
	v_mul_f32_e32 v76, v76, v132
	v_mul_f32_e32 v132, 0xbfb8aa3b, v78
	v_exp_f32_e32 v132, v132
	v_and_b32_e32 v126, 0xffff0000, v126
	v_mul_f32_e32 v79, v79, v125
	v_mul_f32_e32 v77, v77, v134
	v_sub_f32_e32 v126, v126, v112
	v_mul_f32_e32 v77, v77, v126
	v_add_f32_e32 v126, 1.0, v132
	v_mul_f32_e32 v132, 0xbfb8aa3b, v79
	v_exp_f32_e32 v132, v132
	v_rcp_f32_e32 v126, v126
	v_lshlrev_b32_e32 v133, 16, v127
	v_and_b32_e32 v127, 0xffff0000, v127
	v_add_f32_e32 v132, 1.0, v132
	v_rcp_f32_e32 v132, v132
	v_mul_f32_e32 v78, v78, v126
	v_sub_f32_e32 v126, v133, v112
	v_mul_f32_e32 v78, v78, v126
	v_mul_f32_e32 v79, v79, v132
	v_sub_f32_e32 v126, v127, v112
	v_mul_f32_e32 v79, v79, v126
	v_mul_f32_e32 v76, v113, v76
	v_mul_f32_e32 v77, v113, v77
	v_mul_f32_e32 v79, v113, v79
	v_mul_f32_e32 v76, v68, v76
	v_mul_f32_e32 v77, v69, v77
	v_mul_f32_e32 v78, v113, v78
	v_mul_f32_e32 v79, v71, v79
	v_mul_f32_e32 v72, v72, v125
	v_mul_f32_e32 v78, v70, v78
	v_cvt_pk_bf16_f32 v76, v76, v77
	v_cvt_pk_bf16_f32 v77, v78, v79
	v_mul_f32_e32 v79, 0xbfb8aa3b, v72
	v_exp_f32_e32 v79, v79
	v_mul_f32_e32 v73, v73, v125
	v_mul_f32_e32 v127, 0xbfb8aa3b, v73
	v_exp_f32_e32 v127, v127
	v_add_f32_e32 v79, 1.0, v79
	v_rcp_f32_e32 v79, v79
	v_lshl_add_u64 v[118:119], v[140:141], 0, v[118:119]
	global_store_dwordx2 v[118:119], v[76:77], off
	s_waitcnt vmcnt(21)
	v_lshlrev_b32_e32 v76, 16, v128
	v_mul_f32_e32 v72, v72, v79
	v_add_f32_e32 v79, 1.0, v127
	v_rcp_f32_e32 v79, v79
	v_and_b32_e32 v77, 0xffff0000, v128
	v_mul_f32_e32 v74, v74, v125
	v_sub_f32_e32 v76, v76, v112
	v_mul_f32_e32 v75, v75, v125
	v_mul_f32_e32 v72, v72, v76
	v_mul_f32_e32 v73, v73, v79
	v_mul_f32_e32 v76, 0xbfb8aa3b, v74
	v_sub_f32_e32 v77, v77, v112
	v_exp_f32_e32 v76, v76
	v_mul_f32_e32 v73, v73, v77
	v_mul_f32_e32 v77, 0xbfb8aa3b, v75
	v_exp_f32_e32 v77, v77
	v_add_f32_e32 v76, 1.0, v76
	v_rcp_f32_e32 v76, v76
	v_lshlrev_b32_e32 v78, 16, v129
	v_add_f32_e32 v77, 1.0, v77
	v_rcp_f32_e32 v77, v77
	v_and_b32_e32 v126, 0xffff0000, v129
	v_mul_f32_e32 v74, v74, v76
	v_sub_f32_e32 v76, v78, v112
	v_mul_f32_e32 v74, v74, v76
	v_mul_f32_e32 v75, v75, v77
	v_sub_f32_e32 v76, v126, v112
	v_mul_f32_e32 v75, v75, v76
	v_mul_f32_e32 v72, v113, v72
	v_mul_f32_e32 v73, v113, v73
	v_mul_f32_e32 v75, v113, v75
	v_mul_f32_e32 v72, v60, v72
	v_mul_f32_e32 v73, v61, v73
	v_mul_f32_e32 v74, v113, v74
	v_mul_f32_e32 v75, v63, v75
	v_mul_f32_e32 v64, v64, v125
	v_mul_f32_e32 v74, v62, v74
	v_cvt_pk_bf16_f32 v72, v72, v73
	v_cvt_pk_bf16_f32 v73, v74, v75
	v_mul_f32_e32 v75, 0xbfb8aa3b, v64
	v_exp_f32_e32 v75, v75
	v_mul_f32_e32 v65, v65, v125
	v_mul_f32_e32 v77, 0xbfb8aa3b, v65
	v_exp_f32_e32 v77, v77
	v_add_f32_e32 v75, 1.0, v75
	v_rcp_f32_e32 v75, v75
	global_store_dwordx2 v[118:119], v[72:73], off offset:32
	s_waitcnt vmcnt(21)
	v_lshlrev_b32_e32 v72, 16, v130
	v_and_b32_e32 v73, 0xffff0000, v130
	v_mul_f32_e32 v64, v64, v75
	v_add_f32_e32 v75, 1.0, v77
	v_rcp_f32_e32 v75, v75
	v_mul_f32_e32 v66, v66, v125
	v_sub_f32_e32 v72, v72, v112
	v_mul_f32_e32 v67, v67, v125
	v_mul_f32_e32 v64, v64, v72
	v_mul_f32_e32 v65, v65, v75
	v_mul_f32_e32 v72, 0xbfb8aa3b, v66
	v_sub_f32_e32 v73, v73, v112
	v_exp_f32_e32 v72, v72
	v_mul_f32_e32 v65, v65, v73
	v_mul_f32_e32 v73, 0xbfb8aa3b, v67
	v_exp_f32_e32 v73, v73
	v_add_f32_e32 v72, 1.0, v72
	v_rcp_f32_e32 v72, v72
	v_lshlrev_b32_e32 v74, 16, v131
	v_add_f32_e32 v73, 1.0, v73
	v_rcp_f32_e32 v73, v73
	v_and_b32_e32 v76, 0xffff0000, v131
	v_mul_f32_e32 v66, v66, v72
	v_sub_f32_e32 v72, v74, v112
	v_mul_f32_e32 v66, v66, v72
	v_mul_f32_e32 v67, v67, v73
	v_sub_f32_e32 v72, v76, v112
	v_mul_f32_e32 v67, v67, v72
	v_mul_f32_e32 v64, v113, v64
	v_mul_f32_e32 v65, v113, v65
	v_mul_f32_e32 v67, v113, v67
	v_mul_f32_e32 v64, v52, v64
	v_mul_f32_e32 v65, v53, v65
	v_mul_f32_e32 v66, v113, v66
	v_mul_f32_e32 v67, v55, v67
	v_mul_f32_e32 v56, v56, v125
	v_mul_f32_e32 v66, v54, v66
	v_cvt_pk_bf16_f32 v64, v64, v65
	v_cvt_pk_bf16_f32 v65, v66, v67
	v_mul_f32_e32 v67, 0xbfb8aa3b, v56
	v_exp_f32_e32 v67, v67
	v_mul_f32_e32 v57, v57, v125
	v_mul_f32_e32 v73, 0xbfb8aa3b, v57
	v_exp_f32_e32 v73, v73
	v_add_f32_e32 v67, 1.0, v67
	v_rcp_f32_e32 v67, v67
	global_store_dwordx2 v[118:119], v[64:65], off offset:64
	s_waitcnt vmcnt(21)
	v_and_b32_e32 v65, 0xffff0000, v120
	v_mul_f32_e32 v59, v59, v125
	v_mul_f32_e32 v56, v56, v67
	v_add_f32_e32 v67, 1.0, v73
	v_rcp_f32_e32 v67, v67
	v_sub_f32_e32 v65, v65, v112
	v_lshlrev_b32_e32 v64, 16, v120
	v_mul_f32_e32 v58, v58, v125
	v_mul_f32_e32 v57, v57, v67
	v_mul_f32_e32 v57, v57, v65
	v_mul_f32_e32 v65, 0xbfb8aa3b, v59
	v_exp_f32_e32 v65, v65
	v_sub_f32_e32 v64, v64, v112
	v_mul_f32_e32 v56, v56, v64
	v_mul_f32_e32 v64, 0xbfb8aa3b, v58
	v_add_f32_e32 v65, 1.0, v65
	v_rcp_f32_e32 v65, v65
	s_waitcnt vmcnt(20)
	v_mul_f32_e32 v48, v48, v124
	v_exp_f32_e32 v64, v64
	v_mul_f32_e32 v49, v49, v124
	v_mul_f32_e32 v59, v59, v65
	v_mul_f32_e32 v65, 0xbfb8aa3b, v48
	v_exp_f32_e32 v65, v65
	v_add_f32_e32 v64, 1.0, v64
	v_rcp_f32_e32 v64, v64
	v_mul_f32_e32 v67, 0xbfb8aa3b, v49
	v_add_f32_e32 v65, 1.0, v65
	v_rcp_f32_e32 v65, v65
	v_exp_f32_e32 v67, v67
	v_lshlrev_b32_e32 v66, 16, v121
	v_and_b32_e32 v72, 0xffff0000, v121
	v_mul_f32_e32 v58, v58, v64
	v_sub_f32_e32 v64, v66, v112
	v_mul_f32_e32 v58, v58, v64
	v_sub_f32_e32 v64, v72, v112
	v_mul_f32_e32 v48, v48, v65
	v_add_f32_e32 v65, 1.0, v67
	v_mul_f32_e32 v56, v113, v56
	v_mul_f32_e32 v57, v113, v57
	v_mul_f32_e32 v58, v113, v58
	v_mul_f32_e32 v59, v59, v64
	v_rcp_f32_e32 v65, v65
	v_mul_f32_e32 v56, v44, v56
	v_mul_f32_e32 v57, v45, v57
	v_mul_f32_e32 v58, v46, v58
	v_mul_f32_e32 v59, v113, v59
	v_mul_f32_e32 v59, v47, v59
	v_cvt_pk_bf16_f32 v56, v56, v57
	v_cvt_pk_bf16_f32 v57, v58, v59
	s_waitcnt vmcnt(18)
	v_lshlrev_b32_e32 v58, 16, v114
	v_and_b32_e32 v59, 0xffff0000, v114
	v_mul_f32_e32 v50, v50, v124
	v_sub_f32_e32 v58, v58, v100
	v_mul_f32_e32 v51, v51, v124
	v_mul_f32_e32 v48, v48, v58
	v_mul_f32_e32 v49, v49, v65
	v_mul_f32_e32 v58, 0xbfb8aa3b, v50
	v_sub_f32_e32 v59, v59, v100
	v_exp_f32_e32 v58, v58
	v_mul_f32_e32 v49, v49, v59
	v_mul_f32_e32 v59, 0xbfb8aa3b, v51
	v_exp_f32_e32 v59, v59
	v_add_f32_e32 v58, 1.0, v58
	v_rcp_f32_e32 v58, v58
	v_lshlrev_b32_e32 v64, 16, v115
	v_add_f32_e32 v59, 1.0, v59
	v_rcp_f32_e32 v59, v59
	v_and_b32_e32 v66, 0xffff0000, v115
	v_mul_f32_e32 v50, v50, v58
	v_sub_f32_e32 v58, v64, v100
	v_mul_f32_e32 v50, v50, v58
	v_mul_f32_e32 v51, v51, v59
	v_sub_f32_e32 v58, v66, v100
	v_mul_f32_e32 v51, v51, v58
	v_mul_f32_e32 v48, v101, v48
	v_mul_f32_e32 v49, v101, v49
	v_mul_f32_e32 v51, v101, v51
	v_mul_f32_e32 v48, v68, v48
	v_mul_f32_e32 v49, v69, v49
	v_mul_f32_e32 v50, v101, v50
	v_mul_f32_e32 v51, v71, v51
	v_mul_f32_e32 v40, v40, v124
	v_mul_f32_e32 v50, v70, v50
	v_cvt_pk_bf16_f32 v48, v48, v49
	v_cvt_pk_bf16_f32 v49, v50, v51
	v_mul_f32_e32 v51, 0xbfb8aa3b, v40
	v_exp_f32_e32 v51, v51
	v_mul_f32_e32 v41, v41, v124
	v_mul_f32_e32 v59, 0xbfb8aa3b, v41
	v_exp_f32_e32 v59, v59
	v_add_f32_e32 v51, 1.0, v51
	v_rcp_f32_e32 v51, v51
	global_store_dwordx2 v[118:119], v[56:57], off offset:96
	v_lshl_add_u64 v[56:57], v[140:141], 0, v[116:117]
	global_store_dwordx2 v[56:57], v[48:49], off
	v_mul_f32_e32 v40, v40, v51
	v_add_f32_e32 v51, 1.0, v59
	v_rcp_f32_e32 v51, v51
	s_waitcnt vmcnt(19)
	v_lshlrev_b32_e32 v48, 16, v110
	v_and_b32_e32 v49, 0xffff0000, v110
	v_mul_f32_e32 v42, v42, v124
	v_sub_f32_e32 v48, v48, v100
	v_mul_f32_e32 v43, v43, v124
	v_mul_f32_e32 v40, v40, v48
	v_mul_f32_e32 v41, v41, v51
	v_mul_f32_e32 v48, 0xbfb8aa3b, v42
	v_sub_f32_e32 v49, v49, v100
	v_exp_f32_e32 v48, v48
	v_mul_f32_e32 v41, v41, v49
	v_mul_f32_e32 v49, 0xbfb8aa3b, v43
	v_exp_f32_e32 v49, v49
	v_add_f32_e32 v48, 1.0, v48
	v_rcp_f32_e32 v48, v48
	v_lshlrev_b32_e32 v50, 16, v111
	v_add_f32_e32 v49, 1.0, v49
	v_rcp_f32_e32 v49, v49
	v_and_b32_e32 v58, 0xffff0000, v111
	v_mul_f32_e32 v42, v42, v48
	v_sub_f32_e32 v48, v50, v100
	v_mul_f32_e32 v42, v42, v48
	v_mul_f32_e32 v43, v43, v49
	v_sub_f32_e32 v48, v58, v100
	v_mul_f32_e32 v43, v43, v48
	v_mul_f32_e32 v40, v101, v40
	v_mul_f32_e32 v41, v101, v41
	v_mul_f32_e32 v43, v101, v43
	v_mul_f32_e32 v40, v60, v40
	v_mul_f32_e32 v41, v61, v41
	v_mul_f32_e32 v42, v101, v42
	v_mul_f32_e32 v43, v63, v43
	v_mul_f32_e32 v36, v36, v124
	v_mul_f32_e32 v42, v62, v42
	v_cvt_pk_bf16_f32 v40, v40, v41
	v_cvt_pk_bf16_f32 v41, v42, v43
	v_mul_f32_e32 v43, 0xbfb8aa3b, v36
	v_exp_f32_e32 v43, v43
	v_mul_f32_e32 v37, v37, v124
	v_mul_f32_e32 v49, 0xbfb8aa3b, v37
	v_exp_f32_e32 v49, v49
	v_add_f32_e32 v43, 1.0, v43
	v_rcp_f32_e32 v43, v43
	global_store_dwordx2 v[56:57], v[40:41], off offset:32
	s_waitcnt vmcnt(19)
	v_lshlrev_b32_e32 v40, 16, v108
	v_and_b32_e32 v41, 0xffff0000, v108
	v_mul_f32_e32 v36, v36, v43
	v_add_f32_e32 v43, 1.0, v49
	v_rcp_f32_e32 v43, v43
	v_mul_f32_e32 v38, v38, v124
	v_sub_f32_e32 v40, v40, v100
	v_mul_f32_e32 v39, v39, v124
	v_mul_f32_e32 v36, v36, v40
	v_mul_f32_e32 v37, v37, v43
	v_mul_f32_e32 v40, 0xbfb8aa3b, v38
	v_sub_f32_e32 v41, v41, v100
	v_exp_f32_e32 v40, v40
	v_mul_f32_e32 v37, v37, v41
	v_mul_f32_e32 v41, 0xbfb8aa3b, v39
	v_exp_f32_e32 v41, v41
	v_add_f32_e32 v40, 1.0, v40
	v_rcp_f32_e32 v40, v40
	v_lshlrev_b32_e32 v42, 16, v109
	v_add_f32_e32 v41, 1.0, v41
	v_rcp_f32_e32 v41, v41
	v_and_b32_e32 v48, 0xffff0000, v109
	v_mul_f32_e32 v38, v38, v40
	v_sub_f32_e32 v40, v42, v100
	v_mul_f32_e32 v38, v38, v40
	v_mul_f32_e32 v39, v39, v41
	v_sub_f32_e32 v40, v48, v100
	v_mul_f32_e32 v39, v39, v40
	v_mul_f32_e32 v36, v101, v36
	v_mul_f32_e32 v37, v101, v37
	v_mul_f32_e32 v39, v101, v39
	v_mul_f32_e32 v36, v52, v36
	v_mul_f32_e32 v37, v53, v37
	v_mul_f32_e32 v38, v101, v38
	v_mul_f32_e32 v39, v55, v39
	v_mul_f32_e32 v32, v32, v124
	v_mul_f32_e32 v38, v54, v38
	v_cvt_pk_bf16_f32 v36, v36, v37
	v_cvt_pk_bf16_f32 v37, v38, v39
	v_mul_f32_e32 v39, 0xbfb8aa3b, v32
	v_exp_f32_e32 v39, v39
	v_mul_f32_e32 v33, v33, v124
	v_mul_f32_e32 v41, 0xbfb8aa3b, v33
	v_exp_f32_e32 v41, v41
	v_add_f32_e32 v39, 1.0, v39
	v_rcp_f32_e32 v39, v39
	global_store_dwordx2 v[56:57], v[36:37], off offset:64
	s_waitcnt vmcnt(19)
	v_and_b32_e32 v37, 0xffff0000, v106
	v_mul_f32_e32 v35, v35, v124
	v_mul_f32_e32 v32, v32, v39
	v_add_f32_e32 v39, 1.0, v41
	v_rcp_f32_e32 v39, v39
	v_sub_f32_e32 v37, v37, v100
	v_lshlrev_b32_e32 v36, 16, v106
	v_mul_f32_e32 v34, v34, v124
	v_mul_f32_e32 v33, v33, v39
	v_mul_f32_e32 v33, v33, v37
	v_mul_f32_e32 v37, 0xbfb8aa3b, v35
	v_exp_f32_e32 v37, v37
	v_sub_f32_e32 v36, v36, v100
	v_mul_f32_e32 v32, v32, v36
	v_mul_f32_e32 v36, 0xbfb8aa3b, v34
	v_add_f32_e32 v37, 1.0, v37
	v_rcp_f32_e32 v37, v37
	s_waitcnt vmcnt(18)
	v_mul_f32_e32 v28, v28, v123
	v_exp_f32_e32 v36, v36
	v_mul_f32_e32 v29, v29, v123
	v_mul_f32_e32 v35, v35, v37
	v_mul_f32_e32 v37, 0xbfb8aa3b, v28
	v_exp_f32_e32 v37, v37
	v_add_f32_e32 v36, 1.0, v36
	v_rcp_f32_e32 v36, v36
	v_mul_f32_e32 v39, 0xbfb8aa3b, v29
	v_add_f32_e32 v37, 1.0, v37
	v_rcp_f32_e32 v37, v37
	v_exp_f32_e32 v39, v39
	v_lshlrev_b32_e32 v38, 16, v107
	v_and_b32_e32 v40, 0xffff0000, v107
	v_mul_f32_e32 v34, v34, v36
	v_sub_f32_e32 v36, v38, v100
	v_mul_f32_e32 v34, v34, v36
	v_sub_f32_e32 v36, v40, v100
	v_mul_f32_e32 v28, v28, v37
	v_add_f32_e32 v37, 1.0, v39
	v_mul_f32_e32 v32, v101, v32
	v_mul_f32_e32 v33, v101, v33
	v_mul_f32_e32 v34, v101, v34
	v_mul_f32_e32 v35, v35, v36
	v_rcp_f32_e32 v37, v37
	v_mul_f32_e32 v32, v44, v32
	v_mul_f32_e32 v33, v45, v33
	v_mul_f32_e32 v34, v46, v34
	v_mul_f32_e32 v35, v101, v35
	v_mul_f32_e32 v35, v47, v35
	v_cvt_pk_bf16_f32 v32, v32, v33
	v_cvt_pk_bf16_f32 v33, v34, v35
	s_waitcnt vmcnt(16)
	v_lshlrev_b32_e32 v34, 16, v102
	v_and_b32_e32 v35, 0xffff0000, v102
	v_mul_f32_e32 v30, v30, v123
	v_sub_f32_e32 v34, v34, v88
	v_mul_f32_e32 v31, v31, v123
	v_mul_f32_e32 v28, v28, v34
	v_mul_f32_e32 v29, v29, v37
	v_mul_f32_e32 v34, 0xbfb8aa3b, v30
	v_sub_f32_e32 v35, v35, v88
	v_exp_f32_e32 v34, v34
	v_mul_f32_e32 v29, v29, v35
	v_mul_f32_e32 v35, 0xbfb8aa3b, v31
	v_exp_f32_e32 v35, v35
	v_add_f32_e32 v34, 1.0, v34
	v_rcp_f32_e32 v34, v34
	v_lshlrev_b32_e32 v36, 16, v103
	v_add_f32_e32 v35, 1.0, v35
	v_rcp_f32_e32 v35, v35
	v_and_b32_e32 v38, 0xffff0000, v103
	v_mul_f32_e32 v30, v30, v34
	v_sub_f32_e32 v34, v36, v88
	v_mul_f32_e32 v30, v30, v34
	v_mul_f32_e32 v31, v31, v35
	v_sub_f32_e32 v34, v38, v88
	v_mul_f32_e32 v31, v31, v34
	v_mul_f32_e32 v28, v89, v28
	v_mul_f32_e32 v29, v89, v29
	v_mul_f32_e32 v31, v89, v31
	v_mul_f32_e32 v28, v68, v28
	v_mul_f32_e32 v29, v69, v29
	v_mul_f32_e32 v30, v89, v30
	v_mul_f32_e32 v31, v71, v31
	v_mul_f32_e32 v24, v24, v123
	v_mul_f32_e32 v30, v70, v30
	v_cvt_pk_bf16_f32 v28, v28, v29
	v_cvt_pk_bf16_f32 v29, v30, v31
	v_mul_f32_e32 v31, 0xbfb8aa3b, v24
	v_exp_f32_e32 v31, v31
	v_mul_f32_e32 v25, v25, v123
	v_mul_f32_e32 v35, 0xbfb8aa3b, v25
	v_exp_f32_e32 v35, v35
	v_add_f32_e32 v31, 1.0, v31
	v_rcp_f32_e32 v31, v31
	global_store_dwordx2 v[56:57], v[32:33], off offset:96
	v_lshl_add_u64 v[32:33], v[140:141], 0, v[104:105]
	global_store_dwordx2 v[32:33], v[28:29], off
	v_mul_f32_e32 v24, v24, v31
	v_add_f32_e32 v31, 1.0, v35
	v_rcp_f32_e32 v31, v31
	s_waitcnt vmcnt(17)
	v_lshlrev_b32_e32 v28, 16, v98
	v_and_b32_e32 v29, 0xffff0000, v98
	v_mul_f32_e32 v26, v26, v123
	v_sub_f32_e32 v28, v28, v88
	v_mul_f32_e32 v27, v27, v123
	v_mul_f32_e32 v24, v24, v28
	v_mul_f32_e32 v25, v25, v31
	v_mul_f32_e32 v28, 0xbfb8aa3b, v26
	v_sub_f32_e32 v29, v29, v88
	v_exp_f32_e32 v28, v28
	v_mul_f32_e32 v25, v25, v29
	v_mul_f32_e32 v29, 0xbfb8aa3b, v27
	v_exp_f32_e32 v29, v29
	v_add_f32_e32 v28, 1.0, v28
	v_rcp_f32_e32 v28, v28
	v_lshlrev_b32_e32 v30, 16, v99
	v_add_f32_e32 v29, 1.0, v29
	v_rcp_f32_e32 v29, v29
	v_and_b32_e32 v34, 0xffff0000, v99
	v_mul_f32_e32 v26, v26, v28
	v_sub_f32_e32 v28, v30, v88
	v_mul_f32_e32 v26, v26, v28
	v_mul_f32_e32 v27, v27, v29
	v_sub_f32_e32 v28, v34, v88
	v_mul_f32_e32 v27, v27, v28
	v_mul_f32_e32 v24, v89, v24
	v_mul_f32_e32 v25, v89, v25
	v_mul_f32_e32 v27, v89, v27
	v_mul_f32_e32 v24, v60, v24
	v_mul_f32_e32 v25, v61, v25
	v_mul_f32_e32 v26, v89, v26
	v_mul_f32_e32 v27, v63, v27
	v_mul_f32_e32 v20, v20, v123
	v_mul_f32_e32 v26, v62, v26
	v_cvt_pk_bf16_f32 v24, v24, v25
	v_cvt_pk_bf16_f32 v25, v26, v27
	v_mul_f32_e32 v27, 0xbfb8aa3b, v20
	v_exp_f32_e32 v27, v27
	v_mul_f32_e32 v21, v21, v123
	v_mul_f32_e32 v29, 0xbfb8aa3b, v21
	v_exp_f32_e32 v29, v29
	v_add_f32_e32 v27, 1.0, v27
	v_rcp_f32_e32 v27, v27
	global_store_dwordx2 v[32:33], v[24:25], off offset:32
	s_waitcnt vmcnt(17)
	v_lshlrev_b32_e32 v24, 16, v96
	v_and_b32_e32 v25, 0xffff0000, v96
	v_mul_f32_e32 v20, v20, v27
	v_add_f32_e32 v27, 1.0, v29
	v_rcp_f32_e32 v27, v27
	v_mul_f32_e32 v22, v22, v123
	v_sub_f32_e32 v24, v24, v88
	v_mul_f32_e32 v23, v23, v123
	v_mul_f32_e32 v20, v20, v24
	v_mul_f32_e32 v21, v21, v27
	v_mul_f32_e32 v24, 0xbfb8aa3b, v22
	v_sub_f32_e32 v25, v25, v88
	v_exp_f32_e32 v24, v24
	v_mul_f32_e32 v21, v21, v25
	v_mul_f32_e32 v25, 0xbfb8aa3b, v23
	v_exp_f32_e32 v25, v25
	v_add_f32_e32 v24, 1.0, v24
	v_rcp_f32_e32 v24, v24
	v_lshlrev_b32_e32 v26, 16, v97
	v_add_f32_e32 v25, 1.0, v25
	v_rcp_f32_e32 v25, v25
	v_and_b32_e32 v28, 0xffff0000, v97
	v_mul_f32_e32 v22, v22, v24
	v_sub_f32_e32 v24, v26, v88
	v_mul_f32_e32 v22, v22, v24
	v_mul_f32_e32 v23, v23, v25
	v_sub_f32_e32 v24, v28, v88
	v_mul_f32_e32 v23, v23, v24
	v_mul_f32_e32 v20, v89, v20
	v_mul_f32_e32 v21, v89, v21
	v_mul_f32_e32 v23, v89, v23
	v_mul_f32_e32 v20, v52, v20
	v_mul_f32_e32 v21, v53, v21
	v_mul_f32_e32 v22, v89, v22
	v_mul_f32_e32 v23, v55, v23
	v_mul_f32_e32 v16, v16, v123
	v_mul_f32_e32 v22, v54, v22
	v_cvt_pk_bf16_f32 v20, v20, v21
	v_cvt_pk_bf16_f32 v21, v22, v23
	v_mul_f32_e32 v23, 0xbfb8aa3b, v16
	v_exp_f32_e32 v23, v23
	v_mul_f32_e32 v17, v17, v123
	v_mul_f32_e32 v25, 0xbfb8aa3b, v17
	v_exp_f32_e32 v25, v25
	v_add_f32_e32 v23, 1.0, v23
	v_rcp_f32_e32 v23, v23
	global_store_dwordx2 v[32:33], v[20:21], off offset:64
	s_waitcnt vmcnt(17)
	v_and_b32_e32 v21, 0xffff0000, v94
	v_mul_f32_e32 v19, v19, v123
	v_mul_f32_e32 v16, v16, v23
	v_add_f32_e32 v23, 1.0, v25
	v_rcp_f32_e32 v23, v23
	v_sub_f32_e32 v21, v21, v88
	v_lshlrev_b32_e32 v20, 16, v94
	v_mul_f32_e32 v18, v18, v123
	v_mul_f32_e32 v17, v17, v23
	v_mul_f32_e32 v17, v17, v21
	v_mul_f32_e32 v21, 0xbfb8aa3b, v19
	v_exp_f32_e32 v21, v21
	v_sub_f32_e32 v20, v20, v88
	v_mul_f32_e32 v16, v16, v20
	v_mul_f32_e32 v20, 0xbfb8aa3b, v18
	v_add_f32_e32 v21, 1.0, v21
	v_rcp_f32_e32 v21, v21
	s_waitcnt vmcnt(16)
	v_mul_f32_e32 v12, v12, v122
	v_exp_f32_e32 v20, v20
	v_mul_f32_e32 v13, v13, v122
	v_mul_f32_e32 v19, v19, v21
	v_mul_f32_e32 v21, 0xbfb8aa3b, v12
	v_exp_f32_e32 v21, v21
	v_add_f32_e32 v20, 1.0, v20
	v_rcp_f32_e32 v20, v20
	v_mul_f32_e32 v23, 0xbfb8aa3b, v13
	v_add_f32_e32 v21, 1.0, v21
	v_rcp_f32_e32 v21, v21
	v_exp_f32_e32 v23, v23
	v_lshlrev_b32_e32 v22, 16, v95
	v_and_b32_e32 v24, 0xffff0000, v95
	v_mul_f32_e32 v18, v18, v20
	v_sub_f32_e32 v20, v22, v88
	v_mul_f32_e32 v18, v18, v20
	v_sub_f32_e32 v20, v24, v88
	v_mul_f32_e32 v12, v12, v21
	v_add_f32_e32 v21, 1.0, v23
	v_mul_f32_e32 v16, v89, v16
	v_mul_f32_e32 v17, v89, v17
	v_mul_f32_e32 v18, v89, v18
	v_mul_f32_e32 v19, v19, v20
	v_rcp_f32_e32 v21, v21
	v_mul_f32_e32 v16, v44, v16
	v_mul_f32_e32 v17, v45, v17
	v_mul_f32_e32 v18, v46, v18
	v_mul_f32_e32 v19, v89, v19
	v_mul_f32_e32 v19, v47, v19
	v_cvt_pk_bf16_f32 v16, v16, v17
	v_cvt_pk_bf16_f32 v17, v18, v19
	s_waitcnt vmcnt(14)
	v_lshlrev_b32_e32 v18, 16, v90
	v_and_b32_e32 v19, 0xffff0000, v90
	v_mul_f32_e32 v14, v14, v122
	v_sub_f32_e32 v18, v18, v80
	v_mul_f32_e32 v15, v15, v122
	v_mul_f32_e32 v12, v12, v18
	v_mul_f32_e32 v13, v13, v21
	v_mul_f32_e32 v18, 0xbfb8aa3b, v14
	v_sub_f32_e32 v19, v19, v80
	v_exp_f32_e32 v18, v18
	v_mul_f32_e32 v13, v13, v19
	v_mul_f32_e32 v19, 0xbfb8aa3b, v15
	v_exp_f32_e32 v19, v19
	v_add_f32_e32 v18, 1.0, v18
	v_rcp_f32_e32 v18, v18
	v_lshlrev_b32_e32 v20, 16, v91
	v_add_f32_e32 v19, 1.0, v19
	v_rcp_f32_e32 v19, v19
	v_and_b32_e32 v22, 0xffff0000, v91
	v_mul_f32_e32 v14, v14, v18
	v_sub_f32_e32 v18, v20, v80
	v_mul_f32_e32 v14, v14, v18
	v_mul_f32_e32 v15, v15, v19
	v_sub_f32_e32 v18, v22, v80
	v_mul_f32_e32 v15, v15, v18
	v_mul_f32_e32 v12, v81, v12
	v_mul_f32_e32 v13, v81, v13
	v_mul_f32_e32 v15, v81, v15
	v_mul_f32_e32 v12, v68, v12
	v_mul_f32_e32 v13, v69, v13
	v_mul_f32_e32 v14, v81, v14
	v_mul_f32_e32 v15, v71, v15
	v_mul_f32_e32 v8, v8, v122
	v_mul_f32_e32 v14, v70, v14
	v_cvt_pk_bf16_f32 v12, v12, v13
	v_cvt_pk_bf16_f32 v13, v14, v15
	v_mul_f32_e32 v15, 0xbfb8aa3b, v8
	v_exp_f32_e32 v15, v15
	v_mul_f32_e32 v9, v9, v122
	v_mul_f32_e32 v19, 0xbfb8aa3b, v9
	v_exp_f32_e32 v19, v19
	v_add_f32_e32 v15, 1.0, v15
	v_rcp_f32_e32 v15, v15
	global_store_dwordx2 v[32:33], v[16:17], off offset:96
	v_lshl_add_u64 v[16:17], v[140:141], 0, v[92:93]
	global_store_dwordx2 v[16:17], v[12:13], off
	v_mul_f32_e32 v8, v8, v15
	v_add_f32_e32 v15, 1.0, v19
	v_rcp_f32_e32 v15, v15
	s_waitcnt vmcnt(15)
	v_lshlrev_b32_e32 v12, 16, v86
	v_and_b32_e32 v13, 0xffff0000, v86
	v_mul_f32_e32 v10, v10, v122
	v_sub_f32_e32 v12, v12, v80
	v_mul_f32_e32 v11, v11, v122
	v_mul_f32_e32 v8, v8, v12
	v_mul_f32_e32 v9, v9, v15
	v_mul_f32_e32 v12, 0xbfb8aa3b, v10
	v_sub_f32_e32 v13, v13, v80
	v_exp_f32_e32 v12, v12
	v_mul_f32_e32 v9, v9, v13
	v_mul_f32_e32 v13, 0xbfb8aa3b, v11
	v_exp_f32_e32 v13, v13
	v_add_f32_e32 v12, 1.0, v12
	v_rcp_f32_e32 v12, v12
	v_lshlrev_b32_e32 v14, 16, v87
	v_add_f32_e32 v13, 1.0, v13
	v_rcp_f32_e32 v13, v13
	v_and_b32_e32 v18, 0xffff0000, v87
	v_mul_f32_e32 v10, v10, v12
	v_sub_f32_e32 v12, v14, v80
	v_mul_f32_e32 v10, v10, v12
	v_mul_f32_e32 v11, v11, v13
	v_sub_f32_e32 v12, v18, v80
	v_mul_f32_e32 v11, v11, v12
	v_mul_f32_e32 v8, v81, v8
	v_mul_f32_e32 v9, v81, v9
	v_mul_f32_e32 v11, v81, v11
	v_mul_f32_e32 v8, v60, v8
	v_mul_f32_e32 v9, v61, v9
	v_mul_f32_e32 v10, v81, v10
	v_mul_f32_e32 v11, v63, v11
	v_mul_f32_e32 v4, v4, v122
	v_mul_f32_e32 v10, v62, v10
	v_cvt_pk_bf16_f32 v8, v8, v9
	v_cvt_pk_bf16_f32 v9, v10, v11
	v_mul_f32_e32 v11, 0xbfb8aa3b, v4
	v_exp_f32_e32 v11, v11
	v_mul_f32_e32 v5, v5, v122
	v_mul_f32_e32 v13, 0xbfb8aa3b, v5
	v_exp_f32_e32 v13, v13
	v_add_f32_e32 v11, 1.0, v11
	v_rcp_f32_e32 v11, v11
	global_store_dwordx2 v[16:17], v[8:9], off offset:32
	s_waitcnt vmcnt(15)
	v_lshlrev_b32_e32 v8, 16, v84
	v_and_b32_e32 v9, 0xffff0000, v84
	v_mul_f32_e32 v4, v4, v11
	v_add_f32_e32 v11, 1.0, v13
	v_rcp_f32_e32 v11, v11
	v_mul_f32_e32 v6, v6, v122
	v_sub_f32_e32 v8, v8, v80
	v_mul_f32_e32 v7, v7, v122
	v_mul_f32_e32 v4, v4, v8
	v_mul_f32_e32 v5, v5, v11
	v_mul_f32_e32 v8, 0xbfb8aa3b, v6
	v_sub_f32_e32 v9, v9, v80
	v_exp_f32_e32 v8, v8
	v_mul_f32_e32 v5, v5, v9
	v_mul_f32_e32 v9, 0xbfb8aa3b, v7
	v_exp_f32_e32 v9, v9
	v_add_f32_e32 v8, 1.0, v8
	v_rcp_f32_e32 v8, v8
	v_lshlrev_b32_e32 v10, 16, v85
	v_add_f32_e32 v9, 1.0, v9
	v_rcp_f32_e32 v9, v9
	v_and_b32_e32 v12, 0xffff0000, v85
	v_mul_f32_e32 v6, v6, v8
	v_sub_f32_e32 v8, v10, v80
	v_mul_f32_e32 v6, v6, v8
	v_mul_f32_e32 v7, v7, v9
	v_sub_f32_e32 v8, v12, v80
	v_mul_f32_e32 v7, v7, v8
	v_mul_f32_e32 v4, v81, v4
	v_mul_f32_e32 v5, v81, v5
	v_mul_f32_e32 v7, v81, v7
	v_mul_f32_e32 v4, v52, v4
	v_mul_f32_e32 v5, v53, v5
	v_mul_f32_e32 v6, v81, v6
	v_mul_f32_e32 v7, v55, v7
	v_mul_f32_e32 v0, v0, v122
	v_mul_f32_e32 v6, v54, v6
	v_cvt_pk_bf16_f32 v4, v4, v5
	v_cvt_pk_bf16_f32 v5, v6, v7
	v_mul_f32_e32 v7, 0xbfb8aa3b, v0
	v_exp_f32_e32 v7, v7
	v_mul_f32_e32 v1, v1, v122
	v_mul_f32_e32 v9, 0xbfb8aa3b, v1
	v_exp_f32_e32 v9, v9
	v_add_f32_e32 v7, 1.0, v7
	v_rcp_f32_e32 v7, v7
	global_store_dwordx2 v[16:17], v[4:5], off offset:64
	s_waitcnt vmcnt(15)
	v_lshlrev_b32_e32 v4, 16, v82
	v_and_b32_e32 v5, 0xffff0000, v82
	v_mul_f32_e32 v0, v0, v7
	v_add_f32_e32 v7, 1.0, v9
	v_rcp_f32_e32 v7, v7
	v_mul_f32_e32 v2, v2, v122
	v_sub_f32_e32 v4, v4, v80
	v_mul_f32_e32 v3, v3, v122
	v_mul_f32_e32 v0, v0, v4
	v_mul_f32_e32 v1, v1, v7
	v_mul_f32_e32 v4, 0xbfb8aa3b, v2
	v_sub_f32_e32 v5, v5, v80
	v_exp_f32_e32 v4, v4
	v_mul_f32_e32 v1, v1, v5
	v_mul_f32_e32 v5, 0xbfb8aa3b, v3
	v_exp_f32_e32 v5, v5
	v_add_f32_e32 v4, 1.0, v4
	v_rcp_f32_e32 v4, v4
	v_lshlrev_b32_e32 v6, 16, v83
	v_add_f32_e32 v5, 1.0, v5
	v_rcp_f32_e32 v5, v5
	v_and_b32_e32 v8, 0xffff0000, v83
	v_mul_f32_e32 v2, v2, v4
	v_sub_f32_e32 v4, v6, v80
	v_mul_f32_e32 v2, v2, v4
	v_mul_f32_e32 v3, v3, v5
	v_sub_f32_e32 v4, v8, v80
	v_mul_f32_e32 v0, v81, v0
	v_mul_f32_e32 v1, v81, v1
	v_mul_f32_e32 v3, v3, v4
	v_mul_f32_e32 v0, v44, v0
	v_mul_f32_e32 v1, v45, v1
	v_mul_f32_e32 v2, v81, v2
	v_mul_f32_e32 v3, v81, v3
	v_mul_f32_e32 v2, v46, v2
	v_mul_f32_e32 v3, v47, v3
	v_cvt_pk_bf16_f32 v0, v0, v1
	v_cvt_pk_bf16_f32 v1, v2, v3
	global_store_dwordx2 v[16:17], v[0:1], off offset:96
	s_add_i32 s34, s34, s74
	s_cmpk_lt_i32 s34, 0x800
	s_cbranch_scc1 .LBB0_502

.LBB0_704:
	s_lshl_b32 s1, s51, 7
	s_lshl_b32 s0, s33, 10
	s_and_b32 s1, s1, 0x300
	s_or_b32 s0, s0, s1
	s_andn2_b64 vcc, exec, s[12:13]
	s_and_b32 s12, s16, 3
	s_cbranch_vccnz .LBB0_708
	s_ashr_i32 s1, s0, 31
	s_lshl_b32 s10, s52, 7
	s_lshl_b64 s[26:27], s[0:1], 11
	s_add_u32 s26, s5, s26
	s_addc_u32 s27, s6, s27
	s_ashr_i32 s11, s10, 31
	v_mov_b32_e32 v40, v220
	s_lshl_b64 s[10:11], s[10:11], 11
	s_add_u32 s10, s7, s10
	v_ashrrev_i32_e32 v30, 2, v40
	v_ashrrev_i32_e32 v31, 31, v30
	s_addc_u32 s11, s8, s11
	v_lshlrev_b64 v[0:1], 11, v[30:31]
	v_lshlrev_b32_e32 v4, 4, v40
	v_lshl_add_u64 v[2:3], s[10:11], 0, v[0:1]
	v_lshl_add_u64 v[0:1], s[26:27], 0, v[0:1]
	v_and_b32_e32 v152, 48, v4
	v_lshl_add_u64 v[154:155], v[0:1], 0, v[152:153]
	v_add_co_u32_e32 v32, vcc, s9, v154
	v_lshl_add_u64 v[156:157], v[2:3], 0, v[152:153]
	s_nop 0
	v_addc_co_u32_e32 v33, vcc, 0, v155, vcc
	v_add_co_u32_e32 v34, vcc, s31, v154
	global_load_dwordx4 v[6:9], v[154:155], off
	s_nop 0
	v_addc_co_u32_e32 v35, vcc, 0, v155, vcc
	v_add_co_u32_e32 v36, vcc, s35, v154
	global_load_dwordx4 v[10:13], v[32:33], off
	s_nop 0
	v_addc_co_u32_e32 v37, vcc, 0, v155, vcc
	v_add_co_u32_e32 v38, vcc, s9, v156
	global_load_dwordx4 v[14:17], v[34:35], off
	s_nop 0
	v_addc_co_u32_e32 v39, vcc, 0, v157, vcc
	global_load_dwordx4 v[18:21], v[36:37], off
	global_load_dwordx4 v[22:25], v[156:157], off
	global_load_dwordx4 v[26:29], v[38:39], off
	global_load_dwordx4 v[112:115], v[154:155], off offset:64
	global_load_dwordx4 v[120:123], v[32:33], off offset:64
	global_load_dwordx4 v[124:127], v[34:35], off offset:64
	global_load_dwordx4 v[128:131], v[36:37], off offset:64
	global_load_dwordx4 v[116:119], v[156:157], off offset:64
	global_load_dwordx4 v[132:135], v[38:39], off offset:64
	v_lshrrev_b32_e32 v31, 4, v40
	v_lshrrev_b32_e32 v41, 2, v40
	v_sub_u32_e32 v44, 0, v31
	v_sub_u32_e32 v41, 0, v41
	v_and_b32_e32 v42, 0x3ffff8f, v40
	v_lshlrev_b32_e32 v43, 6, v40
	v_xor_b32_e32 v40, v40, v44
	v_xor_b32_e32 v31, v31, v41
	v_lshlrev_b32_e32 v40, 4, v40
	v_lshlrev_b32_e32 v31, 4, v31
	v_and_b32_e32 v45, 0x1000, v43
	v_and_b32_e32 v40, 48, v40
	v_and_b32_e32 v31, 48, v31
	v_mov_b32_e32 v0, 0
	v_and_b32_e32 v46, 0x3c0, v43
	v_and_b32_e32 v43, 0xffffe3c0, v43
	v_lshl_add_u32 v42, v42, 6, v167
	v_lshl_or_b32 v152, v30, 6, v40
	v_or_b32_e32 v30, v31, v45
	s_mov_b32 s10, 0
	s_mov_b32 s1, -2
	v_mov_b32_e32 v1, v0
	v_mov_b32_e32 v2, v0
	v_mov_b32_e32 v3, v0
	v_mov_b32_e32 v4, v0
	v_mov_b32_e32 v5, v0
	v_lshl_add_u64 v[158:159], v[154:155], 0, s[22:23]
	v_lshl_add_u64 v[160:161], v[154:155], 0, s[24:25]
	v_lshl_add_u64 v[162:163], v[154:155], 0, s[28:29]
	v_or3_b32 v168, v45, v46, v31
	v_add_u32_e32 v169, v31, v43
	v_add_u32_e32 v170, v31, v42
	v_add_u32_e32 v171, v30, v46
	v_lshl_add_u64 v[164:165], v[156:157], 0, s[22:23]
	v_mov_b32_e32 v30, v0
	v_mov_b32_e32 v31, v0
	v_mov_b32_e32 v32, v0
	v_mov_b32_e32 v33, v0
	v_mov_b32_e32 v34, v0
	v_mov_b32_e32 v35, v0
	v_mov_b32_e32 v36, v0
	v_mov_b32_e32 v37, v0
	v_mov_b32_e32 v38, v0
	v_mov_b32_e32 v39, v0
	v_mov_b32_e32 v40, v0
	v_mov_b32_e32 v41, v0
	v_mov_b32_e32 v42, v0
	v_mov_b32_e32 v43, v0
	v_mov_b32_e32 v44, v0
	v_mov_b32_e32 v45, v0
	v_mov_b32_e32 v46, v0
	s_waitcnt vmcnt(11)
	ds_write_b128 v152, v[6:9]
	s_waitcnt vmcnt(10)
	ds_write_b128 v152, v[10:13] offset:4096
	s_waitcnt vmcnt(9)
	ds_write_b128 v152, v[14:17] offset:8192
	s_waitcnt vmcnt(8)
	ds_write_b128 v152, v[18:21] offset:12288
	s_waitcnt vmcnt(7)
	ds_write_b128 v152, v[22:25] offset:32768
	s_waitcnt vmcnt(6)
	ds_write_b128 v152, v[26:29] offset:36864
	v_mov_b32_e32 v6, v0
	v_mov_b32_e32 v7, v0
	v_mov_b32_e32 v8, v0
	v_mov_b32_e32 v9, v0
	v_mov_b32_e32 v10, v0
	v_mov_b32_e32 v11, v0
	v_mov_b32_e32 v12, v0
	v_mov_b32_e32 v13, v0
	v_mov_b32_e32 v14, v0
	v_mov_b32_e32 v15, v0
	v_mov_b32_e32 v16, v0
	v_mov_b32_e32 v17, v0
	v_mov_b32_e32 v18, v0
	v_mov_b32_e32 v19, v0
	v_mov_b32_e32 v20, v0
	v_mov_b32_e32 v21, v0
	v_mov_b32_e32 v22, v0
	v_mov_b32_e32 v23, v0
	v_mov_b32_e32 v24, v0
	v_mov_b32_e32 v25, v0
	v_mov_b32_e32 v26, v0
	v_mov_b32_e32 v27, v0
	v_mov_b32_e32 v28, v0
	v_mov_b32_e32 v29, v0
	v_mov_b32_e32 v47, v0
	v_mov_b32_e32 v48, v0
	v_mov_b32_e32 v49, v0
	v_mov_b32_e32 v50, v0
	v_mov_b32_e32 v51, v0
	v_mov_b32_e32 v52, v0
	v_mov_b32_e32 v53, v0
	v_mov_b32_e32 v54, v0
	v_mov_b32_e32 v55, v0
	v_mov_b32_e32 v56, v0
	v_mov_b32_e32 v57, v0
	v_mov_b32_e32 v58, v0
	v_mov_b32_e32 v59, v0
	v_mov_b32_e32 v60, v0
	v_mov_b32_e32 v61, v0
	v_mov_b32_e32 v62, v0
	v_mov_b32_e32 v63, v0
	v_mov_b32_e32 v64, v0
	v_mov_b32_e32 v65, v0
	v_mov_b32_e32 v66, v0
	v_mov_b32_e32 v67, v0
	v_mov_b32_e32 v68, v0
	v_mov_b32_e32 v69, v0
	v_mov_b32_e32 v70, v0
	v_mov_b32_e32 v71, v0
	v_mov_b32_e32 v72, v0
	v_mov_b32_e32 v73, v0
	v_mov_b32_e32 v74, v0
	v_mov_b32_e32 v75, v0
	v_mov_b32_e32 v76, v0
	v_mov_b32_e32 v77, v0
	v_mov_b32_e32 v78, v0
	v_mov_b32_e32 v79, v0
	v_mov_b32_e32 v80, v0
	v_mov_b32_e32 v81, v0
	v_mov_b32_e32 v82, v0
	v_mov_b32_e32 v83, v0
	v_mov_b32_e32 v84, v0
	v_mov_b32_e32 v85, v0
	v_mov_b32_e32 v86, v0
	v_mov_b32_e32 v87, v0
	v_mov_b32_e32 v88, v0
	v_mov_b32_e32 v89, v0
	v_mov_b32_e32 v90, v0
	v_mov_b32_e32 v91, v0
	v_mov_b32_e32 v92, v0
	v_mov_b32_e32 v93, v0
	v_mov_b32_e32 v94, v0
	v_mov_b32_e32 v95, v0
	v_mov_b32_e32 v96, v0
	v_mov_b32_e32 v97, v0
	v_mov_b32_e32 v98, v0
	v_mov_b32_e32 v99, v0
	v_mov_b32_e32 v100, v0
	v_mov_b32_e32 v101, v0
	v_mov_b32_e32 v102, v0
	v_mov_b32_e32 v103, v0
	v_mov_b32_e32 v104, v0
	v_mov_b32_e32 v105, v0
	v_mov_b32_e32 v106, v0
	v_mov_b32_e32 v107, v0
	v_mov_b32_e32 v108, v0
	v_mov_b32_e32 v109, v0
	v_mov_b32_e32 v110, v0
	v_mov_b32_e32 v111, v0
	v_mov_b32_e32 v136, v0
	v_mov_b32_e32 v137, v0
	v_mov_b32_e32 v138, v0
	v_mov_b32_e32 v139, v0
	v_mov_b32_e32 v140, v0
	v_mov_b32_e32 v141, v0
	v_mov_b32_e32 v142, v0
	v_mov_b32_e32 v143, v0
	v_mov_b32_e32 v144, v0
	v_mov_b32_e32 v145, v0
	v_mov_b32_e32 v146, v0
	v_mov_b32_e32 v147, v0
	v_mov_b32_e32 v148, v0
	v_mov_b32_e32 v149, v0
	v_mov_b32_e32 v150, v0
	v_mov_b32_e32 v151, v0
	s_waitcnt lgkmcnt(0)
	s_add_i32 s11, s10, 64
	s_min_u32 s13, s11, 0x3e0
	s_lshl_b32 s16, s13, 1
	v_lshl_add_u64 v[172:173], v[154:155], 0, s[16:17]
	v_lshl_add_u64 v[176:177], v[158:159], 0, s[16:17]
	v_lshl_add_u64 v[180:181], v[160:161], 0, s[16:17]
	v_lshl_add_u64 v[184:185], v[162:163], 0, s[16:17]
	v_lshl_add_u64 v[188:189], v[156:157], 0, s[16:17]
	v_lshl_add_u64 v[192:193], v[164:165], 0, s[16:17]

.LBB0_706:
	global_load_dwordx4 v[172:175], v[172:173], off
	ds_read_b128 v[196:199], v171 offset:32768
	global_load_dwordx4 v[176:179], v[176:177], off
	ds_read_b128 v[200:203], v171 offset:33792
	global_load_dwordx4 v[180:183], v[180:181], off
	ds_read_b128 v[204:207], v171 offset:34816
	global_load_dwordx4 v[184:187], v[184:185], off
	ds_read_b128 v[208:211], v171 offset:35840
	global_load_dwordx4 v[188:191], v[188:189], off
	ds_read_b128 v[212:215], v169
	global_load_dwordx4 v[192:195], v[192:193], off
	ds_read_b128 v[216:219], v169 offset:1024
	ds_read_b128 v[222:225], v169 offset:2048
	ds_read_b128 v[226:229], v169 offset:3072
	ds_read_b128 v[230:233], v169 offset:4096
	ds_read_b128 v[234:237], v169 offset:5120
	ds_read_b128 v[238:241], v169 offset:6144
	ds_read_b128 v[242:245], v169 offset:7168
	s_setprio 1
	s_waitcnt lgkmcnt(7)
	v_mfma_f32_16x16x32_bf16 v[148:151], v[196:199], v[212:215], v[148:151]
	v_mfma_f32_16x16x32_bf16 v[144:147], v[200:203], v[212:215], v[144:147]
	v_mfma_f32_16x16x32_bf16 v[140:143], v[204:207], v[212:215], v[140:143]
	v_mfma_f32_16x16x32_bf16 v[136:139], v[208:211], v[212:215], v[136:139]
	s_waitcnt vmcnt(11)
	ds_write_b128 v152, v[112:115] offset:16384
	s_waitcnt lgkmcnt(7)
	v_mfma_f32_16x16x32_bf16 v[108:111], v[196:199], v[216:219], v[108:111]
	v_mfma_f32_16x16x32_bf16 v[104:107], v[200:203], v[216:219], v[104:107]
	v_mfma_f32_16x16x32_bf16 v[100:103], v[204:207], v[216:219], v[100:103]
	v_mfma_f32_16x16x32_bf16 v[96:99], v[208:211], v[216:219], v[96:99]
	s_waitcnt vmcnt(9)
	ds_write_b128 v152, v[120:123] offset:20480
	s_waitcnt lgkmcnt(7)
	v_mfma_f32_16x16x32_bf16 v[92:95], v[196:199], v[222:225], v[92:95]
	v_mfma_f32_16x16x32_bf16 v[88:91], v[200:203], v[222:225], v[88:91]
	v_mfma_f32_16x16x32_bf16 v[84:87], v[204:207], v[222:225], v[84:87]
	v_mfma_f32_16x16x32_bf16 v[80:83], v[208:211], v[222:225], v[80:83]
	s_waitcnt vmcnt(8)
	ds_write_b128 v152, v[124:127] offset:24576
	s_waitcnt lgkmcnt(7)
	v_mfma_f32_16x16x32_bf16 v[76:79], v[196:199], v[226:229], v[76:79]
	v_mfma_f32_16x16x32_bf16 v[72:75], v[200:203], v[226:229], v[72:75]
	v_mfma_f32_16x16x32_bf16 v[68:71], v[204:207], v[226:229], v[68:71]
	v_mfma_f32_16x16x32_bf16 v[64:67], v[208:211], v[226:229], v[64:67]
	s_waitcnt vmcnt(7)
	ds_write_b128 v152, v[128:131] offset:28672
	s_waitcnt lgkmcnt(7)
	v_mfma_f32_16x16x32_bf16 v[60:63], v[196:199], v[230:233], v[60:63]
	v_mfma_f32_16x16x32_bf16 v[56:59], v[200:203], v[230:233], v[56:59]
	v_mfma_f32_16x16x32_bf16 v[52:55], v[204:207], v[230:233], v[52:55]
	v_mfma_f32_16x16x32_bf16 v[48:51], v[208:211], v[230:233], v[48:51]
	s_waitcnt vmcnt(7)
	ds_write_b128 v152, v[116:119] offset:40960
	s_waitcnt lgkmcnt(7)
	v_mfma_f32_16x16x32_bf16 v[44:47], v[196:199], v[234:237], v[44:47]
	v_mfma_f32_16x16x32_bf16 v[40:43], v[200:203], v[234:237], v[40:43]
	v_mfma_f32_16x16x32_bf16 v[36:39], v[204:207], v[234:237], v[36:39]
	v_mfma_f32_16x16x32_bf16 v[32:35], v[208:211], v[234:237], v[32:35]
	s_waitcnt vmcnt(6)
	ds_write_b128 v152, v[132:135] offset:45056
	s_waitcnt lgkmcnt(7)
	v_mfma_f32_16x16x32_bf16 v[28:31], v[196:199], v[238:241], v[28:31]
	v_mfma_f32_16x16x32_bf16 v[24:27], v[200:203], v[238:241], v[24:27]
	v_mfma_f32_16x16x32_bf16 v[20:23], v[204:207], v[238:241], v[20:23]
	v_mfma_f32_16x16x32_bf16 v[16:19], v[208:211], v[238:241], v[16:19]
	s_waitcnt lgkmcnt(6)
	v_mfma_f32_16x16x32_bf16 v[12:15], v[196:199], v[242:245], v[12:15]
	v_mfma_f32_16x16x32_bf16 v[8:11], v[200:203], v[242:245], v[8:11]
	v_mfma_f32_16x16x32_bf16 v[4:7], v[204:207], v[242:245], v[4:7]
	v_mfma_f32_16x16x32_bf16 v[0:3], v[208:211], v[242:245], v[0:3]
	s_setprio 0
	s_min_u32 s10, s10, 0x380
	s_lshl_b32 s16, s10, 1
	s_mov_b32 s27, s17
	s_add_i32 s26, s16, 0xc0
	v_lshl_add_u64 v[112:113], v[154:155], 0, s[16:17]
	v_lshl_add_u64 v[116:117], v[156:157], 0, s[16:17]
	v_lshl_add_u64 v[120:121], v[158:159], 0, s[26:27]
	v_lshl_add_u64 v[124:125], v[160:161], 0, s[26:27]
	v_lshl_add_u64 v[128:129], v[162:163], 0, s[26:27]
	v_lshl_add_u64 v[132:133], v[164:165], 0, s[26:27]
	s_waitcnt lgkmcnt(0)
	s_barrier
	global_load_dwordx4 v[112:115], v[112:113], off offset:192
	ds_read_b128 v[196:199], v168 offset:40960
	global_load_dwordx4 v[116:119], v[116:117], off offset:192
	ds_read_b128 v[200:203], v168 offset:41984
	global_load_dwordx4 v[120:123], v[120:121], off
	ds_read_b128 v[204:207], v168 offset:43008
	global_load_dwordx4 v[124:127], v[124:125], off
	ds_read_b128 v[208:211], v168 offset:44032
	global_load_dwordx4 v[128:131], v[128:129], off
	ds_read_b128 v[212:215], v170
	global_load_dwordx4 v[132:135], v[132:133], off
	ds_read_b128 v[216:219], v170 offset:1024
	ds_read_b128 v[222:225], v170 offset:2048
	ds_read_b128 v[226:229], v170 offset:3072
	ds_read_b128 v[230:233], v170 offset:4096
	ds_read_b128 v[234:237], v170 offset:5120
	ds_read_b128 v[238:241], v170 offset:6144
	ds_read_b128 v[242:245], v170 offset:7168
	s_setprio 1
	s_waitcnt lgkmcnt(7)
	v_mfma_f32_16x16x32_bf16 v[148:151], v[196:199], v[212:215], v[148:151]
	v_mfma_f32_16x16x32_bf16 v[144:147], v[200:203], v[212:215], v[144:147]
	v_mfma_f32_16x16x32_bf16 v[140:143], v[204:207], v[212:215], v[140:143]
	v_mfma_f32_16x16x32_bf16 v[136:139], v[208:211], v[212:215], v[136:139]
	s_waitcnt vmcnt(11)
	ds_write_b128 v152, v[172:175]
	s_waitcnt lgkmcnt(7)
	v_mfma_f32_16x16x32_bf16 v[108:111], v[196:199], v[216:219], v[108:111]
	v_mfma_f32_16x16x32_bf16 v[104:107], v[200:203], v[216:219], v[104:107]
	v_mfma_f32_16x16x32_bf16 v[100:103], v[204:207], v[216:219], v[100:103]
	v_mfma_f32_16x16x32_bf16 v[96:99], v[208:211], v[216:219], v[96:99]
	s_waitcnt vmcnt(10)
	ds_write_b128 v152, v[176:179] offset:4096
	s_waitcnt lgkmcnt(7)
	v_mfma_f32_16x16x32_bf16 v[92:95], v[196:199], v[222:225], v[92:95]
	v_mfma_f32_16x16x32_bf16 v[88:91], v[200:203], v[222:225], v[88:91]
	v_mfma_f32_16x16x32_bf16 v[84:87], v[204:207], v[222:225], v[84:87]
	v_mfma_f32_16x16x32_bf16 v[80:83], v[208:211], v[222:225], v[80:83]
	s_waitcnt vmcnt(9)
	ds_write_b128 v152, v[180:183] offset:8192
	s_waitcnt lgkmcnt(7)
	v_mfma_f32_16x16x32_bf16 v[76:79], v[196:199], v[226:229], v[76:79]
	v_mfma_f32_16x16x32_bf16 v[72:75], v[200:203], v[226:229], v[72:75]
	v_mfma_f32_16x16x32_bf16 v[68:71], v[204:207], v[226:229], v[68:71]
	v_mfma_f32_16x16x32_bf16 v[64:67], v[208:211], v[226:229], v[64:67]
	s_waitcnt vmcnt(8)
	ds_write_b128 v152, v[184:187] offset:12288
	s_waitcnt lgkmcnt(7)
	v_mfma_f32_16x16x32_bf16 v[60:63], v[196:199], v[230:233], v[60:63]
	v_mfma_f32_16x16x32_bf16 v[56:59], v[200:203], v[230:233], v[56:59]
	v_mfma_f32_16x16x32_bf16 v[52:55], v[204:207], v[230:233], v[52:55]
	v_mfma_f32_16x16x32_bf16 v[48:51], v[208:211], v[230:233], v[48:51]
	s_waitcnt vmcnt(7)
	ds_write_b128 v152, v[188:191] offset:32768
	s_waitcnt lgkmcnt(7)
	v_mfma_f32_16x16x32_bf16 v[44:47], v[196:199], v[234:237], v[44:47]
	v_mfma_f32_16x16x32_bf16 v[40:43], v[200:203], v[234:237], v[40:43]
	v_mfma_f32_16x16x32_bf16 v[36:39], v[204:207], v[234:237], v[36:39]
	v_mfma_f32_16x16x32_bf16 v[32:35], v[208:211], v[234:237], v[32:35]
	s_waitcnt vmcnt(6)
	ds_write_b128 v152, v[192:195] offset:36864
	s_waitcnt lgkmcnt(7)
	v_mfma_f32_16x16x32_bf16 v[28:31], v[196:199], v[238:241], v[28:31]
	v_mfma_f32_16x16x32_bf16 v[24:27], v[200:203], v[238:241], v[24:27]
	v_mfma_f32_16x16x32_bf16 v[20:23], v[204:207], v[238:241], v[20:23]
	v_mfma_f32_16x16x32_bf16 v[16:19], v[208:211], v[238:241], v[16:19]
	s_waitcnt lgkmcnt(6)
	v_mfma_f32_16x16x32_bf16 v[12:15], v[196:199], v[242:245], v[12:15]
	v_mfma_f32_16x16x32_bf16 v[8:11], v[200:203], v[242:245], v[8:11]
	v_mfma_f32_16x16x32_bf16 v[4:7], v[204:207], v[242:245], v[4:7]
	v_mfma_f32_16x16x32_bf16 v[0:3], v[208:211], v[242:245], v[0:3]
	s_setprio 0
	s_add_i32 s1, s1, 2
	s_mov_b32 s10, s11
	s_add_i32 s11, s10, 64
	s_min_u32 s13, s11, 0x3e0
	s_lshl_b32 s16, s13, 1
	v_lshl_add_u64 v[172:173], v[154:155], 0, s[16:17]
	v_lshl_add_u64 v[176:177], v[158:159], 0, s[16:17]
	v_lshl_add_u64 v[180:181], v[160:161], 0, s[16:17]
	v_lshl_add_u64 v[184:185], v[162:163], 0, s[16:17]
	v_lshl_add_u64 v[188:189], v[156:157], 0, s[16:17]
	v_lshl_add_u64 v[192:193], v[164:165], 0, s[16:17]
	s_cmp_lt_u32 s1, 30
	s_waitcnt lgkmcnt(0)
	s_cbranch_scc1 .Lrot_3
	s_barrier
	s_waitcnt vmcnt(4)
	v_mov_b32_e32 v116, v220
	s_nop 0
	v_and_b32_e32 v112, 0xffffff80, v116
	v_add_u32_e32 v117, s0, v112
	v_and_or_b32 v114, v116, 15, v117
	v_ashrrev_i32_e32 v115, 31, v114
	v_lshl_add_u64 v[112:113], v[114:115], 2, s[14:15]
	global_load_dword v246, v[112:113], off offset:64
	global_load_dword v247, v[112:113], off offset:128
	global_load_dword v248, v[112:113], off offset:192
	global_load_dword v249, v[112:113], off offset:256
	global_load_dword v250, v[112:113], off offset:320
	global_load_dword v251, v[112:113], off offset:384
	global_load_dword v252, v[112:113], off offset:448
	global_load_dword v122, v[112:113], off
	v_and_b32_e32 v112, 64, v116
	v_lshrrev_b32_e32 v115, 1, v116
	v_ashrrev_i32_e32 v116, 14, v117
	v_ashrrev_i32_e32 v117, 31, v116
	v_lshlrev_b32_e32 v152, 1, v112
	v_or_b32_e32 v118, 16, v114
	v_lshlrev_b64 v[116:117], 16, v[116:117]
	v_lshl_add_u64 v[112:113], s[38:39], 0, v[152:153]
	v_and_b32_e32 v152, 24, v115
	v_ashrrev_i32_e32 v119, 31, v118
	v_lshl_or_b32 v115, s12, 14, v116
	s_waitcnt vmcnt(4)
	v_lshl_add_u64 v[120:121], v[118:119], 2, s[14:15]
	v_lshl_add_u64 v[112:113], v[112:113], 0, v[152:153]
	s_waitcnt vmcnt(0)
	v_fmamk_f32 v116, v122, 0x3a800000, v166
	v_mul_f32_e32 v119, 0x4b800000, v116
	v_cmp_gt_f32_e32 vcc, s40, v116
	s_nop 1
	v_cndmask_b32_e32 v116, v116, v119, vcc
	v_rsq_f32_e32 v119, v116
	v_and_or_b32 v116, v114, s41, v115
	v_lshlrev_b64 v[122:123], 8, v[116:117]
	v_lshl_add_u64 v[122:123], v[112:113], 0, v[122:123]
	v_mul_f32_e32 v116, 0x45800000, v119
	v_cndmask_b32_e32 v116, v119, v116, vcc
	v_mul_f32_e32 v124, v149, v116
	v_mul_f32_e32 v125, v150, v116
	v_mul_f32_e32 v119, v148, v116
	v_mul_f32_e32 v126, v151, v116
	v_mul_f32_e32 v127, v144, v116
	v_mul_f32_e32 v128, v145, v116
	v_mul_f32_e32 v129, v146, v116
	v_mul_f32_e32 v130, v147, v116
	v_mul_f32_e32 v131, v140, v116
	v_cvt_pk_bf16_f32 v124, v119, v124
	v_cvt_pk_bf16_f32 v125, v125, v126
	v_mul_f32_e32 v132, v141, v116
	v_mul_f32_e32 v133, v142, v116
	v_mul_f32_e32 v134, v143, v116
	v_mul_f32_e32 v135, v136, v116
	v_mul_f32_e32 v136, v137, v116
	v_mul_f32_e32 v137, v138, v116
	v_mul_f32_e32 v116, v139, v116
	v_cvt_pk_bf16_f32 v126, v127, v128
	v_cvt_pk_bf16_f32 v127, v129, v130
	v_cvt_pk_bf16_f32 v128, v131, v132
	v_cvt_pk_bf16_f32 v129, v133, v134
	v_cvt_pk_bf16_f32 v130, v135, v136
	v_cvt_pk_bf16_f32 v131, v137, v116
	global_store_dwordx2 v[122:123], v[124:125], off
	global_store_dwordx2 v[122:123], v[126:127], off offset:32
	global_store_dwordx2 v[122:123], v[128:129], off offset:64
	global_store_dwordx2 v[122:123], v[130:131], off offset:96
	v_mov_b32_e32 v116, v246
	v_or_b32_e32 v120, 32, v114
	v_ashrrev_i32_e32 v121, 31, v120
	v_lshl_add_u64 v[122:123], v[120:121], 2, s[14:15]
	v_fmamk_f32 v116, v116, 0x3a800000, v166
	v_mul_f32_e32 v119, 0x4b800000, v116
	v_cmp_gt_f32_e32 vcc, s40, v116
	s_nop 1
	v_cndmask_b32_e32 v116, v116, v119, vcc
	v_rsq_f32_e32 v121, v116
	v_and_or_b32 v116, v118, s42, v115
	v_lshlrev_b64 v[118:119], 8, v[116:117]
	v_lshl_add_u64 v[118:119], v[112:113], 0, v[118:119]
	v_mul_f32_e32 v116, 0x45800000, v121
	v_cndmask_b32_e32 v116, v121, v116, vcc
	v_mul_f32_e32 v108, v108, v116
	v_mul_f32_e32 v109, v109, v116
	v_mul_f32_e32 v110, v110, v116
	v_mul_f32_e32 v111, v111, v116
	v_mul_f32_e32 v100, v100, v116
	v_mul_f32_e32 v101, v101, v116
	v_mul_f32_e32 v102, v102, v116
	v_mul_f32_e32 v103, v103, v116
	v_mul_f32_e32 v121, v96, v116
	v_mul_f32_e32 v124, v97, v116
	v_cvt_pk_bf16_f32 v96, v108, v109
	v_cvt_pk_bf16_f32 v97, v110, v111
	v_mul_f32_e32 v104, v104, v116
	v_mul_f32_e32 v105, v105, v116
	v_mul_f32_e32 v106, v106, v116
	v_mul_f32_e32 v107, v107, v116
	v_mul_f32_e32 v125, v98, v116
	v_mul_f32_e32 v116, v99, v116
	v_cvt_pk_bf16_f32 v98, v104, v105
	v_cvt_pk_bf16_f32 v99, v106, v107
	v_cvt_pk_bf16_f32 v100, v100, v101
	v_cvt_pk_bf16_f32 v101, v102, v103
	v_cvt_pk_bf16_f32 v102, v121, v124
	v_cvt_pk_bf16_f32 v103, v125, v116
	global_store_dwordx2 v[118:119], v[96:97], off
	global_store_dwordx2 v[118:119], v[98:99], off offset:32
	global_store_dwordx2 v[118:119], v[100:101], off offset:64
	global_store_dwordx2 v[118:119], v[102:103], off offset:96
	v_mov_b32_e32 v100, v247
	v_or_b32_e32 v96, 48, v114
	v_ashrrev_i32_e32 v97, 31, v96
	v_lshl_add_u64 v[98:99], v[96:97], 2, s[14:15]
	v_and_or_b32 v116, v120, s43, v115
	v_fmamk_f32 v97, v100, 0x3a800000, v166
	v_mul_f32_e32 v100, 0x4b800000, v97
	v_cmp_gt_f32_e32 vcc, s40, v97
	s_nop 1
	v_cndmask_b32_e32 v97, v97, v100, vcc
	v_rsq_f32_e32 v97, v97
	v_lshlrev_b64 v[100:101], 8, v[116:117]
	v_lshl_add_u64 v[100:101], v[112:113], 0, v[100:101]
	v_and_or_b32 v116, v96, s44, v115
	v_mul_f32_e32 v102, 0x45800000, v97
	v_cndmask_b32_e32 v97, v97, v102, vcc
	v_mul_f32_e32 v92, v92, v97
	v_mul_f32_e32 v93, v93, v97
	v_mul_f32_e32 v94, v94, v97
	v_mul_f32_e32 v95, v95, v97
	v_mul_f32_e32 v84, v84, v97
	v_mul_f32_e32 v85, v85, v97
	v_mul_f32_e32 v86, v86, v97
	v_mul_f32_e32 v87, v87, v97
	v_mul_f32_e32 v102, v80, v97
	v_mul_f32_e32 v103, v81, v97
	v_cvt_pk_bf16_f32 v80, v92, v93
	v_cvt_pk_bf16_f32 v81, v94, v95
	v_mul_f32_e32 v88, v88, v97
	v_mul_f32_e32 v89, v89, v97
	v_mul_f32_e32 v90, v90, v97
	v_mul_f32_e32 v91, v91, v97
	v_mul_f32_e32 v104, v82, v97
	v_mul_f32_e32 v97, v83, v97
	v_cvt_pk_bf16_f32 v82, v88, v89
	v_cvt_pk_bf16_f32 v83, v90, v91
	v_cvt_pk_bf16_f32 v84, v84, v85
	v_cvt_pk_bf16_f32 v85, v86, v87
	v_cvt_pk_bf16_f32 v86, v102, v103
	v_cvt_pk_bf16_f32 v87, v104, v97
	global_store_dwordx2 v[100:101], v[80:81], off
	global_store_dwordx2 v[100:101], v[82:83], off offset:32
	global_store_dwordx2 v[100:101], v[84:85], off offset:64
	global_store_dwordx2 v[100:101], v[86:87], off offset:96
	v_mov_b32_e32 v84, v248
	v_or_b32_e32 v80, 64, v114
	v_ashrrev_i32_e32 v81, 31, v80
	v_lshl_add_u64 v[82:83], v[80:81], 2, s[14:15]
	v_fmamk_f32 v81, v84, 0x3a800000, v166
	v_mul_f32_e32 v84, 0x4b800000, v81
	v_cmp_gt_f32_e32 vcc, s40, v81
	s_nop 1
	v_cndmask_b32_e32 v81, v81, v84, vcc
	v_rsq_f32_e32 v81, v81
	v_lshlrev_b64 v[84:85], 8, v[116:117]
	v_lshl_add_u64 v[84:85], v[112:113], 0, v[84:85]
	v_and_or_b32 v116, v80, s45, v115
	v_mul_f32_e32 v86, 0x45800000, v81
	v_cndmask_b32_e32 v81, v81, v86, vcc
	v_mul_f32_e32 v76, v76, v81
	v_mul_f32_e32 v77, v77, v81
	v_mul_f32_e32 v78, v78, v81
	v_mul_f32_e32 v79, v79, v81
	v_mul_f32_e32 v68, v68, v81
	v_mul_f32_e32 v69, v69, v81
	v_mul_f32_e32 v70, v70, v81
	v_mul_f32_e32 v71, v71, v81
	v_mul_f32_e32 v86, v64, v81
	v_mul_f32_e32 v87, v65, v81
	v_cvt_pk_bf16_f32 v64, v76, v77
	v_cvt_pk_bf16_f32 v65, v78, v79
	v_mul_f32_e32 v72, v72, v81
	v_mul_f32_e32 v73, v73, v81
	v_mul_f32_e32 v74, v74, v81
	v_mul_f32_e32 v75, v75, v81
	v_mul_f32_e32 v88, v66, v81
	v_mul_f32_e32 v81, v67, v81
	v_cvt_pk_bf16_f32 v66, v72, v73
	v_cvt_pk_bf16_f32 v67, v74, v75
	v_cvt_pk_bf16_f32 v68, v68, v69
	v_cvt_pk_bf16_f32 v69, v70, v71
	v_cvt_pk_bf16_f32 v70, v86, v87
	v_cvt_pk_bf16_f32 v71, v88, v81
	global_store_dwordx2 v[84:85], v[64:65], off
	global_store_dwordx2 v[84:85], v[66:67], off offset:32
	global_store_dwordx2 v[84:85], v[68:69], off offset:64
	global_store_dwordx2 v[84:85], v[70:71], off offset:96
	v_mov_b32_e32 v68, v249
	v_or_b32_e32 v64, 0x50, v114
	v_ashrrev_i32_e32 v65, 31, v64
	v_lshl_add_u64 v[66:67], v[64:65], 2, s[14:15]
	v_fmamk_f32 v65, v68, 0x3a800000, v166
	v_mul_f32_e32 v68, 0x4b800000, v65
	v_cmp_gt_f32_e32 vcc, s40, v65
	s_nop 1
	v_cndmask_b32_e32 v65, v65, v68, vcc
	v_rsq_f32_e32 v65, v65
	v_lshlrev_b64 v[68:69], 8, v[116:117]
	v_lshl_add_u64 v[68:69], v[112:113], 0, v[68:69]
	v_and_or_b32 v116, v64, s46, v115
	v_mul_f32_e32 v70, 0x45800000, v65
	v_cndmask_b32_e32 v65, v65, v70, vcc
	v_mul_f32_e32 v60, v60, v65
	v_mul_f32_e32 v61, v61, v65
	v_mul_f32_e32 v62, v62, v65
	v_mul_f32_e32 v63, v63, v65
	v_mul_f32_e32 v52, v52, v65
	v_mul_f32_e32 v53, v53, v65
	v_mul_f32_e32 v54, v54, v65
	v_mul_f32_e32 v55, v55, v65
	v_mul_f32_e32 v70, v48, v65
	v_mul_f32_e32 v71, v49, v65
	v_cvt_pk_bf16_f32 v48, v60, v61
	v_cvt_pk_bf16_f32 v49, v62, v63
	v_mul_f32_e32 v56, v56, v65
	v_mul_f32_e32 v57, v57, v65
	v_mul_f32_e32 v58, v58, v65
	v_mul_f32_e32 v59, v59, v65
	v_mul_f32_e32 v72, v50, v65
	v_mul_f32_e32 v65, v51, v65
	v_cvt_pk_bf16_f32 v50, v56, v57
	v_cvt_pk_bf16_f32 v51, v58, v59
	v_cvt_pk_bf16_f32 v52, v52, v53
	v_cvt_pk_bf16_f32 v53, v54, v55
	v_cvt_pk_bf16_f32 v54, v70, v71
	v_cvt_pk_bf16_f32 v55, v72, v65
	global_store_dwordx2 v[68:69], v[48:49], off
	global_store_dwordx2 v[68:69], v[50:51], off offset:32
	global_store_dwordx2 v[68:69], v[52:53], off offset:64
	global_store_dwordx2 v[68:69], v[54:55], off offset:96
	v_mov_b32_e32 v52, v250
	v_or_b32_e32 v48, 0x60, v114
	v_ashrrev_i32_e32 v49, 31, v48
	v_lshl_add_u64 v[50:51], v[48:49], 2, s[14:15]
	v_fmamk_f32 v49, v52, 0x3a800000, v166
	v_mul_f32_e32 v52, 0x4b800000, v49
	v_cmp_gt_f32_e32 vcc, s40, v49
	s_nop 1
	v_cndmask_b32_e32 v49, v49, v52, vcc
	v_rsq_f32_e32 v49, v49
	v_lshlrev_b64 v[52:53], 8, v[116:117]
	v_lshl_add_u64 v[52:53], v[112:113], 0, v[52:53]
	v_and_or_b32 v116, v48, s47, v115
	v_mul_f32_e32 v54, 0x45800000, v49
	v_cndmask_b32_e32 v49, v49, v54, vcc
	v_mul_f32_e32 v44, v44, v49
	v_mul_f32_e32 v45, v45, v49
	v_mul_f32_e32 v46, v46, v49
	v_mul_f32_e32 v47, v47, v49
	v_mul_f32_e32 v36, v36, v49
	v_mul_f32_e32 v37, v37, v49
	v_mul_f32_e32 v38, v38, v49
	v_mul_f32_e32 v39, v39, v49
	v_mul_f32_e32 v54, v32, v49
	v_mul_f32_e32 v55, v33, v49
	v_cvt_pk_bf16_f32 v32, v44, v45
	v_cvt_pk_bf16_f32 v33, v46, v47
	v_mul_f32_e32 v40, v40, v49
	v_mul_f32_e32 v41, v41, v49
	v_mul_f32_e32 v42, v42, v49
	v_mul_f32_e32 v43, v43, v49
	v_mul_f32_e32 v56, v34, v49
	v_mul_f32_e32 v49, v35, v49
	v_cvt_pk_bf16_f32 v34, v40, v41
	v_cvt_pk_bf16_f32 v35, v42, v43
	v_cvt_pk_bf16_f32 v36, v36, v37
	v_cvt_pk_bf16_f32 v37, v38, v39
	v_cvt_pk_bf16_f32 v38, v54, v55
	v_cvt_pk_bf16_f32 v39, v56, v49
	global_store_dwordx2 v[52:53], v[32:33], off
	global_store_dwordx2 v[52:53], v[34:35], off offset:32
	global_store_dwordx2 v[52:53], v[36:37], off offset:64
	global_store_dwordx2 v[52:53], v[38:39], off offset:96
	v_mov_b32_e32 v36, v251
	v_or_b32_e32 v32, 0x70, v114
	v_ashrrev_i32_e32 v33, 31, v32
	v_lshl_add_u64 v[34:35], v[32:33], 2, s[14:15]
	v_fmamk_f32 v33, v36, 0x3a800000, v166
	v_mul_f32_e32 v36, 0x4b800000, v33
	v_cmp_gt_f32_e32 vcc, s40, v33
	s_nop 1
	v_cndmask_b32_e32 v33, v33, v36, vcc
	v_rsq_f32_e32 v33, v33
	v_lshlrev_b64 v[36:37], 8, v[116:117]
	v_lshl_add_u64 v[36:37], v[112:113], 0, v[36:37]
	v_and_or_b32 v116, v32, s48, v115
	v_mul_f32_e32 v38, 0x45800000, v33
	v_cndmask_b32_e32 v33, v33, v38, vcc
	v_mul_f32_e32 v28, v28, v33
	v_mul_f32_e32 v29, v29, v33
	v_mul_f32_e32 v30, v30, v33
	v_mul_f32_e32 v31, v31, v33
	v_mul_f32_e32 v20, v20, v33
	v_mul_f32_e32 v21, v21, v33
	v_mul_f32_e32 v22, v22, v33
	v_mul_f32_e32 v23, v23, v33
	v_mul_f32_e32 v38, v16, v33
	v_mul_f32_e32 v39, v17, v33
	v_cvt_pk_bf16_f32 v16, v28, v29
	v_cvt_pk_bf16_f32 v17, v30, v31
	v_mul_f32_e32 v24, v24, v33
	v_mul_f32_e32 v25, v25, v33
	v_mul_f32_e32 v26, v26, v33
	v_mul_f32_e32 v27, v27, v33
	v_mul_f32_e32 v40, v18, v33
	v_mul_f32_e32 v33, v19, v33
	v_cvt_pk_bf16_f32 v18, v24, v25
	v_cvt_pk_bf16_f32 v19, v26, v27
	v_cvt_pk_bf16_f32 v20, v20, v21
	v_cvt_pk_bf16_f32 v21, v22, v23
	v_cvt_pk_bf16_f32 v22, v38, v39
	v_cvt_pk_bf16_f32 v23, v40, v33
	global_store_dwordx2 v[36:37], v[16:17], off
	global_store_dwordx2 v[36:37], v[18:19], off offset:32
	global_store_dwordx2 v[36:37], v[20:21], off offset:64
	global_store_dwordx2 v[36:37], v[22:23], off offset:96
	v_mov_b32_e32 v16, v252
	v_fmamk_f32 v16, v16, 0x3a800000, v166
	v_mul_f32_e32 v17, 0x4b800000, v16
	v_cmp_gt_f32_e32 vcc, s40, v16
	s_nop 1
	v_cndmask_b32_e32 v16, v16, v17, vcc
	v_rsq_f32_e32 v18, v16
	v_lshlrev_b64 v[16:17], 8, v[116:117]
	v_lshl_add_u64 v[16:17], v[112:113], 0, v[16:17]
	v_mul_f32_e32 v19, 0x45800000, v18
	v_cndmask_b32_e32 v18, v18, v19, vcc
	v_mul_f32_e32 v12, v12, v18
	v_mul_f32_e32 v13, v13, v18
	v_mul_f32_e32 v14, v14, v18
	v_mul_f32_e32 v15, v15, v18
	v_mul_f32_e32 v4, v4, v18
	v_mul_f32_e32 v5, v5, v18
	v_mul_f32_e32 v6, v6, v18
	v_mul_f32_e32 v7, v7, v18
	v_mul_f32_e32 v19, v0, v18
	v_mul_f32_e32 v20, v1, v18
	v_cvt_pk_bf16_f32 v0, v12, v13
	v_cvt_pk_bf16_f32 v1, v14, v15
	v_mul_f32_e32 v8, v8, v18
	v_mul_f32_e32 v9, v9, v18
	v_mul_f32_e32 v10, v10, v18
	v_mul_f32_e32 v11, v11, v18
	v_mul_f32_e32 v21, v2, v18
	v_mul_f32_e32 v18, v3, v18
	v_cvt_pk_bf16_f32 v2, v8, v9
	v_cvt_pk_bf16_f32 v3, v10, v11
	v_cvt_pk_bf16_f32 v4, v4, v5
	v_cvt_pk_bf16_f32 v5, v6, v7
	v_cvt_pk_bf16_f32 v6, v19, v20
	v_cvt_pk_bf16_f32 v7, v21, v18
	global_store_dwordx2 v[16:17], v[0:1], off
	global_store_dwordx2 v[16:17], v[2:3], off offset:32
	global_store_dwordx2 v[16:17], v[4:5], off offset:64
	global_store_dwordx2 v[16:17], v[6:7], off offset:96
	s_branch .LBB0_699
.LBB0_708:
	s_and_b64 vcc, exec, s[10:11]
	s_cbranch_vccz .LBB0_699
	s_ashr_i32 s1, s0, 31
	s_lshl_b64 s[10:11], s[0:1], 11
	s_add_u32 s10, s5, s10
	v_mov_b32_e32 v7, v220
	s_addc_u32 s11, s6, s11
	s_lshl_b32 s1, s52, 18
	s_add_u32 s26, s7, s1
	v_ashrrev_i32_e32 v32, 2, v7
	v_ashrrev_i32_e32 v33, 31, v32
	s_addc_u32 s27, s8, 0
	v_lshlrev_b64 v[0:1], 11, v[32:33]
	v_lshlrev_b32_e32 v4, 4, v7
	v_lshl_add_u64 v[2:3], s[26:27], 0, v[0:1]
	v_lshl_add_u64 v[0:1], s[10:11], 0, v[0:1]
	v_and_b32_e32 v152, 48, v4
	v_lshl_add_u64 v[154:155], v[0:1], 0, v[152:153]
	v_add_co_u32_e32 v34, vcc, s9, v154
	v_lshl_add_u64 v[156:157], v[2:3], 0, v[152:153]
	s_nop 0
	v_addc_co_u32_e32 v35, vcc, 0, v155, vcc
	v_add_co_u32_e32 v36, vcc, s31, v154
	global_load_dwordx4 v[8:11], v[154:155], off
	s_nop 0
	v_addc_co_u32_e32 v37, vcc, 0, v155, vcc
	v_add_co_u32_e32 v38, vcc, s35, v154
	global_load_dwordx4 v[12:15], v[34:35], off
	s_nop 0
	v_addc_co_u32_e32 v39, vcc, 0, v155, vcc
	v_add_co_u32_e32 v40, vcc, s9, v156
	global_load_dwordx4 v[16:19], v[36:37], off
	s_nop 0
	v_addc_co_u32_e32 v41, vcc, 0, v157, vcc
	global_load_dwordx4 v[20:23], v[38:39], off
	global_load_dwordx4 v[24:27], v[156:157], off
	global_load_dwordx4 v[28:31], v[40:41], off
	global_load_dwordx4 v[112:115], v[154:155], off offset:64
	global_load_dwordx4 v[120:123], v[34:35], off offset:64
	global_load_dwordx4 v[124:127], v[36:37], off offset:64
	global_load_dwordx4 v[132:135], v[38:39], off offset:64
	global_load_dwordx4 v[116:119], v[156:157], off offset:64
	global_load_dwordx4 v[136:139], v[40:41], off offset:64
	v_lshrrev_b32_e32 v33, 4, v7
	v_lshrrev_b32_e32 v42, 2, v7
	v_sub_u32_e32 v45, 0, v33
	v_sub_u32_e32 v42, 0, v42
	v_and_b32_e32 v43, 0x3ffff8f, v7
	v_lshlrev_b32_e32 v44, 6, v7
	v_xor_b32_e32 v7, v7, v45
	v_xor_b32_e32 v33, v33, v42
	v_lshlrev_b32_e32 v7, 4, v7
	v_lshlrev_b32_e32 v33, 4, v33
	v_and_b32_e32 v46, 0x1000, v44
	v_and_b32_e32 v7, 48, v7
	v_and_b32_e32 v33, 48, v33
	v_mov_b32_e32 v0, 0
	v_and_b32_e32 v47, 0x3c0, v44
	v_and_b32_e32 v44, 0xffffe3c0, v44
	v_lshl_add_u32 v43, v43, 6, v167
	v_lshl_or_b32 v152, v32, 6, v7
	v_or_b32_e32 v7, v33, v46
	s_mov_b32 s10, 0
	s_mov_b32 s1, -2
	v_mov_b32_e32 v1, v0
	v_mov_b32_e32 v2, v0
	v_mov_b32_e32 v3, v0
	v_mov_b32_e32 v4, v0
	v_mov_b32_e32 v5, v0
	v_mov_b32_e32 v6, v0
	v_lshl_add_u64 v[158:159], v[154:155], 0, s[22:23]
	v_lshl_add_u64 v[160:161], v[154:155], 0, s[24:25]
	v_lshl_add_u64 v[162:163], v[154:155], 0, s[28:29]
	v_or3_b32 v168, v46, v47, v33
	v_add_u32_e32 v169, v33, v44
	v_add_u32_e32 v170, v33, v43
	v_lshl_add_u64 v[164:165], v[156:157], 0, s[22:23]
	v_add_u32_e32 v171, v7, v47
	v_mov_b32_e32 v7, v0
	v_mov_b32_e32 v32, v0
	v_mov_b32_e32 v33, v0
	v_mov_b32_e32 v34, v0
	v_mov_b32_e32 v35, v0
	v_mov_b32_e32 v36, v0
	v_mov_b32_e32 v37, v0
	v_mov_b32_e32 v38, v0
	v_mov_b32_e32 v39, v0
	v_mov_b32_e32 v40, v0
	v_mov_b32_e32 v41, v0
	v_mov_b32_e32 v42, v0
	v_mov_b32_e32 v43, v0
	v_mov_b32_e32 v44, v0
	v_mov_b32_e32 v45, v0
	v_mov_b32_e32 v46, v0
	v_mov_b32_e32 v47, v0
	s_waitcnt vmcnt(11)
	ds_write_b128 v152, v[8:11]
	s_waitcnt vmcnt(10)
	ds_write_b128 v152, v[12:15] offset:4096
	s_waitcnt vmcnt(9)
	ds_write_b128 v152, v[16:19] offset:8192
	s_waitcnt vmcnt(8)
	ds_write_b128 v152, v[20:23] offset:12288
	s_waitcnt vmcnt(7)
	ds_write_b128 v152, v[24:27] offset:32768
	s_waitcnt vmcnt(6)
	ds_write_b128 v152, v[28:31] offset:36864
	v_mov_b32_e32 v8, v0
	v_mov_b32_e32 v9, v0
	v_mov_b32_e32 v10, v0
	v_mov_b32_e32 v11, v0
	v_mov_b32_e32 v12, v0
	v_mov_b32_e32 v13, v0
	v_mov_b32_e32 v14, v0
	v_mov_b32_e32 v15, v0
	v_mov_b32_e32 v16, v0
	v_mov_b32_e32 v17, v0
	v_mov_b32_e32 v18, v0
	v_mov_b32_e32 v19, v0
	v_mov_b32_e32 v20, v0
	v_mov_b32_e32 v21, v0
	v_mov_b32_e32 v22, v0
	v_mov_b32_e32 v23, v0
	v_mov_b32_e32 v24, v0
	v_mov_b32_e32 v25, v0
	v_mov_b32_e32 v26, v0
	v_mov_b32_e32 v27, v0
	v_mov_b32_e32 v28, v0
	v_mov_b32_e32 v29, v0
	v_mov_b32_e32 v30, v0
	v_mov_b32_e32 v31, v0
	v_mov_b32_e32 v48, v0
	v_mov_b32_e32 v49, v0
	v_mov_b32_e32 v50, v0
	v_mov_b32_e32 v51, v0
	v_mov_b32_e32 v52, v0
	v_mov_b32_e32 v53, v0
	v_mov_b32_e32 v54, v0
	v_mov_b32_e32 v55, v0
	v_mov_b32_e32 v56, v0
	v_mov_b32_e32 v57, v0
	v_mov_b32_e32 v58, v0
	v_mov_b32_e32 v59, v0
	v_mov_b32_e32 v60, v0
	v_mov_b32_e32 v61, v0
	v_mov_b32_e32 v62, v0
	v_mov_b32_e32 v63, v0
	v_mov_b32_e32 v64, v0
	v_mov_b32_e32 v65, v0
	v_mov_b32_e32 v66, v0
	v_mov_b32_e32 v67, v0
	v_mov_b32_e32 v68, v0
	v_mov_b32_e32 v69, v0
	v_mov_b32_e32 v70, v0
	v_mov_b32_e32 v71, v0
	v_mov_b32_e32 v72, v0
	v_mov_b32_e32 v73, v0
	v_mov_b32_e32 v74, v0
	v_mov_b32_e32 v75, v0
	v_mov_b32_e32 v76, v0
	v_mov_b32_e32 v77, v0
	v_mov_b32_e32 v78, v0
	v_mov_b32_e32 v79, v0
	v_mov_b32_e32 v80, v0
	v_mov_b32_e32 v81, v0
	v_mov_b32_e32 v82, v0
	v_mov_b32_e32 v83, v0
	v_mov_b32_e32 v84, v0
	v_mov_b32_e32 v85, v0
	v_mov_b32_e32 v86, v0
	v_mov_b32_e32 v87, v0
	v_mov_b32_e32 v88, v0
	v_mov_b32_e32 v89, v0
	v_mov_b32_e32 v90, v0
	v_mov_b32_e32 v91, v0
	v_mov_b32_e32 v92, v0
	v_mov_b32_e32 v93, v0
	v_mov_b32_e32 v94, v0
	v_mov_b32_e32 v95, v0
	v_mov_b32_e32 v96, v0
	v_mov_b32_e32 v97, v0
	v_mov_b32_e32 v98, v0
	v_mov_b32_e32 v99, v0
	v_mov_b32_e32 v100, v0
	v_mov_b32_e32 v101, v0
	v_mov_b32_e32 v102, v0
	v_mov_b32_e32 v103, v0
	v_mov_b32_e32 v104, v0
	v_mov_b32_e32 v105, v0
	v_mov_b32_e32 v106, v0
	v_mov_b32_e32 v107, v0
	v_mov_b32_e32 v108, v0
	v_mov_b32_e32 v109, v0
	v_mov_b32_e32 v110, v0
	v_mov_b32_e32 v111, v0
	v_mov_b32_e32 v128, v0
	v_mov_b32_e32 v129, v0
	v_mov_b32_e32 v130, v0
	v_mov_b32_e32 v131, v0
	v_mov_b32_e32 v140, v0
	v_mov_b32_e32 v141, v0
	v_mov_b32_e32 v142, v0
	v_mov_b32_e32 v143, v0
	v_mov_b32_e32 v144, v0
	v_mov_b32_e32 v145, v0
	v_mov_b32_e32 v146, v0
	v_mov_b32_e32 v147, v0
	v_mov_b32_e32 v148, v0
	v_mov_b32_e32 v149, v0
	v_mov_b32_e32 v150, v0
	v_mov_b32_e32 v151, v0
	s_waitcnt lgkmcnt(0)
	s_add_i32 s11, s10, 64
	s_min_u32 s13, s11, 0x3e0
	s_lshl_b32 s16, s13, 1
	v_lshl_add_u64 v[172:173], v[154:155], 0, s[16:17]
	v_lshl_add_u64 v[176:177], v[158:159], 0, s[16:17]
	v_lshl_add_u64 v[180:181], v[160:161], 0, s[16:17]
	v_lshl_add_u64 v[184:185], v[162:163], 0, s[16:17]
	v_lshl_add_u64 v[188:189], v[156:157], 0, s[16:17]
	v_lshl_add_u64 v[192:193], v[164:165], 0, s[16:17]

.LBB0_710:
	global_load_dwordx4 v[172:175], v[172:173], off
	ds_read_b128 v[196:199], v171 offset:32768
	global_load_dwordx4 v[176:179], v[176:177], off
	ds_read_b128 v[200:203], v171 offset:33792
	global_load_dwordx4 v[180:183], v[180:181], off
	ds_read_b128 v[204:207], v171 offset:34816
	global_load_dwordx4 v[184:187], v[184:185], off
	ds_read_b128 v[208:211], v171 offset:35840
	global_load_dwordx4 v[188:191], v[188:189], off
	ds_read_b128 v[212:215], v169
	global_load_dwordx4 v[192:195], v[192:193], off
	ds_read_b128 v[216:219], v169 offset:1024
	ds_read_b128 v[222:225], v169 offset:2048
	ds_read_b128 v[226:229], v169 offset:3072
	ds_read_b128 v[230:233], v169 offset:4096
	ds_read_b128 v[234:237], v169 offset:5120
	ds_read_b128 v[238:241], v169 offset:6144
	ds_read_b128 v[242:245], v169 offset:7168
	s_setprio 1
	s_waitcnt lgkmcnt(7)
	v_mfma_f32_16x16x32_bf16 v[148:151], v[212:215], v[196:199], v[148:151]
	v_mfma_f32_16x16x32_bf16 v[144:147], v[212:215], v[200:203], v[144:147]
	v_mfma_f32_16x16x32_bf16 v[140:143], v[212:215], v[204:207], v[140:143]
	v_mfma_f32_16x16x32_bf16 v[128:131], v[212:215], v[208:211], v[128:131]
	s_waitcnt vmcnt(11)
	ds_write_b128 v152, v[112:115] offset:16384
	s_waitcnt lgkmcnt(7)
	v_mfma_f32_16x16x32_bf16 v[108:111], v[216:219], v[196:199], v[108:111]
	v_mfma_f32_16x16x32_bf16 v[104:107], v[216:219], v[200:203], v[104:107]
	v_mfma_f32_16x16x32_bf16 v[100:103], v[216:219], v[204:207], v[100:103]
	v_mfma_f32_16x16x32_bf16 v[96:99], v[216:219], v[208:211], v[96:99]
	s_waitcnt vmcnt(9)
	ds_write_b128 v152, v[120:123] offset:20480
	s_waitcnt lgkmcnt(7)
	v_mfma_f32_16x16x32_bf16 v[92:95], v[222:225], v[196:199], v[92:95]
	v_mfma_f32_16x16x32_bf16 v[88:91], v[222:225], v[200:203], v[88:91]
	v_mfma_f32_16x16x32_bf16 v[84:87], v[222:225], v[204:207], v[84:87]
	v_mfma_f32_16x16x32_bf16 v[80:83], v[222:225], v[208:211], v[80:83]
	s_waitcnt vmcnt(8)
	ds_write_b128 v152, v[124:127] offset:24576
	s_waitcnt lgkmcnt(7)
	v_mfma_f32_16x16x32_bf16 v[76:79], v[226:229], v[196:199], v[76:79]
	v_mfma_f32_16x16x32_bf16 v[72:75], v[226:229], v[200:203], v[72:75]
	v_mfma_f32_16x16x32_bf16 v[68:71], v[226:229], v[204:207], v[68:71]
	v_mfma_f32_16x16x32_bf16 v[64:67], v[226:229], v[208:211], v[64:67]
	s_waitcnt vmcnt(7)
	ds_write_b128 v152, v[132:135] offset:28672
	s_waitcnt lgkmcnt(7)
	v_mfma_f32_16x16x32_bf16 v[60:63], v[230:233], v[196:199], v[60:63]
	v_mfma_f32_16x16x32_bf16 v[56:59], v[230:233], v[200:203], v[56:59]
	v_mfma_f32_16x16x32_bf16 v[52:55], v[230:233], v[204:207], v[52:55]
	v_mfma_f32_16x16x32_bf16 v[48:51], v[230:233], v[208:211], v[48:51]
	s_waitcnt vmcnt(7)
	ds_write_b128 v152, v[116:119] offset:40960
	s_waitcnt lgkmcnt(7)
	v_mfma_f32_16x16x32_bf16 v[44:47], v[234:237], v[196:199], v[44:47]
	v_mfma_f32_16x16x32_bf16 v[40:43], v[234:237], v[200:203], v[40:43]
	v_mfma_f32_16x16x32_bf16 v[36:39], v[234:237], v[204:207], v[36:39]
	v_mfma_f32_16x16x32_bf16 v[32:35], v[234:237], v[208:211], v[32:35]
	s_waitcnt vmcnt(6)
	ds_write_b128 v152, v[136:139] offset:45056
	s_waitcnt lgkmcnt(7)
	v_mfma_f32_16x16x32_bf16 v[28:31], v[238:241], v[196:199], v[28:31]
	v_mfma_f32_16x16x32_bf16 v[24:27], v[238:241], v[200:203], v[24:27]
	v_mfma_f32_16x16x32_bf16 v[20:23], v[238:241], v[204:207], v[20:23]
	v_mfma_f32_16x16x32_bf16 v[16:19], v[238:241], v[208:211], v[16:19]
	s_waitcnt lgkmcnt(6)
	v_mfma_f32_16x16x32_bf16 v[12:15], v[242:245], v[196:199], v[12:15]
	v_mfma_f32_16x16x32_bf16 v[8:11], v[242:245], v[200:203], v[8:11]
	v_mfma_f32_16x16x32_bf16 v[4:7], v[242:245], v[204:207], v[4:7]
	v_mfma_f32_16x16x32_bf16 v[0:3], v[242:245], v[208:211], v[0:3]
	s_setprio 0
	s_min_u32 s10, s10, 0x380
	s_lshl_b32 s16, s10, 1
	s_mov_b32 s27, s17
	s_add_i32 s26, s16, 0xc0
	v_lshl_add_u64 v[112:113], v[154:155], 0, s[16:17]
	v_lshl_add_u64 v[116:117], v[156:157], 0, s[16:17]
	v_lshl_add_u64 v[120:121], v[158:159], 0, s[26:27]
	v_lshl_add_u64 v[124:125], v[160:161], 0, s[26:27]
	v_lshl_add_u64 v[132:133], v[162:163], 0, s[26:27]
	v_lshl_add_u64 v[136:137], v[164:165], 0, s[26:27]
	s_waitcnt lgkmcnt(0)
	s_barrier
	global_load_dwordx4 v[112:115], v[112:113], off offset:192
	ds_read_b128 v[196:199], v168 offset:40960
	global_load_dwordx4 v[116:119], v[116:117], off offset:192
	ds_read_b128 v[200:203], v168 offset:41984
	global_load_dwordx4 v[120:123], v[120:121], off
	ds_read_b128 v[204:207], v168 offset:43008
	global_load_dwordx4 v[124:127], v[124:125], off
	ds_read_b128 v[208:211], v168 offset:44032
	global_load_dwordx4 v[132:135], v[132:133], off
	ds_read_b128 v[212:215], v170
	global_load_dwordx4 v[136:139], v[136:137], off
	ds_read_b128 v[216:219], v170 offset:1024
	ds_read_b128 v[222:225], v170 offset:2048
	ds_read_b128 v[226:229], v170 offset:3072
	ds_read_b128 v[230:233], v170 offset:4096
	ds_read_b128 v[234:237], v170 offset:5120
	ds_read_b128 v[238:241], v170 offset:6144
	ds_read_b128 v[242:245], v170 offset:7168
	s_setprio 1
	s_waitcnt lgkmcnt(7)
	v_mfma_f32_16x16x32_bf16 v[148:151], v[212:215], v[196:199], v[148:151]
	v_mfma_f32_16x16x32_bf16 v[144:147], v[212:215], v[200:203], v[144:147]
	v_mfma_f32_16x16x32_bf16 v[140:143], v[212:215], v[204:207], v[140:143]
	v_mfma_f32_16x16x32_bf16 v[128:131], v[212:215], v[208:211], v[128:131]
	s_waitcnt vmcnt(11)
	ds_write_b128 v152, v[172:175]
	s_waitcnt lgkmcnt(7)
	v_mfma_f32_16x16x32_bf16 v[108:111], v[216:219], v[196:199], v[108:111]
	v_mfma_f32_16x16x32_bf16 v[104:107], v[216:219], v[200:203], v[104:107]
	v_mfma_f32_16x16x32_bf16 v[100:103], v[216:219], v[204:207], v[100:103]
	v_mfma_f32_16x16x32_bf16 v[96:99], v[216:219], v[208:211], v[96:99]
	s_waitcnt vmcnt(10)
	ds_write_b128 v152, v[176:179] offset:4096
	s_waitcnt lgkmcnt(7)
	v_mfma_f32_16x16x32_bf16 v[92:95], v[222:225], v[196:199], v[92:95]
	v_mfma_f32_16x16x32_bf16 v[88:91], v[222:225], v[200:203], v[88:91]
	v_mfma_f32_16x16x32_bf16 v[84:87], v[222:225], v[204:207], v[84:87]
	v_mfma_f32_16x16x32_bf16 v[80:83], v[222:225], v[208:211], v[80:83]
	s_waitcnt vmcnt(9)
	ds_write_b128 v152, v[180:183] offset:8192
	s_waitcnt lgkmcnt(7)
	v_mfma_f32_16x16x32_bf16 v[76:79], v[226:229], v[196:199], v[76:79]
	v_mfma_f32_16x16x32_bf16 v[72:75], v[226:229], v[200:203], v[72:75]
	v_mfma_f32_16x16x32_bf16 v[68:71], v[226:229], v[204:207], v[68:71]
	v_mfma_f32_16x16x32_bf16 v[64:67], v[226:229], v[208:211], v[64:67]
	s_waitcnt vmcnt(8)
	ds_write_b128 v152, v[184:187] offset:12288
	s_waitcnt lgkmcnt(7)
	v_mfma_f32_16x16x32_bf16 v[60:63], v[230:233], v[196:199], v[60:63]
	v_mfma_f32_16x16x32_bf16 v[56:59], v[230:233], v[200:203], v[56:59]
	v_mfma_f32_16x16x32_bf16 v[52:55], v[230:233], v[204:207], v[52:55]
	v_mfma_f32_16x16x32_bf16 v[48:51], v[230:233], v[208:211], v[48:51]
	s_waitcnt vmcnt(7)
	ds_write_b128 v152, v[188:191] offset:32768
	s_waitcnt lgkmcnt(7)
	v_mfma_f32_16x16x32_bf16 v[44:47], v[234:237], v[196:199], v[44:47]
	v_mfma_f32_16x16x32_bf16 v[40:43], v[234:237], v[200:203], v[40:43]
	v_mfma_f32_16x16x32_bf16 v[36:39], v[234:237], v[204:207], v[36:39]
	v_mfma_f32_16x16x32_bf16 v[32:35], v[234:237], v[208:211], v[32:35]
	s_waitcnt vmcnt(6)
	ds_write_b128 v152, v[192:195] offset:36864
	s_waitcnt lgkmcnt(7)
	v_mfma_f32_16x16x32_bf16 v[28:31], v[238:241], v[196:199], v[28:31]
	v_mfma_f32_16x16x32_bf16 v[24:27], v[238:241], v[200:203], v[24:27]
	v_mfma_f32_16x16x32_bf16 v[20:23], v[238:241], v[204:207], v[20:23]
	v_mfma_f32_16x16x32_bf16 v[16:19], v[238:241], v[208:211], v[16:19]
	s_waitcnt lgkmcnt(6)
	v_mfma_f32_16x16x32_bf16 v[12:15], v[242:245], v[196:199], v[12:15]
	v_mfma_f32_16x16x32_bf16 v[8:11], v[242:245], v[200:203], v[8:11]
	v_mfma_f32_16x16x32_bf16 v[4:7], v[242:245], v[204:207], v[4:7]
	v_mfma_f32_16x16x32_bf16 v[0:3], v[242:245], v[208:211], v[0:3]
	s_setprio 0
	s_add_i32 s1, s1, 2
	s_mov_b32 s10, s11
	s_add_i32 s11, s10, 64
	s_min_u32 s13, s11, 0x3e0
	s_lshl_b32 s16, s13, 1
	v_lshl_add_u64 v[172:173], v[154:155], 0, s[16:17]
	v_lshl_add_u64 v[176:177], v[158:159], 0, s[16:17]
	v_lshl_add_u64 v[180:181], v[160:161], 0, s[16:17]
	v_lshl_add_u64 v[184:185], v[162:163], 0, s[16:17]
	v_lshl_add_u64 v[188:189], v[156:157], 0, s[16:17]
	v_lshl_add_u64 v[192:193], v[164:165], 0, s[16:17]
	s_cmp_lt_u32 s1, 30
	s_waitcnt lgkmcnt(0)
	s_cbranch_scc1 .Lrot_2
	s_barrier
	s_waitcnt vmcnt(5)
	v_mov_b32_e32 v114, v220
	v_mov_b32_e32 v115, v153
	v_and_b32_e32 v112, 0xffffff80, v114
	s_waitcnt vmcnt(4)
	v_add_u32_e32 v116, s0, v112
	v_lshrrev_b32_e32 v112, 2, v114
	v_and_b32_e32 v118, 12, v112
	s_waitcnt vmcnt(3)
	v_or_b32_e32 v120, v118, v116
	v_ashrrev_i32_e32 v121, 31, v120
	v_lshl_add_u64 v[112:113], v[120:121], 2, s[14:15]
	global_load_dwordx4 v[132:135], v[112:113], off
	v_ashrrev_i32_e32 v122, 14, v116
	v_ashrrev_i32_e32 v123, 31, v122
	v_lshlrev_b64 v[122:123], 10, v[122:123]
	v_mov_b64_e32 v[112:113], s[34:35]
	s_waitcnt vmcnt(3)
	v_lshrrev_b32_e32 v126, 6, v116
	v_or_b32_e32 v124, 16, v120
	v_lshl_or_b32 v121, s12, 8, v122
	v_ashrrev_i32_e32 v125, 31, v124
	v_and_or_b32 v122, v126, s49, v121
	s_waitcnt vmcnt(1)
	v_lshl_add_u64 v[136:137], v[124:125], 2, s[14:15]
	global_load_dwordx4 v[246:249], v[136:137], off
	v_lshlrev_b64 v[124:125], 14, v[122:123]
	v_lshlrev_b32_e32 v114, 7, v114
	v_lshlrev_b32_e32 v152, 1, v118
	v_lshl_add_u64 v[124:125], s[38:39], 0, v[124:125]
	v_and_b32_e32 v114, 0x2780, v114
	v_lshl_add_u64 v[126:127], v[124:125], 0, v[152:153]
	v_mov_b32_e32 v117, v153
	v_mov_b32_e32 v119, v153
	v_or_b32_e32 v116, 0x1000, v114
	v_or_b32_e32 v118, 0x1800, v114
	v_lshl_add_u64 v[124:125], v[126:127], 0, v[114:115]
	v_lshl_add_u64 v[138:139], v[126:127], 0, v[116:117]
	v_lshl_add_u64 v[154:155], v[126:127], 0, v[118:119]
	s_waitcnt vmcnt(1)
	v_pk_fma_f32 v[132:133], v[132:133], s[30:31], v[112:113] op_sel_hi:[1,0,0]
	v_pk_fma_f32 v[134:135], v[134:135], s[30:31], v[112:113] op_sel_hi:[1,0,0]
	v_mul_f32_e32 v122, 0x4b800000, v132
	v_mul_f32_e32 v156, 0x4b800000, v133
	v_mul_f32_e32 v157, 0x4b800000, v134
	v_mul_f32_e32 v158, 0x4b800000, v135
	v_cmp_gt_f32_e32 vcc, s40, v132
	v_cmp_gt_f32_e64 s[0:1], s40, v133
	v_cmp_gt_f32_e64 s[10:11], s40, v134
	v_cmp_gt_f32_e64 s[12:13], s40, v135
	v_cndmask_b32_e32 v122, v132, v122, vcc
	v_cndmask_b32_e64 v132, v133, v156, s[0:1]
	v_cndmask_b32_e64 v133, v134, v157, s[10:11]
	v_cndmask_b32_e64 v134, v135, v158, s[12:13]
	v_rsq_f32_e32 v122, v122
	v_rsq_f32_e32 v132, v132
	v_rsq_f32_e32 v133, v133
	v_rsq_f32_e32 v134, v134
	v_mul_f32_e32 v135, 0x45800000, v122
	v_mul_f32_e32 v156, 0x45800000, v132
	v_mul_f32_e32 v157, 0x45800000, v133
	v_mul_f32_e32 v158, 0x45800000, v134
	v_cndmask_b32_e32 v122, v122, v135, vcc
	v_cndmask_b32_e64 v132, v132, v156, s[0:1]
	v_cndmask_b32_e64 v133, v133, v157, s[10:11]
	v_cndmask_b32_e64 v134, v134, v158, s[12:13]
	v_mul_f32_e32 v135, v148, v122
	v_mul_f32_e32 v148, v149, v132
	v_mul_f32_e32 v149, v150, v133
	v_mul_f32_e32 v150, v151, v134
	v_mul_f32_e32 v144, v144, v122
	v_mul_f32_e32 v140, v140, v122
	v_mul_f32_e32 v122, v128, v122
	v_mul_f32_e32 v151, v129, v132
	v_cvt_pk_bf16_f32 v128, v135, v148
	v_cvt_pk_bf16_f32 v129, v149, v150
	v_mul_f32_e32 v145, v145, v132
	v_mul_f32_e32 v146, v146, v133
	v_mul_f32_e32 v147, v147, v134
	v_mul_f32_e32 v141, v141, v132
	v_mul_f32_e32 v142, v142, v133
	v_mul_f32_e32 v143, v143, v134
	v_mul_f32_e32 v156, v130, v133
	v_mul_f32_e32 v157, v131, v134
	v_cvt_pk_bf16_f32 v130, v144, v145
	v_cvt_pk_bf16_f32 v131, v146, v147
	v_cvt_pk_bf16_f32 v132, v140, v141
	v_cvt_pk_bf16_f32 v133, v142, v143
	v_cvt_pk_bf16_f32 v134, v122, v151
	v_cvt_pk_bf16_f32 v135, v156, v157
	global_store_dwordx2 v[124:125], v[128:129], off
	global_store_dwordx2 v[124:125], v[130:131], off offset:2048
	global_store_dwordx2 v[138:139], v[132:133], off
	global_store_dwordx2 v[154:155], v[134:135], off
	v_or_b32_e32 v132, 32, v120
	v_ashrrev_i32_e32 v133, 31, v132
	v_lshl_add_u64 v[134:135], v[126:127], 0, 32
	v_lshl_add_u64 v[132:133], v[132:133], 2, s[14:15]
	global_load_dwordx4 v[250:253], v[132:133], off
	v_lshl_add_u64 v[136:137], v[134:135], 0, v[116:117]
	v_lshl_add_u64 v[134:135], v[134:135], 0, v[118:119]
	s_waitcnt vmcnt(5)
	v_mov_b32_e32 v128, v246
	v_mov_b32_e32 v129, v247
	v_mov_b32_e32 v130, v248
	v_mov_b32_e32 v131, v249
	v_pk_fma_f32 v[128:129], v[128:129], s[30:31], v[112:113] op_sel_hi:[1,0,0]
	v_pk_fma_f32 v[130:131], v[130:131], s[30:31], v[112:113] op_sel_hi:[1,0,0]
	v_mul_f32_e32 v122, 0x4b800000, v128
	v_mul_f32_e32 v138, 0x4b800000, v129
	v_mul_f32_e32 v139, 0x4b800000, v130
	v_mul_f32_e32 v140, 0x4b800000, v131
	v_cmp_gt_f32_e32 vcc, s40, v128
	v_cmp_gt_f32_e64 s[0:1], s40, v129
	v_cmp_gt_f32_e64 s[10:11], s40, v130
	v_cmp_gt_f32_e64 s[12:13], s40, v131
	v_cndmask_b32_e32 v122, v128, v122, vcc
	v_cndmask_b32_e64 v128, v129, v138, s[0:1]
	v_cndmask_b32_e64 v129, v130, v139, s[10:11]
	v_cndmask_b32_e64 v130, v131, v140, s[12:13]
	v_rsq_f32_e32 v122, v122
	v_rsq_f32_e32 v128, v128
	v_rsq_f32_e32 v129, v129
	v_rsq_f32_e32 v130, v130
	v_mul_f32_e32 v131, 0x45800000, v122
	v_mul_f32_e32 v138, 0x45800000, v128
	v_mul_f32_e32 v139, 0x45800000, v129
	v_mul_f32_e32 v140, 0x45800000, v130
	v_cndmask_b32_e32 v122, v122, v131, vcc
	v_cndmask_b32_e64 v128, v128, v138, s[0:1]
	v_cndmask_b32_e64 v129, v129, v139, s[10:11]
	v_cndmask_b32_e64 v130, v130, v140, s[12:13]
	v_mul_f32_e32 v108, v108, v122
	v_mul_f32_e32 v109, v109, v128
	v_mul_f32_e32 v110, v110, v129
	v_mul_f32_e32 v111, v111, v130
	v_mul_f32_e32 v104, v104, v122
	v_mul_f32_e32 v105, v105, v128
	v_mul_f32_e32 v100, v100, v122
	v_mul_f32_e32 v101, v101, v128
	v_mul_f32_e32 v102, v102, v129
	v_mul_f32_e32 v103, v103, v130
	v_mul_f32_e32 v122, v96, v122
	v_mul_f32_e32 v128, v97, v128
	v_cvt_pk_bf16_f32 v96, v108, v109
	v_cvt_pk_bf16_f32 v97, v110, v111
	v_mul_f32_e32 v106, v106, v129
	v_mul_f32_e32 v107, v107, v130
	v_mul_f32_e32 v129, v98, v129
	v_mul_f32_e32 v130, v99, v130
	v_cvt_pk_bf16_f32 v98, v104, v105
	v_cvt_pk_bf16_f32 v99, v106, v107
	v_cvt_pk_bf16_f32 v100, v100, v101
	v_cvt_pk_bf16_f32 v101, v102, v103
	v_cvt_pk_bf16_f32 v102, v122, v128
	v_cvt_pk_bf16_f32 v103, v129, v130
	global_store_dwordx2 v[124:125], v[96:97], off offset:32
	global_store_dwordx2 v[124:125], v[98:99], off offset:2080
	global_store_dwordx2 v[136:137], v[100:101], off
	global_store_dwordx2 v[134:135], v[102:103], off
	v_or_b32_e32 v100, 48, v120
	v_ashrrev_i32_e32 v101, 31, v100
	v_lshl_add_u64 v[102:103], v[126:127], 0, 64
	v_lshl_add_u64 v[100:101], v[100:101], 2, s[14:15]
	global_load_dwordx4 v[246:249], v[100:101], off
	v_lshl_add_u64 v[104:105], v[102:103], 0, v[116:117]
	v_lshl_add_u64 v[102:103], v[102:103], 0, v[118:119]
	s_waitcnt vmcnt(5)
	v_mov_b32_e32 v96, v250
	v_mov_b32_e32 v97, v251
	v_mov_b32_e32 v98, v252
	v_mov_b32_e32 v99, v253
	v_pk_fma_f32 v[96:97], v[96:97], s[30:31], v[112:113] op_sel_hi:[1,0,0]
	v_pk_fma_f32 v[98:99], v[98:99], s[30:31], v[112:113] op_sel_hi:[1,0,0]
	v_mul_f32_e32 v106, 0x4b800000, v96
	v_mul_f32_e32 v107, 0x4b800000, v97
	v_mul_f32_e32 v108, 0x4b800000, v98
	v_mul_f32_e32 v109, 0x4b800000, v99
	v_cmp_gt_f32_e32 vcc, s40, v96
	v_cmp_gt_f32_e64 s[0:1], s40, v97
	v_cmp_gt_f32_e64 s[10:11], s40, v98
	v_cmp_gt_f32_e64 s[12:13], s40, v99
	v_cndmask_b32_e32 v96, v96, v106, vcc
	v_cndmask_b32_e64 v97, v97, v107, s[0:1]
	v_cndmask_b32_e64 v98, v98, v108, s[10:11]
	v_cndmask_b32_e64 v99, v99, v109, s[12:13]
	v_rsq_f32_e32 v96, v96
	v_rsq_f32_e32 v97, v97
	v_rsq_f32_e32 v98, v98
	v_rsq_f32_e32 v99, v99
	v_mul_f32_e32 v106, 0x45800000, v96
	v_mul_f32_e32 v107, 0x45800000, v97
	v_mul_f32_e32 v108, 0x45800000, v98
	v_mul_f32_e32 v109, 0x45800000, v99
	v_cndmask_b32_e32 v96, v96, v106, vcc
	v_cndmask_b32_e64 v97, v97, v107, s[0:1]
	v_cndmask_b32_e64 v98, v98, v108, s[10:11]
	v_cndmask_b32_e64 v99, v99, v109, s[12:13]
	v_mul_f32_e32 v92, v92, v96
	v_mul_f32_e32 v93, v93, v97
	v_mul_f32_e32 v94, v94, v98
	v_mul_f32_e32 v95, v95, v99
	v_mul_f32_e32 v88, v88, v96
	v_mul_f32_e32 v89, v89, v97
	v_mul_f32_e32 v84, v84, v96
	v_mul_f32_e32 v85, v85, v97
	v_mul_f32_e32 v86, v86, v98
	v_mul_f32_e32 v87, v87, v99
	v_mul_f32_e32 v96, v80, v96
	v_mul_f32_e32 v97, v81, v97
	v_cvt_pk_bf16_f32 v80, v92, v93
	v_cvt_pk_bf16_f32 v81, v94, v95
	v_mul_f32_e32 v90, v90, v98
	v_mul_f32_e32 v91, v91, v99
	v_mul_f32_e32 v98, v82, v98
	v_mul_f32_e32 v99, v83, v99
	v_cvt_pk_bf16_f32 v82, v88, v89
	v_cvt_pk_bf16_f32 v83, v90, v91
	v_cvt_pk_bf16_f32 v84, v84, v85
	v_cvt_pk_bf16_f32 v85, v86, v87
	v_cvt_pk_bf16_f32 v86, v96, v97
	v_cvt_pk_bf16_f32 v87, v98, v99
	global_store_dwordx2 v[124:125], v[80:81], off offset:64
	global_store_dwordx2 v[124:125], v[82:83], off offset:2112
	global_store_dwordx2 v[104:105], v[84:85], off
	global_store_dwordx2 v[102:103], v[86:87], off
	v_or_b32_e32 v84, 64, v120
	v_ashrrev_i32_e32 v85, 31, v84
	v_lshl_add_u64 v[86:87], v[84:85], 2, s[14:15]
	global_load_dwordx4 v[250:253], v[86:87], off
	v_lshl_add_u64 v[88:89], v[126:127], 0, s[36:37]
	v_lshl_add_u64 v[90:91], v[88:89], 0, v[116:117]
	v_lshl_add_u64 v[88:89], v[88:89], 0, v[118:119]
	s_waitcnt vmcnt(5)
	v_mov_b32_e32 v80, v246
	v_mov_b32_e32 v81, v247
	v_mov_b32_e32 v82, v248
	v_mov_b32_e32 v83, v249
	v_pk_fma_f32 v[80:81], v[80:81], s[30:31], v[112:113] op_sel_hi:[1,0,0]
	v_pk_fma_f32 v[82:83], v[82:83], s[30:31], v[112:113] op_sel_hi:[1,0,0]
	v_mul_f32_e32 v85, 0x4b800000, v80
	v_mul_f32_e32 v92, 0x4b800000, v81
	v_mul_f32_e32 v93, 0x4b800000, v82
	v_mul_f32_e32 v94, 0x4b800000, v83
	v_cmp_gt_f32_e32 vcc, s40, v80
	v_cmp_gt_f32_e64 s[0:1], s40, v81
	v_cmp_gt_f32_e64 s[10:11], s40, v82
	v_cmp_gt_f32_e64 s[12:13], s40, v83
	v_cndmask_b32_e32 v80, v80, v85, vcc
	v_cndmask_b32_e64 v81, v81, v92, s[0:1]
	v_cndmask_b32_e64 v82, v82, v93, s[10:11]
	v_cndmask_b32_e64 v83, v83, v94, s[12:13]
	v_rsq_f32_e32 v80, v80
	v_rsq_f32_e32 v81, v81
	v_rsq_f32_e32 v82, v82
	v_rsq_f32_e32 v83, v83
	v_mul_f32_e32 v85, 0x45800000, v80
	v_mul_f32_e32 v92, 0x45800000, v81
	v_mul_f32_e32 v93, 0x45800000, v82
	v_mul_f32_e32 v94, 0x45800000, v83
	v_cndmask_b32_e32 v80, v80, v85, vcc
	v_cndmask_b32_e64 v81, v81, v92, s[0:1]
	v_cndmask_b32_e64 v82, v82, v93, s[10:11]
	v_cndmask_b32_e64 v83, v83, v94, s[12:13]
	v_mul_f32_e32 v76, v76, v80
	v_mul_f32_e32 v77, v77, v81
	v_mul_f32_e32 v78, v78, v82
	v_mul_f32_e32 v79, v79, v83
	v_mul_f32_e32 v72, v72, v80
	v_mul_f32_e32 v73, v73, v81
	v_mul_f32_e32 v68, v68, v80
	v_mul_f32_e32 v69, v69, v81
	v_mul_f32_e32 v70, v70, v82
	v_mul_f32_e32 v71, v71, v83
	v_mul_f32_e32 v80, v64, v80
	v_mul_f32_e32 v81, v65, v81
	v_cvt_pk_bf16_f32 v64, v76, v77
	v_cvt_pk_bf16_f32 v65, v78, v79
	v_mul_f32_e32 v74, v74, v82
	v_mul_f32_e32 v75, v75, v83
	v_mul_f32_e32 v82, v66, v82
	v_mul_f32_e32 v83, v67, v83
	v_cvt_pk_bf16_f32 v66, v72, v73
	v_cvt_pk_bf16_f32 v67, v74, v75
	v_cvt_pk_bf16_f32 v68, v68, v69
	v_cvt_pk_bf16_f32 v69, v70, v71
	v_cvt_pk_bf16_f32 v70, v80, v81
	v_cvt_pk_bf16_f32 v71, v82, v83
	global_store_dwordx2 v[124:125], v[64:65], off offset:96
	global_store_dwordx2 v[124:125], v[66:67], off offset:2144
	global_store_dwordx2 v[90:91], v[68:69], off
	global_store_dwordx2 v[88:89], v[70:71], off
	v_or_b32_e32 v68, 0x50, v120
	v_ashrrev_i32_e32 v69, 31, v68
	v_lshl_add_u64 v[70:71], v[68:69], 2, s[14:15]
	global_load_dwordx4 v[246:249], v[70:71], off
	v_lshrrev_b32_e32 v72, 6, v84
	v_and_or_b32 v122, v72, s50, v121
	v_lshlrev_b64 v[72:73], 14, v[122:123]
	v_lshl_add_u64 v[72:73], s[38:39], 0, v[72:73]
	v_lshl_add_u64 v[72:73], v[72:73], 0, v[152:153]
	v_lshl_add_u64 v[74:75], v[72:73], 0, v[114:115]
	v_lshl_add_u64 v[76:77], v[72:73], 0, v[116:117]
	v_lshl_add_u64 v[72:73], v[72:73], 0, v[118:119]
	s_waitcnt vmcnt(5)
	v_mov_b32_e32 v64, v250
	v_mov_b32_e32 v65, v251
	v_mov_b32_e32 v66, v252
	v_mov_b32_e32 v67, v253
	v_pk_fma_f32 v[64:65], v[64:65], s[30:31], v[112:113] op_sel_hi:[1,0,0]
	v_pk_fma_f32 v[66:67], v[66:67], s[30:31], v[112:113] op_sel_hi:[1,0,0]
	v_mul_f32_e32 v69, 0x4b800000, v64
	v_mul_f32_e32 v78, 0x4b800000, v65
	v_mul_f32_e32 v79, 0x4b800000, v66
	v_mul_f32_e32 v80, 0x4b800000, v67
	v_cmp_gt_f32_e32 vcc, s40, v64
	v_cmp_gt_f32_e64 s[0:1], s40, v65
	v_cmp_gt_f32_e64 s[10:11], s40, v66
	v_cmp_gt_f32_e64 s[12:13], s40, v67
	v_cndmask_b32_e32 v64, v64, v69, vcc
	v_cndmask_b32_e64 v65, v65, v78, s[0:1]
	v_cndmask_b32_e64 v66, v66, v79, s[10:11]
	v_cndmask_b32_e64 v67, v67, v80, s[12:13]
	v_rsq_f32_e32 v64, v64
	v_rsq_f32_e32 v65, v65
	v_rsq_f32_e32 v66, v66
	v_rsq_f32_e32 v67, v67
	v_mul_f32_e32 v69, 0x45800000, v64
	v_mul_f32_e32 v78, 0x45800000, v65
	v_mul_f32_e32 v79, 0x45800000, v66
	v_mul_f32_e32 v80, 0x45800000, v67
	v_cndmask_b32_e32 v64, v64, v69, vcc
	v_cndmask_b32_e64 v65, v65, v78, s[0:1]
	v_cndmask_b32_e64 v66, v66, v79, s[10:11]
	v_cndmask_b32_e64 v67, v67, v80, s[12:13]
	v_mul_f32_e32 v60, v60, v64
	v_mul_f32_e32 v61, v61, v65
	v_mul_f32_e32 v62, v62, v66
	v_mul_f32_e32 v63, v63, v67
	v_mul_f32_e32 v56, v56, v64
	v_mul_f32_e32 v57, v57, v65
	v_mul_f32_e32 v52, v52, v64
	v_mul_f32_e32 v53, v53, v65
	v_mul_f32_e32 v54, v54, v66
	v_mul_f32_e32 v55, v55, v67
	v_mul_f32_e32 v64, v48, v64
	v_mul_f32_e32 v65, v49, v65
	v_cvt_pk_bf16_f32 v48, v60, v61
	v_cvt_pk_bf16_f32 v49, v62, v63
	v_mul_f32_e32 v58, v58, v66
	v_mul_f32_e32 v59, v59, v67
	v_mul_f32_e32 v66, v50, v66
	v_mul_f32_e32 v67, v51, v67
	v_cvt_pk_bf16_f32 v50, v56, v57
	v_cvt_pk_bf16_f32 v51, v58, v59
	v_cvt_pk_bf16_f32 v52, v52, v53
	v_cvt_pk_bf16_f32 v53, v54, v55
	v_cvt_pk_bf16_f32 v54, v64, v65
	v_cvt_pk_bf16_f32 v55, v66, v67
	global_store_dwordx2 v[74:75], v[48:49], off
	global_store_dwordx2 v[74:75], v[50:51], off offset:2048
	global_store_dwordx2 v[76:77], v[52:53], off
	global_store_dwordx2 v[72:73], v[54:55], off
	v_or_b32_e32 v52, 0x60, v120
	v_ashrrev_i32_e32 v53, 31, v52
	v_lshl_add_u64 v[54:55], v[52:53], 2, s[14:15]
	global_load_dwordx4 v[250:253], v[54:55], off
	v_lshrrev_b32_e32 v56, 6, v68
	v_and_or_b32 v122, v56, s50, v121
	v_lshlrev_b64 v[56:57], 14, v[122:123]
	v_lshl_add_u64 v[56:57], s[38:39], 0, v[56:57]
	v_lshl_add_u64 v[56:57], v[56:57], 0, v[152:153]
	v_lshl_add_u64 v[58:59], v[56:57], 0, 32
	v_lshl_add_u64 v[56:57], v[56:57], 0, v[114:115]
	v_lshl_add_u64 v[60:61], v[58:59], 0, v[116:117]
	v_lshl_add_u64 v[58:59], v[58:59], 0, v[118:119]
	s_waitcnt vmcnt(5)
	v_mov_b32_e32 v48, v246
	v_mov_b32_e32 v49, v247
	v_mov_b32_e32 v50, v248
	v_mov_b32_e32 v51, v249
	v_pk_fma_f32 v[48:49], v[48:49], s[30:31], v[112:113] op_sel_hi:[1,0,0]
	v_pk_fma_f32 v[50:51], v[50:51], s[30:31], v[112:113] op_sel_hi:[1,0,0]
	v_mul_f32_e32 v53, 0x4b800000, v48
	v_mul_f32_e32 v62, 0x4b800000, v49
	v_mul_f32_e32 v63, 0x4b800000, v50
	v_mul_f32_e32 v64, 0x4b800000, v51
	v_cmp_gt_f32_e32 vcc, s40, v48
	v_cmp_gt_f32_e64 s[0:1], s40, v49
	v_cmp_gt_f32_e64 s[10:11], s40, v50
	v_cmp_gt_f32_e64 s[12:13], s40, v51
	v_cndmask_b32_e32 v48, v48, v53, vcc
	v_cndmask_b32_e64 v49, v49, v62, s[0:1]
	v_cndmask_b32_e64 v50, v50, v63, s[10:11]
	v_cndmask_b32_e64 v51, v51, v64, s[12:13]
	v_rsq_f32_e32 v48, v48
	v_rsq_f32_e32 v49, v49
	v_rsq_f32_e32 v50, v50
	v_rsq_f32_e32 v51, v51
	v_mul_f32_e32 v53, 0x45800000, v48
	v_mul_f32_e32 v62, 0x45800000, v49
	v_mul_f32_e32 v63, 0x45800000, v50
	v_mul_f32_e32 v64, 0x45800000, v51
	v_cndmask_b32_e32 v48, v48, v53, vcc
	v_cndmask_b32_e64 v49, v49, v62, s[0:1]
	v_cndmask_b32_e64 v50, v50, v63, s[10:11]
	v_cndmask_b32_e64 v51, v51, v64, s[12:13]
	v_mul_f32_e32 v44, v44, v48
	v_mul_f32_e32 v45, v45, v49
	v_mul_f32_e32 v46, v46, v50
	v_mul_f32_e32 v47, v47, v51
	v_mul_f32_e32 v40, v40, v48
	v_mul_f32_e32 v41, v41, v49
	v_mul_f32_e32 v36, v36, v48
	v_mul_f32_e32 v37, v37, v49
	v_mul_f32_e32 v38, v38, v50
	v_mul_f32_e32 v39, v39, v51
	v_mul_f32_e32 v48, v32, v48
	v_mul_f32_e32 v49, v33, v49
	v_cvt_pk_bf16_f32 v32, v44, v45
	v_cvt_pk_bf16_f32 v33, v46, v47
	v_mul_f32_e32 v42, v42, v50
	v_mul_f32_e32 v43, v43, v51
	v_mul_f32_e32 v50, v34, v50
	v_mul_f32_e32 v51, v35, v51
	v_cvt_pk_bf16_f32 v34, v40, v41
	v_cvt_pk_bf16_f32 v35, v42, v43
	v_cvt_pk_bf16_f32 v36, v36, v37
	v_cvt_pk_bf16_f32 v37, v38, v39
	v_cvt_pk_bf16_f32 v38, v48, v49
	v_cvt_pk_bf16_f32 v39, v50, v51
	global_store_dwordx2 v[56:57], v[32:33], off offset:32
	global_store_dwordx2 v[56:57], v[34:35], off offset:2080
	global_store_dwordx2 v[60:61], v[36:37], off
	global_store_dwordx2 v[58:59], v[38:39], off
	v_or_b32_e32 v36, 0x70, v120
	v_ashrrev_i32_e32 v37, 31, v36
	v_lshl_add_u64 v[38:39], v[36:37], 2, s[14:15]
	global_load_dwordx4 v[246:249], v[38:39], off
	v_lshrrev_b32_e32 v40, 6, v52
	v_and_or_b32 v122, v40, s50, v121
	v_lshlrev_b64 v[40:41], 14, v[122:123]
	v_lshl_add_u64 v[40:41], s[38:39], 0, v[40:41]
	v_lshl_add_u64 v[40:41], v[40:41], 0, v[152:153]
	v_lshl_add_u64 v[42:43], v[40:41], 0, 64
	v_lshl_add_u64 v[40:41], v[40:41], 0, v[114:115]
	v_lshl_add_u64 v[44:45], v[42:43], 0, v[116:117]
	v_lshl_add_u64 v[42:43], v[42:43], 0, v[118:119]
	s_waitcnt vmcnt(5)
	v_mov_b32_e32 v32, v250
	v_mov_b32_e32 v33, v251
	v_mov_b32_e32 v34, v252
	v_mov_b32_e32 v35, v253
	v_pk_fma_f32 v[32:33], v[32:33], s[30:31], v[112:113] op_sel_hi:[1,0,0]
	v_pk_fma_f32 v[34:35], v[34:35], s[30:31], v[112:113] op_sel_hi:[1,0,0]
	v_mul_f32_e32 v37, 0x4b800000, v32
	v_mul_f32_e32 v46, 0x4b800000, v33
	v_mul_f32_e32 v47, 0x4b800000, v34
	v_mul_f32_e32 v48, 0x4b800000, v35
	v_cmp_gt_f32_e32 vcc, s40, v32
	v_cmp_gt_f32_e64 s[0:1], s40, v33
	v_cmp_gt_f32_e64 s[10:11], s40, v34
	v_cmp_gt_f32_e64 s[12:13], s40, v35
	v_cndmask_b32_e32 v32, v32, v37, vcc
	v_cndmask_b32_e64 v33, v33, v46, s[0:1]
	v_cndmask_b32_e64 v34, v34, v47, s[10:11]
	v_cndmask_b32_e64 v35, v35, v48, s[12:13]
	v_rsq_f32_e32 v32, v32
	v_rsq_f32_e32 v33, v33
	v_rsq_f32_e32 v34, v34
	v_rsq_f32_e32 v35, v35
	v_mul_f32_e32 v37, 0x45800000, v32
	v_mul_f32_e32 v46, 0x45800000, v33
	v_mul_f32_e32 v47, 0x45800000, v34
	v_mul_f32_e32 v48, 0x45800000, v35
	v_cndmask_b32_e32 v32, v32, v37, vcc
	v_cndmask_b32_e64 v33, v33, v46, s[0:1]
	v_cndmask_b32_e64 v34, v34, v47, s[10:11]
	v_cndmask_b32_e64 v35, v35, v48, s[12:13]
	v_mul_f32_e32 v28, v28, v32
	v_mul_f32_e32 v29, v29, v33
	v_mul_f32_e32 v30, v30, v34
	v_mul_f32_e32 v31, v31, v35
	v_mul_f32_e32 v24, v24, v32
	v_mul_f32_e32 v25, v25, v33
	v_mul_f32_e32 v20, v20, v32
	v_mul_f32_e32 v21, v21, v33
	v_mul_f32_e32 v22, v22, v34
	v_mul_f32_e32 v23, v23, v35
	v_mul_f32_e32 v32, v16, v32
	v_mul_f32_e32 v33, v17, v33
	v_cvt_pk_bf16_f32 v16, v28, v29
	v_cvt_pk_bf16_f32 v17, v30, v31
	v_mul_f32_e32 v26, v26, v34
	v_mul_f32_e32 v27, v27, v35
	v_mul_f32_e32 v34, v18, v34
	v_mul_f32_e32 v35, v19, v35
	v_cvt_pk_bf16_f32 v18, v24, v25
	v_cvt_pk_bf16_f32 v19, v26, v27
	v_cvt_pk_bf16_f32 v20, v20, v21
	v_cvt_pk_bf16_f32 v21, v22, v23
	v_cvt_pk_bf16_f32 v22, v32, v33
	v_cvt_pk_bf16_f32 v23, v34, v35
	global_store_dwordx2 v[40:41], v[16:17], off offset:64
	global_store_dwordx2 v[40:41], v[18:19], off offset:2112
	global_store_dwordx2 v[44:45], v[20:21], off
	global_store_dwordx2 v[42:43], v[22:23], off
	v_lshrrev_b32_e32 v20, 6, v36
	v_and_or_b32 v122, v20, s50, v121
	v_lshlrev_b64 v[20:21], 14, v[122:123]
	v_lshl_add_u64 v[20:21], s[38:39], 0, v[20:21]
	v_lshl_add_u64 v[20:21], v[20:21], 0, v[152:153]
	v_lshl_add_u64 v[22:23], v[20:21], 0, s[36:37]
	v_lshl_add_u64 v[20:21], v[20:21], 0, v[114:115]
	v_lshl_add_u64 v[24:25], v[22:23], 0, v[116:117]
	v_lshl_add_u64 v[22:23], v[22:23], 0, v[118:119]
	s_waitcnt vmcnt(4)
	v_mov_b32_e32 v16, v246
	v_mov_b32_e32 v17, v247
	v_mov_b32_e32 v18, v248
	v_mov_b32_e32 v19, v249
	v_pk_fma_f32 v[16:17], v[16:17], s[30:31], v[112:113] op_sel_hi:[1,0,0]
	v_pk_fma_f32 v[18:19], v[18:19], s[30:31], v[112:113] op_sel_hi:[1,0,0]
	v_mul_f32_e32 v26, 0x4b800000, v16
	v_mul_f32_e32 v27, 0x4b800000, v17
	v_mul_f32_e32 v28, 0x4b800000, v18
	v_mul_f32_e32 v29, 0x4b800000, v19
	v_cmp_gt_f32_e32 vcc, s40, v16
	v_cmp_gt_f32_e64 s[0:1], s40, v17
	v_cmp_gt_f32_e64 s[10:11], s40, v18
	v_cmp_gt_f32_e64 s[12:13], s40, v19
	v_cndmask_b32_e32 v16, v16, v26, vcc
	v_cndmask_b32_e64 v17, v17, v27, s[0:1]
	v_cndmask_b32_e64 v18, v18, v28, s[10:11]
	v_cndmask_b32_e64 v19, v19, v29, s[12:13]
	v_rsq_f32_e32 v16, v16
	v_rsq_f32_e32 v17, v17
	v_rsq_f32_e32 v18, v18
	v_rsq_f32_e32 v19, v19
	v_mul_f32_e32 v26, 0x45800000, v16
	v_mul_f32_e32 v27, 0x45800000, v17
	v_mul_f32_e32 v28, 0x45800000, v18
	v_mul_f32_e32 v29, 0x45800000, v19
	v_cndmask_b32_e32 v16, v16, v26, vcc
	v_cndmask_b32_e64 v17, v17, v27, s[0:1]
	v_cndmask_b32_e64 v18, v18, v28, s[10:11]
	v_cndmask_b32_e64 v19, v19, v29, s[12:13]
	v_mul_f32_e32 v12, v12, v16
	v_mul_f32_e32 v13, v13, v17
	v_mul_f32_e32 v14, v14, v18
	v_mul_f32_e32 v15, v15, v19
	v_mul_f32_e32 v8, v8, v16
	v_mul_f32_e32 v9, v9, v17
	v_mul_f32_e32 v4, v4, v16
	v_mul_f32_e32 v5, v5, v17
	v_mul_f32_e32 v6, v6, v18
	v_mul_f32_e32 v7, v7, v19
	v_mul_f32_e32 v16, v0, v16
	v_mul_f32_e32 v17, v1, v17
	v_cvt_pk_bf16_f32 v0, v12, v13
	v_cvt_pk_bf16_f32 v1, v14, v15
	v_mul_f32_e32 v10, v10, v18
	v_mul_f32_e32 v11, v11, v19
	v_mul_f32_e32 v18, v2, v18
	v_mul_f32_e32 v19, v3, v19
	v_cvt_pk_bf16_f32 v2, v8, v9
	v_cvt_pk_bf16_f32 v3, v10, v11
	v_cvt_pk_bf16_f32 v4, v4, v5
	v_cvt_pk_bf16_f32 v5, v6, v7
	v_cvt_pk_bf16_f32 v6, v16, v17
	v_cvt_pk_bf16_f32 v7, v18, v19
	global_store_dwordx2 v[20:21], v[0:1], off offset:96
	global_store_dwordx2 v[20:21], v[2:3], off offset:2144
	global_store_dwordx2 v[24:25], v[4:5], off
	global_store_dwordx2 v[22:23], v[6:7], off
	s_branch .LBB0_699

.LBB0_768:
	s_ashr_i32 s10, s4, 3
	s_mul_hi_i32 s11, s10, 0x78787879
	s_lshr_b32 s12, s11, 31
	s_ashr_i32 s11, s11, 3
	s_add_i32 s11, s11, s12
	s_mul_i32 s12, s11, 17
	s_sub_i32 s10, s10, s12
	s_lshl_b32 s12, s4, 8
	s_lshl_b32 s11, s11, 11
	s_and_b32 s12, s12, 0x700
	s_or_b32 s12, s11, s12
	s_ashr_i32 s13, s12, 31
	s_lshl_b32 s10, s10, 7
	s_lshl_b64 s[14:15], s[12:13], 11
	s_add_u32 s14, s6, s14
	s_addc_u32 s15, s7, s15
	s_ashr_i32 s11, s10, 31
	v_mov_b32_e32 v36, v220
	s_lshl_b64 s[16:17], s[10:11], 11
	s_add_u32 s16, s8, s16
	v_ashrrev_i32_e32 v26, 2, v36
	v_ashrrev_i32_e32 v27, 31, v26
	s_addc_u32 s17, s9, s17
	v_lshlrev_b64 v[0:1], 11, v[26:27]
	v_lshlrev_b32_e32 v4, 4, v36
	v_lshl_add_u64 v[2:3], s[16:17], 0, v[0:1]
	v_lshl_add_u64 v[0:1], s[14:15], 0, v[0:1]
	v_and_b32_e32 v152, 48, v4
	v_lshl_add_u64 v[154:155], v[0:1], 0, v[152:153]
	v_add_co_u32_e32 v28, vcc, s38, v154
	v_lshl_add_u64 v[156:157], v[2:3], 0, v[152:153]
	s_nop 0
	v_addc_co_u32_e32 v29, vcc, 0, v155, vcc
	v_add_co_u32_e32 v30, vcc, s39, v154
	global_load_dwordx4 v[2:5], v[154:155], off
	s_nop 0
	v_addc_co_u32_e32 v31, vcc, 0, v155, vcc
	v_add_co_u32_e32 v32, vcc, s40, v154
	global_load_dwordx4 v[6:9], v[28:29], off
	s_nop 0
	v_addc_co_u32_e32 v33, vcc, 0, v155, vcc
	v_add_co_u32_e32 v34, vcc, s38, v156
	global_load_dwordx4 v[10:13], v[30:31], off
	s_nop 0
	v_addc_co_u32_e32 v35, vcc, 0, v157, vcc
	global_load_dwordx4 v[14:17], v[32:33], off
	global_load_dwordx4 v[18:21], v[156:157], off
	global_load_dwordx4 v[22:25], v[34:35], off
	global_load_dwordx4 v[120:123], v[154:155], off offset:64
	global_load_dwordx4 v[128:131], v[28:29], off offset:64
	global_load_dwordx4 v[132:135], v[30:31], off offset:64
	global_load_dwordx4 v[136:139], v[32:33], off offset:64
	global_load_dwordx4 v[124:127], v[156:157], off offset:64
	global_load_dwordx4 v[140:143], v[34:35], off offset:64
	v_lshrrev_b32_e32 v1, 4, v36
	v_lshrrev_b32_e32 v27, 2, v36
	v_sub_u32_e32 v39, 0, v1
	v_sub_u32_e32 v27, 0, v27
	v_and_b32_e32 v37, 0x3ffff8f, v36
	v_lshlrev_b32_e32 v38, 6, v36
	v_xor_b32_e32 v36, v36, v39
	v_xor_b32_e32 v1, v1, v27
	v_lshlrev_b32_e32 v27, 4, v36
	v_lshlrev_b32_e32 v1, 4, v1
	v_and_b32_e32 v40, 0x1000, v38
	v_and_b32_e32 v27, 48, v27
	v_and_b32_e32 v1, 48, v1
	v_and_b32_e32 v41, 0x3c0, v38
	v_and_b32_e32 v38, 0xffffe3c0, v38
	v_lshl_add_u32 v37, v37, 6, v166
	v_lshl_or_b32 v152, v26, 6, v27
	v_or_b32_e32 v26, v1, v40
	s_mov_b32 s11, -2
	s_mov_b32 s13, s35
	v_mov_b32_e32 v0, 0
	v_or3_b32 v168, v40, v41, v1
	v_add_u32_e32 v169, v1, v38
	v_add_u32_e32 v170, v1, v37
	v_add_u32_e32 v171, v26, v41
	v_lshl_add_u64 v[158:159], v[154:155], 0, s[24:25]
	v_lshl_add_u64 v[160:161], v[154:155], 0, s[28:29]
	v_lshl_add_u64 v[162:163], v[154:155], 0, s[30:31]
	v_lshl_add_u64 v[164:165], v[156:157], 0, s[24:25]
	v_mov_b32_e32 v1, v153
	v_mov_b32_e32 v26, v153
	v_mov_b32_e32 v27, v153
	v_mov_b32_e32 v28, 0
	v_mov_b32_e32 v29, v153
	v_mov_b32_e32 v30, v153
	v_mov_b32_e32 v31, v153
	v_mov_b32_e32 v32, 0
	v_mov_b32_e32 v33, v153
	v_mov_b32_e32 v34, v153
	v_mov_b32_e32 v35, v153
	v_mov_b32_e32 v36, 0
	v_mov_b32_e32 v37, v153
	v_mov_b32_e32 v38, v153
	v_mov_b32_e32 v39, v153
	v_mov_b32_e32 v40, 0
	v_mov_b32_e32 v41, v153
	v_mov_b32_e32 v42, v153
	v_mov_b32_e32 v43, v153
	v_mov_b32_e32 v44, 0
	s_waitcnt vmcnt(11)
	ds_write_b128 v152, v[2:5]
	s_waitcnt vmcnt(10)
	ds_write_b128 v152, v[6:9] offset:4096
	s_waitcnt vmcnt(9)
	ds_write_b128 v152, v[10:13] offset:8192
	s_waitcnt vmcnt(8)
	ds_write_b128 v152, v[14:17] offset:12288
	s_waitcnt vmcnt(7)
	ds_write_b128 v152, v[18:21] offset:32768
	s_waitcnt vmcnt(6)
	ds_write_b128 v152, v[22:25] offset:36864
	v_mov_b32_e32 v2, v153
	v_mov_b32_e32 v3, v153
	v_mov_b32_e32 v4, 0
	v_mov_b32_e32 v5, v153
	v_mov_b32_e32 v6, v153
	v_mov_b32_e32 v7, v153
	v_mov_b32_e32 v8, 0
	v_mov_b32_e32 v9, v153
	v_mov_b32_e32 v10, v153
	v_mov_b32_e32 v11, v153
	v_mov_b32_e32 v12, 0
	v_mov_b32_e32 v13, v153
	v_mov_b32_e32 v14, v153
	v_mov_b32_e32 v15, v153
	v_mov_b32_e32 v16, 0
	v_mov_b32_e32 v17, v153
	v_mov_b32_e32 v18, v153
	v_mov_b32_e32 v19, v153
	v_mov_b32_e32 v20, 0
	v_mov_b32_e32 v21, v153
	v_mov_b32_e32 v22, v153
	v_mov_b32_e32 v23, v153
	v_mov_b32_e32 v24, 0
	v_mov_b32_e32 v25, v153
	v_mov_b32_e32 v45, v153
	v_mov_b32_e32 v46, v153
	v_mov_b32_e32 v47, v153
	v_mov_b32_e32 v48, 0
	v_mov_b32_e32 v49, v153
	v_mov_b32_e32 v50, v153
	v_mov_b32_e32 v51, v153
	v_mov_b32_e32 v52, 0
	v_mov_b32_e32 v53, v153
	v_mov_b32_e32 v54, v153
	v_mov_b32_e32 v55, v153
	v_mov_b32_e32 v56, 0
	v_mov_b32_e32 v57, v153
	v_mov_b32_e32 v58, v153
	v_mov_b32_e32 v59, v153
	v_mov_b32_e32 v60, 0
	v_mov_b32_e32 v61, v153
	v_mov_b32_e32 v62, v153
	v_mov_b32_e32 v63, v153
	v_mov_b32_e32 v64, 0
	v_mov_b32_e32 v65, v153
	v_mov_b32_e32 v66, v153
	v_mov_b32_e32 v67, v153
	v_mov_b32_e32 v68, 0
	v_mov_b32_e32 v69, v153
	v_mov_b32_e32 v70, v153
	v_mov_b32_e32 v71, v153
	v_mov_b32_e32 v72, 0
	v_mov_b32_e32 v73, v153
	v_mov_b32_e32 v74, v153
	v_mov_b32_e32 v75, v153
	v_mov_b32_e32 v76, 0
	v_mov_b32_e32 v77, v153
	v_mov_b32_e32 v78, v153
	v_mov_b32_e32 v79, v153
	v_mov_b32_e32 v80, 0
	v_mov_b32_e32 v81, v153
	v_mov_b32_e32 v82, v153
	v_mov_b32_e32 v83, v153
	v_mov_b32_e32 v84, 0
	v_mov_b32_e32 v85, v153
	v_mov_b32_e32 v86, v153
	v_mov_b32_e32 v87, v153
	v_mov_b32_e32 v88, 0
	v_mov_b32_e32 v89, v153
	v_mov_b32_e32 v90, v153
	v_mov_b32_e32 v91, v153
	v_mov_b32_e32 v92, 0
	v_mov_b32_e32 v93, v153
	v_mov_b32_e32 v94, v153
	v_mov_b32_e32 v95, v153
	v_mov_b32_e32 v96, 0
	v_mov_b32_e32 v97, v153
	v_mov_b32_e32 v98, v153
	v_mov_b32_e32 v99, v153
	v_mov_b32_e32 v100, 0
	v_mov_b32_e32 v101, v153
	v_mov_b32_e32 v102, v153
	v_mov_b32_e32 v103, v153
	v_mov_b32_e32 v104, 0
	v_mov_b32_e32 v105, v153
	v_mov_b32_e32 v106, v153
	v_mov_b32_e32 v107, v153
	v_mov_b32_e32 v108, 0
	v_mov_b32_e32 v109, v153
	v_mov_b32_e32 v110, v153
	v_mov_b32_e32 v111, v153
	v_mov_b32_e32 v112, 0
	v_mov_b32_e32 v113, v153
	v_mov_b32_e32 v114, v153
	v_mov_b32_e32 v115, v153
	v_mov_b32_e32 v116, 0
	v_mov_b32_e32 v117, v153
	v_mov_b32_e32 v118, v153
	v_mov_b32_e32 v119, v153
	v_mov_b32_e32 v144, 0
	v_mov_b32_e32 v145, v153
	v_mov_b32_e32 v146, v153
	v_mov_b32_e32 v147, v153
	v_mov_b32_e32 v148, 0
	v_mov_b32_e32 v149, v153
	v_mov_b32_e32 v150, v153
	v_mov_b32_e32 v151, v153
	s_waitcnt lgkmcnt(0)
	s_add_i32 s14, s13, 64
	s_min_u32 s15, s14, 0x3e0
	s_lshl_b32 s34, s15, 1
	v_lshl_add_u64 v[172:173], v[154:155], 0, s[34:35]
	v_lshl_add_u64 v[176:177], v[158:159], 0, s[34:35]
	v_lshl_add_u64 v[180:181], v[160:161], 0, s[34:35]
	v_lshl_add_u64 v[184:185], v[162:163], 0, s[34:35]
	v_lshl_add_u64 v[188:189], v[156:157], 0, s[34:35]
	v_lshl_add_u64 v[192:193], v[164:165], 0, s[34:35]

.LBB0_769:
	global_load_dwordx4 v[172:175], v[172:173], off
	ds_read_b128 v[196:199], v171 offset:32768
	global_load_dwordx4 v[176:179], v[176:177], off
	ds_read_b128 v[200:203], v171 offset:33792
	global_load_dwordx4 v[180:183], v[180:181], off
	ds_read_b128 v[204:207], v171 offset:34816
	global_load_dwordx4 v[184:187], v[184:185], off
	ds_read_b128 v[208:211], v171 offset:35840
	global_load_dwordx4 v[188:191], v[188:189], off
	ds_read_b128 v[212:215], v169
	global_load_dwordx4 v[192:195], v[192:193], off
	ds_read_b128 v[216:219], v169 offset:1024
	ds_read_b128 v[222:225], v169 offset:2048
	ds_read_b128 v[226:229], v169 offset:3072
	ds_read_b128 v[230:233], v169 offset:4096
	ds_read_b128 v[234:237], v169 offset:5120
	ds_read_b128 v[238:241], v169 offset:6144
	ds_read_b128 v[242:245], v169 offset:7168
	s_setprio 1
	s_waitcnt lgkmcnt(7)
	v_mfma_f32_16x16x32_bf16 v[148:151], v[196:199], v[212:215], v[148:151]
	v_mfma_f32_16x16x32_bf16 v[144:147], v[200:203], v[212:215], v[144:147]
	v_mfma_f32_16x16x32_bf16 v[116:119], v[204:207], v[212:215], v[116:119]
	v_mfma_f32_16x16x32_bf16 v[112:115], v[208:211], v[212:215], v[112:115]
	s_waitcnt vmcnt(11)
	ds_write_b128 v152, v[120:123] offset:16384
	s_waitcnt lgkmcnt(7)
	v_mfma_f32_16x16x32_bf16 v[108:111], v[196:199], v[216:219], v[108:111]
	v_mfma_f32_16x16x32_bf16 v[104:107], v[200:203], v[216:219], v[104:107]
	v_mfma_f32_16x16x32_bf16 v[100:103], v[204:207], v[216:219], v[100:103]
	v_mfma_f32_16x16x32_bf16 v[96:99], v[208:211], v[216:219], v[96:99]
	s_waitcnt vmcnt(9)
	ds_write_b128 v152, v[128:131] offset:20480
	s_waitcnt lgkmcnt(7)
	v_mfma_f32_16x16x32_bf16 v[92:95], v[196:199], v[222:225], v[92:95]
	v_mfma_f32_16x16x32_bf16 v[88:91], v[200:203], v[222:225], v[88:91]
	v_mfma_f32_16x16x32_bf16 v[84:87], v[204:207], v[222:225], v[84:87]
	v_mfma_f32_16x16x32_bf16 v[80:83], v[208:211], v[222:225], v[80:83]
	s_waitcnt vmcnt(8)
	ds_write_b128 v152, v[132:135] offset:24576
	s_waitcnt lgkmcnt(7)
	v_mfma_f32_16x16x32_bf16 v[76:79], v[196:199], v[226:229], v[76:79]
	v_mfma_f32_16x16x32_bf16 v[72:75], v[200:203], v[226:229], v[72:75]
	v_mfma_f32_16x16x32_bf16 v[68:71], v[204:207], v[226:229], v[68:71]
	v_mfma_f32_16x16x32_bf16 v[64:67], v[208:211], v[226:229], v[64:67]
	s_waitcnt vmcnt(7)
	ds_write_b128 v152, v[136:139] offset:28672
	s_waitcnt lgkmcnt(7)
	v_mfma_f32_16x16x32_bf16 v[60:63], v[196:199], v[230:233], v[60:63]
	v_mfma_f32_16x16x32_bf16 v[56:59], v[200:203], v[230:233], v[56:59]
	v_mfma_f32_16x16x32_bf16 v[52:55], v[204:207], v[230:233], v[52:55]
	v_mfma_f32_16x16x32_bf16 v[48:51], v[208:211], v[230:233], v[48:51]
	s_waitcnt vmcnt(7)
	ds_write_b128 v152, v[124:127] offset:40960
	s_waitcnt lgkmcnt(7)
	v_mfma_f32_16x16x32_bf16 v[44:47], v[196:199], v[234:237], v[44:47]
	v_mfma_f32_16x16x32_bf16 v[40:43], v[200:203], v[234:237], v[40:43]
	v_mfma_f32_16x16x32_bf16 v[36:39], v[204:207], v[234:237], v[36:39]
	v_mfma_f32_16x16x32_bf16 v[32:35], v[208:211], v[234:237], v[32:35]
	s_waitcnt vmcnt(6)
	ds_write_b128 v152, v[140:143] offset:45056
	s_waitcnt lgkmcnt(7)
	v_mfma_f32_16x16x32_bf16 v[28:31], v[196:199], v[238:241], v[28:31]
	v_mfma_f32_16x16x32_bf16 v[24:27], v[200:203], v[238:241], v[24:27]
	v_mfma_f32_16x16x32_bf16 v[20:23], v[204:207], v[238:241], v[20:23]
	v_mfma_f32_16x16x32_bf16 v[16:19], v[208:211], v[238:241], v[16:19]
	s_waitcnt lgkmcnt(6)
	v_mfma_f32_16x16x32_bf16 v[12:15], v[196:199], v[242:245], v[12:15]
	v_mfma_f32_16x16x32_bf16 v[8:11], v[200:203], v[242:245], v[8:11]
	v_mfma_f32_16x16x32_bf16 v[4:7], v[204:207], v[242:245], v[4:7]
	v_mfma_f32_16x16x32_bf16 v[0:3], v[208:211], v[242:245], v[0:3]
	s_setprio 0
	s_min_u32 s13, s13, 0x380
	s_lshl_b32 s34, s13, 1
	s_mov_b32 s17, s35
	s_add_i32 s16, s34, 0xc0
	v_lshl_add_u64 v[120:121], v[154:155], 0, s[34:35]
	v_lshl_add_u64 v[124:125], v[156:157], 0, s[34:35]
	v_lshl_add_u64 v[128:129], v[158:159], 0, s[16:17]
	v_lshl_add_u64 v[132:133], v[160:161], 0, s[16:17]
	v_lshl_add_u64 v[136:137], v[162:163], 0, s[16:17]
	v_lshl_add_u64 v[140:141], v[164:165], 0, s[16:17]
	s_waitcnt lgkmcnt(0)
	s_barrier
	global_load_dwordx4 v[120:123], v[120:121], off offset:192
	ds_read_b128 v[196:199], v168 offset:40960
	global_load_dwordx4 v[124:127], v[124:125], off offset:192
	ds_read_b128 v[200:203], v168 offset:41984
	global_load_dwordx4 v[128:131], v[128:129], off
	ds_read_b128 v[204:207], v168 offset:43008
	global_load_dwordx4 v[132:135], v[132:133], off
	ds_read_b128 v[208:211], v168 offset:44032
	global_load_dwordx4 v[136:139], v[136:137], off
	ds_read_b128 v[212:215], v170
	global_load_dwordx4 v[140:143], v[140:141], off
	ds_read_b128 v[216:219], v170 offset:1024
	ds_read_b128 v[222:225], v170 offset:2048
	ds_read_b128 v[226:229], v170 offset:3072
	ds_read_b128 v[230:233], v170 offset:4096
	ds_read_b128 v[234:237], v170 offset:5120
	ds_read_b128 v[238:241], v170 offset:6144
	ds_read_b128 v[242:245], v170 offset:7168
	s_setprio 1
	s_waitcnt lgkmcnt(7)
	v_mfma_f32_16x16x32_bf16 v[148:151], v[196:199], v[212:215], v[148:151]
	v_mfma_f32_16x16x32_bf16 v[144:147], v[200:203], v[212:215], v[144:147]
	v_mfma_f32_16x16x32_bf16 v[116:119], v[204:207], v[212:215], v[116:119]
	v_mfma_f32_16x16x32_bf16 v[112:115], v[208:211], v[212:215], v[112:115]
	s_waitcnt vmcnt(11)
	ds_write_b128 v152, v[172:175]
	s_waitcnt lgkmcnt(7)
	v_mfma_f32_16x16x32_bf16 v[108:111], v[196:199], v[216:219], v[108:111]
	v_mfma_f32_16x16x32_bf16 v[104:107], v[200:203], v[216:219], v[104:107]
	v_mfma_f32_16x16x32_bf16 v[100:103], v[204:207], v[216:219], v[100:103]
	v_mfma_f32_16x16x32_bf16 v[96:99], v[208:211], v[216:219], v[96:99]
	s_waitcnt vmcnt(10)
	ds_write_b128 v152, v[176:179] offset:4096
	s_waitcnt lgkmcnt(7)
	v_mfma_f32_16x16x32_bf16 v[92:95], v[196:199], v[222:225], v[92:95]
	v_mfma_f32_16x16x32_bf16 v[88:91], v[200:203], v[222:225], v[88:91]
	v_mfma_f32_16x16x32_bf16 v[84:87], v[204:207], v[222:225], v[84:87]
	v_mfma_f32_16x16x32_bf16 v[80:83], v[208:211], v[222:225], v[80:83]
	s_waitcnt vmcnt(9)
	ds_write_b128 v152, v[180:183] offset:8192
	s_waitcnt lgkmcnt(7)
	v_mfma_f32_16x16x32_bf16 v[76:79], v[196:199], v[226:229], v[76:79]
	v_mfma_f32_16x16x32_bf16 v[72:75], v[200:203], v[226:229], v[72:75]
	v_mfma_f32_16x16x32_bf16 v[68:71], v[204:207], v[226:229], v[68:71]
	v_mfma_f32_16x16x32_bf16 v[64:67], v[208:211], v[226:229], v[64:67]
	s_waitcnt vmcnt(8)
	ds_write_b128 v152, v[184:187] offset:12288
	s_waitcnt lgkmcnt(7)
	v_mfma_f32_16x16x32_bf16 v[60:63], v[196:199], v[230:233], v[60:63]
	v_mfma_f32_16x16x32_bf16 v[56:59], v[200:203], v[230:233], v[56:59]
	v_mfma_f32_16x16x32_bf16 v[52:55], v[204:207], v[230:233], v[52:55]
	v_mfma_f32_16x16x32_bf16 v[48:51], v[208:211], v[230:233], v[48:51]
	s_waitcnt vmcnt(7)
	ds_write_b128 v152, v[188:191] offset:32768
	s_waitcnt lgkmcnt(7)
	v_mfma_f32_16x16x32_bf16 v[44:47], v[196:199], v[234:237], v[44:47]
	v_mfma_f32_16x16x32_bf16 v[40:43], v[200:203], v[234:237], v[40:43]
	v_mfma_f32_16x16x32_bf16 v[36:39], v[204:207], v[234:237], v[36:39]
	v_mfma_f32_16x16x32_bf16 v[32:35], v[208:211], v[234:237], v[32:35]
	s_waitcnt vmcnt(6)
	ds_write_b128 v152, v[192:195] offset:36864
	s_waitcnt lgkmcnt(7)
	v_mfma_f32_16x16x32_bf16 v[28:31], v[196:199], v[238:241], v[28:31]
	v_mfma_f32_16x16x32_bf16 v[24:27], v[200:203], v[238:241], v[24:27]
	v_mfma_f32_16x16x32_bf16 v[20:23], v[204:207], v[238:241], v[20:23]
	v_mfma_f32_16x16x32_bf16 v[16:19], v[208:211], v[238:241], v[16:19]
	s_waitcnt lgkmcnt(6)
	v_mfma_f32_16x16x32_bf16 v[12:15], v[196:199], v[242:245], v[12:15]
	v_mfma_f32_16x16x32_bf16 v[8:11], v[200:203], v[242:245], v[8:11]
	v_mfma_f32_16x16x32_bf16 v[4:7], v[204:207], v[242:245], v[4:7]
	v_mfma_f32_16x16x32_bf16 v[0:3], v[208:211], v[242:245], v[0:3]
	s_setprio 0
	s_add_i32 s11, s11, 2
	s_mov_b32 s13, s14
	s_add_i32 s14, s13, 64
	s_min_u32 s15, s14, 0x3e0
	s_lshl_b32 s34, s15, 1
	v_lshl_add_u64 v[172:173], v[154:155], 0, s[34:35]
	v_lshl_add_u64 v[176:177], v[158:159], 0, s[34:35]
	v_lshl_add_u64 v[180:181], v[160:161], 0, s[34:35]
	v_lshl_add_u64 v[184:185], v[162:163], 0, s[34:35]
	v_lshl_add_u64 v[188:189], v[156:157], 0, s[34:35]
	v_lshl_add_u64 v[192:193], v[164:165], 0, s[34:35]
	s_cmp_lt_u32 s11, 30
	s_waitcnt lgkmcnt(0)
	s_cbranch_scc1 .Lrot_1
	s_barrier
	s_waitcnt vmcnt(4)
	v_mov_b32_e32 v126, v220
	v_mov_b64_e32 v[124:125], s[72:73]
	v_and_b32_e32 v120, 0xffffff80, v126
	v_add_u32_e32 v120, s12, v120
	v_and_or_b32 v122, v126, 15, v120
	v_ashrrev_i32_e32 v123, 31, v122
	v_lshl_add_u64 v[120:121], v[122:123], 2, s[0:1]
	global_load_dword v246, v[120:121], off offset:64
	global_load_dword v247, v[120:121], off offset:128
	global_load_dword v248, v[120:121], off offset:192
	global_load_dword v249, v[120:121], off offset:256
	global_load_dword v250, v[120:121], off offset:320
	global_load_dword v251, v[120:121], off offset:384
	global_load_dword v252, v[120:121], off offset:448
	global_load_dword v120, v[120:121], off
	v_and_b32_e32 v121, 64, v126
	v_lshrrev_b32_e32 v126, 2, v126
	v_and_b32_e32 v126, 12, v126
	s_waitcnt vmcnt(0)
	v_fmamk_f32 v120, v120, 0x3a800000, v167
	v_mul_f32_e32 v127, 0x4b800000, v120
	v_cmp_gt_f32_e32 vcc, s42, v120
	s_nop 1
	v_cndmask_b32_e32 v120, v120, v127, vcc
	v_rsq_f32_e32 v127, v120
	v_or3_b32 v120, v121, v126, s10
	v_mad_i64_i32 v[124:125], s[10:11], v122, s41, v[124:125]
	v_mul_f32_e32 v121, 0x45800000, v127
	v_cndmask_b32_e32 v129, v127, v121, vcc
	v_mul_f32_e32 v132, v148, v129
	v_mul_f32_e32 v131, v149, v129
	v_mul_f32_e32 v130, v150, v129
	v_mul_f32_e32 v128, v151, v129
	v_cmp_lt_i32_e64 s[10:11], s43, v120
	s_and_saveexec_b64 s[12:13], s[10:11]
	s_xor_b64 s[12:13], exec, s[12:13]
	s_cbranch_execz .LBB0_774
	v_cmp_gt_u32_e32 vcc, s44, v120
	s_and_saveexec_b64 s[14:15], vcc
	s_cbranch_execz .LBB0_773
	v_mul_f32_e32 v121, 0xbfb8aa3b, v132
	v_exp_f32_e32 v121, v121
	v_mul_f32_e32 v126, 0xbfb8aa3b, v131
	v_mul_f32_e32 v127, 0xbfb8aa3b, v128
	v_exp_f32_e32 v126, v126
	v_add_f32_e32 v121, 1.0, v121
	v_rcp_f32_e32 v132, v121
	v_mul_f32_e32 v121, 0xbfb8aa3b, v130
	v_exp_f32_e32 v121, v121
	v_exp_f32_e32 v127, v127
	v_add_f32_e32 v126, 1.0, v126
	v_rcp_f32_e32 v133, v126
	v_add_f32_e32 v121, 1.0, v121
	v_rcp_f32_e32 v134, v121
	v_add_f32_e32 v121, 1.0, v127
	v_rcp_f32_e32 v135, v121
	v_mov_b32_e32 v121, v153
	v_lshl_add_u64 v[126:127], v[120:121], 2, v[124:125]
	v_add_co_u32_e32 v126, vcc, 0x2ffe000, v126
	s_nop 1
	v_addc_co_u32_e32 v127, vcc, 0, v127, vcc
	global_store_dwordx4 v[126:127], v[132:135], off

.LBB0_1736:
	s_ashr_i32 s12, s23, 3
	s_lshr_b32 s20, s12, 28
	s_add_i32 s20, s12, s20
	s_and_b32 s21, s20, 0x1fffff0
	s_sub_i32 s12, s12, s21
	s_lshl_b32 s20, s20, 7
	s_lshl_b32 s21, s23, 8
	s_and_b32 s20, s20, 0xfffff800
	s_and_b32 s21, s21, 0x700
	s_or_b32 s20, s20, s21
	s_ashr_i32 s21, s20, 31
	s_lshl_b32 s24, s12, 7
	s_lshl_b64 s[26:27], s[20:21], 11
	s_add_u32 s26, s3, s26
	s_addc_u32 s27, s4, s27
	s_add_i32 s12, s24, 0x880
	v_mov_b32_e32 v36, v220
	s_lshl_b64 s[28:29], s[12:13], 11
	s_add_u32 s28, s5, s28
	v_ashrrev_i32_e32 v26, 2, v36
	v_ashrrev_i32_e32 v27, 31, v26
	s_addc_u32 s29, s6, s29
	v_lshlrev_b64 v[0:1], 11, v[26:27]
	v_lshlrev_b32_e32 v4, 4, v36
	v_lshl_add_u64 v[2:3], s[28:29], 0, v[0:1]
	v_lshl_add_u64 v[0:1], s[26:27], 0, v[0:1]
	v_and_b32_e32 v152, 48, v4
	v_lshl_add_u64 v[154:155], v[0:1], 0, v[152:153]
	v_add_co_u32_e32 v28, vcc, s7, v154
	v_lshl_add_u64 v[156:157], v[2:3], 0, v[152:153]
	s_nop 0
	v_addc_co_u32_e32 v29, vcc, 0, v155, vcc
	v_add_co_u32_e32 v30, vcc, s8, v154
	global_load_dwordx4 v[2:5], v[154:155], off
	s_nop 0
	v_addc_co_u32_e32 v31, vcc, 0, v155, vcc
	v_add_co_u32_e32 v32, vcc, s9, v154
	global_load_dwordx4 v[6:9], v[28:29], off
	s_nop 0
	v_addc_co_u32_e32 v33, vcc, 0, v155, vcc
	v_add_co_u32_e32 v34, vcc, s7, v156
	global_load_dwordx4 v[10:13], v[30:31], off
	s_nop 0
	v_addc_co_u32_e32 v35, vcc, 0, v157, vcc
	global_load_dwordx4 v[14:17], v[32:33], off
	global_load_dwordx4 v[18:21], v[156:157], off
	global_load_dwordx4 v[22:25], v[34:35], off
	global_load_dwordx4 v[120:123], v[154:155], off offset:64
	global_load_dwordx4 v[124:127], v[28:29], off offset:64
	global_load_dwordx4 v[128:131], v[30:31], off offset:64
	global_load_dwordx4 v[136:139], v[32:33], off offset:64
	global_load_dwordx4 v[132:135], v[156:157], off offset:64
	global_load_dwordx4 v[140:143], v[34:35], off offset:64
	v_lshrrev_b32_e32 v27, 4, v36
	v_lshrrev_b32_e32 v37, 2, v36
	v_sub_u32_e32 v40, 0, v27
	v_sub_u32_e32 v37, 0, v37
	v_and_b32_e32 v38, 0x3ffff8f, v36
	v_lshlrev_b32_e32 v39, 6, v36
	v_xor_b32_e32 v36, v36, v40
	v_xor_b32_e32 v27, v27, v37
	v_lshlrev_b32_e32 v36, 4, v36
	v_lshlrev_b32_e32 v27, 4, v27
	v_and_b32_e32 v41, 0x1000, v39
	v_and_b32_e32 v36, 48, v36
	v_and_b32_e32 v27, 48, v27
	v_and_b32_e32 v42, 0x3c0, v39
	v_and_b32_e32 v39, 0xffffe3c0, v39
	v_lshl_add_u32 v38, v38, 6, v166
	v_lshl_or_b32 v152, v26, 6, v36
	v_or_b32_e32 v26, v27, v41
	s_mov_b32 s21, -2
	s_mov_b32 s25, s13
	v_mov_b32_e32 v0, 0
	v_mov_b32_e32 v1, v153
	v_or3_b32 v168, v41, v42, v27
	v_add_u32_e32 v169, v27, v39
	v_add_u32_e32 v170, v27, v38
	v_add_u32_e32 v171, v26, v42
	v_lshl_add_u64 v[158:159], v[154:155], 0, s[14:15]
	v_lshl_add_u64 v[160:161], v[154:155], 0, s[16:17]
	v_lshl_add_u64 v[162:163], v[154:155], 0, s[18:19]
	v_lshl_add_u64 v[164:165], v[156:157], 0, s[14:15]
	v_mov_b32_e32 v26, v153
	v_mov_b32_e32 v27, v153
	v_mov_b32_e32 v28, 0
	v_mov_b32_e32 v29, v153
	v_mov_b32_e32 v30, v153
	v_mov_b32_e32 v31, v153
	v_mov_b32_e32 v32, 0
	v_mov_b32_e32 v33, v153
	v_mov_b32_e32 v34, v153
	v_mov_b32_e32 v35, v153
	v_mov_b32_e32 v36, 0
	v_mov_b32_e32 v37, v153
	v_mov_b32_e32 v38, v153
	v_mov_b32_e32 v39, v153
	v_mov_b32_e32 v40, 0
	v_mov_b32_e32 v41, v153
	v_mov_b32_e32 v42, v153
	v_mov_b32_e32 v43, v153
	v_mov_b32_e32 v44, 0
	s_waitcnt vmcnt(11)
	ds_write_b128 v152, v[2:5]
	s_waitcnt vmcnt(10)
	ds_write_b128 v152, v[6:9] offset:4096
	s_waitcnt vmcnt(9)
	ds_write_b128 v152, v[10:13] offset:8192
	s_waitcnt vmcnt(8)
	ds_write_b128 v152, v[14:17] offset:12288
	s_waitcnt vmcnt(7)
	ds_write_b128 v152, v[18:21] offset:32768
	s_waitcnt vmcnt(6)
	ds_write_b128 v152, v[22:25] offset:36864
	v_mov_b32_e32 v2, v153
	v_mov_b32_e32 v3, v153
	v_mov_b32_e32 v4, 0
	v_mov_b32_e32 v5, v153
	v_mov_b32_e32 v6, v153
	v_mov_b32_e32 v7, v153
	v_mov_b32_e32 v8, 0
	v_mov_b32_e32 v9, v153
	v_mov_b32_e32 v10, v153
	v_mov_b32_e32 v11, v153
	v_mov_b32_e32 v12, 0
	v_mov_b32_e32 v13, v153
	v_mov_b32_e32 v14, v153
	v_mov_b32_e32 v15, v153
	v_mov_b32_e32 v16, 0
	v_mov_b32_e32 v17, v153
	v_mov_b32_e32 v18, v153
	v_mov_b32_e32 v19, v153
	v_mov_b32_e32 v20, 0
	v_mov_b32_e32 v21, v153
	v_mov_b32_e32 v22, v153
	v_mov_b32_e32 v23, v153
	v_mov_b32_e32 v24, 0
	v_mov_b32_e32 v25, v153
	v_mov_b32_e32 v45, v153
	v_mov_b32_e32 v46, v153
	v_mov_b32_e32 v47, v153
	v_mov_b32_e32 v48, 0
	v_mov_b32_e32 v49, v153
	v_mov_b32_e32 v50, v153
	v_mov_b32_e32 v51, v153
	v_mov_b32_e32 v52, 0
	v_mov_b32_e32 v53, v153
	v_mov_b32_e32 v54, v153
	v_mov_b32_e32 v55, v153
	v_mov_b32_e32 v56, 0
	v_mov_b32_e32 v57, v153
	v_mov_b32_e32 v58, v153
	v_mov_b32_e32 v59, v153
	v_mov_b32_e32 v60, 0
	v_mov_b32_e32 v61, v153
	v_mov_b32_e32 v62, v153
	v_mov_b32_e32 v63, v153
	v_mov_b32_e32 v64, 0
	v_mov_b32_e32 v65, v153
	v_mov_b32_e32 v66, v153
	v_mov_b32_e32 v67, v153
	v_mov_b32_e32 v68, 0
	v_mov_b32_e32 v69, v153
	v_mov_b32_e32 v70, v153
	v_mov_b32_e32 v71, v153
	v_mov_b32_e32 v72, 0
	v_mov_b32_e32 v73, v153
	v_mov_b32_e32 v74, v153
	v_mov_b32_e32 v75, v153
	v_mov_b32_e32 v76, 0
	v_mov_b32_e32 v77, v153
	v_mov_b32_e32 v78, v153
	v_mov_b32_e32 v79, v153
	v_mov_b32_e32 v80, 0
	v_mov_b32_e32 v81, v153
	v_mov_b32_e32 v82, v153
	v_mov_b32_e32 v83, v153
	v_mov_b32_e32 v84, 0
	v_mov_b32_e32 v85, v153
	v_mov_b32_e32 v86, v153
	v_mov_b32_e32 v87, v153
	v_mov_b32_e32 v88, 0
	v_mov_b32_e32 v89, v153
	v_mov_b32_e32 v90, v153
	v_mov_b32_e32 v91, v153
	v_mov_b32_e32 v92, 0
	v_mov_b32_e32 v93, v153
	v_mov_b32_e32 v94, v153
	v_mov_b32_e32 v95, v153
	v_mov_b32_e32 v96, 0
	v_mov_b32_e32 v97, v153
	v_mov_b32_e32 v98, v153
	v_mov_b32_e32 v99, v153
	v_mov_b32_e32 v100, 0
	v_mov_b32_e32 v101, v153
	v_mov_b32_e32 v102, v153
	v_mov_b32_e32 v103, v153
	v_mov_b32_e32 v104, 0
	v_mov_b32_e32 v105, v153
	v_mov_b32_e32 v106, v153
	v_mov_b32_e32 v107, v153
	v_mov_b32_e32 v108, 0
	v_mov_b32_e32 v109, v153
	v_mov_b32_e32 v110, v153
	v_mov_b32_e32 v111, v153
	v_mov_b32_e32 v112, 0
	v_mov_b32_e32 v113, v153
	v_mov_b32_e32 v114, v153
	v_mov_b32_e32 v115, v153
	v_mov_b32_e32 v116, 0
	v_mov_b32_e32 v117, v153
	v_mov_b32_e32 v118, v153
	v_mov_b32_e32 v119, v153
	v_mov_b32_e32 v144, 0
	v_mov_b32_e32 v145, v153
	v_mov_b32_e32 v146, v153
	v_mov_b32_e32 v147, v153
	v_mov_b32_e32 v148, 0
	v_mov_b32_e32 v149, v153
	v_mov_b32_e32 v150, v153
	v_mov_b32_e32 v151, v153
	s_waitcnt lgkmcnt(0)
	s_add_i32 s26, s25, 64
	s_min_u32 s12, s26, 0x3e0
	s_lshl_b32 s12, s12, 1
	v_lshl_add_u64 v[172:173], v[154:155], 0, s[12:13]
	v_lshl_add_u64 v[176:177], v[158:159], 0, s[12:13]
	v_lshl_add_u64 v[180:181], v[160:161], 0, s[12:13]
	v_lshl_add_u64 v[184:185], v[162:163], 0, s[12:13]
	v_lshl_add_u64 v[188:189], v[156:157], 0, s[12:13]
	v_lshl_add_u64 v[192:193], v[164:165], 0, s[12:13]

.LBB0_1737:
	global_load_dwordx4 v[172:175], v[172:173], off
	ds_read_b128 v[196:199], v171 offset:32768
	global_load_dwordx4 v[176:179], v[176:177], off
	ds_read_b128 v[200:203], v171 offset:33792
	global_load_dwordx4 v[180:183], v[180:181], off
	ds_read_b128 v[204:207], v171 offset:34816
	global_load_dwordx4 v[184:187], v[184:185], off
	ds_read_b128 v[208:211], v171 offset:35840
	global_load_dwordx4 v[188:191], v[188:189], off
	ds_read_b128 v[212:215], v169
	global_load_dwordx4 v[192:195], v[192:193], off
	ds_read_b128 v[216:219], v169 offset:1024
	ds_read_b128 v[222:225], v169 offset:2048
	ds_read_b128 v[226:229], v169 offset:3072
	ds_read_b128 v[230:233], v169 offset:4096
	ds_read_b128 v[234:237], v169 offset:5120
	ds_read_b128 v[238:241], v169 offset:6144
	ds_read_b128 v[242:245], v169 offset:7168
	s_setprio 1
	s_waitcnt lgkmcnt(7)
	v_mfma_f32_16x16x32_bf16 v[148:151], v[196:199], v[212:215], v[148:151]
	v_mfma_f32_16x16x32_bf16 v[144:147], v[200:203], v[212:215], v[144:147]
	v_mfma_f32_16x16x32_bf16 v[116:119], v[204:207], v[212:215], v[116:119]
	v_mfma_f32_16x16x32_bf16 v[112:115], v[208:211], v[212:215], v[112:115]
	s_waitcnt vmcnt(11)
	ds_write_b128 v152, v[120:123] offset:16384
	s_waitcnt lgkmcnt(7)
	v_mfma_f32_16x16x32_bf16 v[108:111], v[196:199], v[216:219], v[108:111]
	v_mfma_f32_16x16x32_bf16 v[104:107], v[200:203], v[216:219], v[104:107]
	v_mfma_f32_16x16x32_bf16 v[100:103], v[204:207], v[216:219], v[100:103]
	v_mfma_f32_16x16x32_bf16 v[96:99], v[208:211], v[216:219], v[96:99]
	s_waitcnt vmcnt(9)
	ds_write_b128 v152, v[124:127] offset:20480
	s_waitcnt lgkmcnt(7)
	v_mfma_f32_16x16x32_bf16 v[92:95], v[196:199], v[222:225], v[92:95]
	v_mfma_f32_16x16x32_bf16 v[88:91], v[200:203], v[222:225], v[88:91]
	v_mfma_f32_16x16x32_bf16 v[84:87], v[204:207], v[222:225], v[84:87]
	v_mfma_f32_16x16x32_bf16 v[80:83], v[208:211], v[222:225], v[80:83]
	s_waitcnt vmcnt(8)
	ds_write_b128 v152, v[128:131] offset:24576
	s_waitcnt lgkmcnt(7)
	v_mfma_f32_16x16x32_bf16 v[76:79], v[196:199], v[226:229], v[76:79]
	v_mfma_f32_16x16x32_bf16 v[72:75], v[200:203], v[226:229], v[72:75]
	v_mfma_f32_16x16x32_bf16 v[68:71], v[204:207], v[226:229], v[68:71]
	v_mfma_f32_16x16x32_bf16 v[64:67], v[208:211], v[226:229], v[64:67]
	s_waitcnt vmcnt(7)
	ds_write_b128 v152, v[136:139] offset:28672
	s_waitcnt lgkmcnt(7)
	v_mfma_f32_16x16x32_bf16 v[60:63], v[196:199], v[230:233], v[60:63]
	v_mfma_f32_16x16x32_bf16 v[56:59], v[200:203], v[230:233], v[56:59]
	v_mfma_f32_16x16x32_bf16 v[52:55], v[204:207], v[230:233], v[52:55]
	v_mfma_f32_16x16x32_bf16 v[48:51], v[208:211], v[230:233], v[48:51]
	s_waitcnt vmcnt(6)
	ds_write_b128 v152, v[140:143] offset:45056
	s_waitcnt lgkmcnt(7)
	v_mfma_f32_16x16x32_bf16 v[44:47], v[196:199], v[234:237], v[44:47]
	v_mfma_f32_16x16x32_bf16 v[40:43], v[200:203], v[234:237], v[40:43]
	v_mfma_f32_16x16x32_bf16 v[36:39], v[204:207], v[234:237], v[36:39]
	v_mfma_f32_16x16x32_bf16 v[32:35], v[208:211], v[234:237], v[32:35]
	ds_write_b128 v152, v[132:135] offset:40960
	s_waitcnt lgkmcnt(7)
	v_mfma_f32_16x16x32_bf16 v[28:31], v[196:199], v[238:241], v[28:31]
	v_mfma_f32_16x16x32_bf16 v[24:27], v[200:203], v[238:241], v[24:27]
	v_mfma_f32_16x16x32_bf16 v[20:23], v[204:207], v[238:241], v[20:23]
	v_mfma_f32_16x16x32_bf16 v[16:19], v[208:211], v[238:241], v[16:19]
	s_waitcnt lgkmcnt(6)
	v_mfma_f32_16x16x32_bf16 v[12:15], v[196:199], v[242:245], v[12:15]
	v_mfma_f32_16x16x32_bf16 v[8:11], v[200:203], v[242:245], v[8:11]
	v_mfma_f32_16x16x32_bf16 v[4:7], v[204:207], v[242:245], v[4:7]
	v_mfma_f32_16x16x32_bf16 v[0:3], v[208:211], v[242:245], v[0:3]
	s_setprio 0
	s_min_u32 s12, s25, 0x380
	s_lshl_b32 s12, s12, 1
	s_mov_b32 s29, s13
	s_add_i32 s28, s12, 0xc0
	v_lshl_add_u64 v[120:121], v[154:155], 0, s[12:13]
	v_lshl_add_u64 v[124:125], v[156:157], 0, s[12:13]
	v_lshl_add_u64 v[126:127], v[158:159], 0, s[28:29]
	v_lshl_add_u64 v[128:129], v[160:161], 0, s[28:29]
	v_lshl_add_u64 v[136:137], v[162:163], 0, s[28:29]
	v_lshl_add_u64 v[140:141], v[164:165], 0, s[28:29]
	s_waitcnt lgkmcnt(0)
	s_barrier
	global_load_dwordx4 v[120:123], v[120:121], off offset:192
	ds_read_b128 v[196:199], v168 offset:40960
	global_load_dwordx4 v[132:135], v[124:125], off offset:192
	ds_read_b128 v[200:203], v168 offset:41984
	global_load_dwordx4 v[124:127], v[126:127], off
	ds_read_b128 v[204:207], v168 offset:43008
	global_load_dwordx4 v[128:131], v[128:129], off
	ds_read_b128 v[208:211], v168 offset:44032
	global_load_dwordx4 v[136:139], v[136:137], off
	ds_read_b128 v[212:215], v170
	global_load_dwordx4 v[140:143], v[140:141], off
	ds_read_b128 v[216:219], v170 offset:1024
	ds_read_b128 v[222:225], v170 offset:2048
	ds_read_b128 v[226:229], v170 offset:3072
	ds_read_b128 v[230:233], v170 offset:4096
	ds_read_b128 v[234:237], v170 offset:5120
	ds_read_b128 v[238:241], v170 offset:6144
	ds_read_b128 v[242:245], v170 offset:7168
	s_setprio 1
	s_waitcnt lgkmcnt(7)
	v_mfma_f32_16x16x32_bf16 v[148:151], v[196:199], v[212:215], v[148:151]
	v_mfma_f32_16x16x32_bf16 v[144:147], v[200:203], v[212:215], v[144:147]
	v_mfma_f32_16x16x32_bf16 v[116:119], v[204:207], v[212:215], v[116:119]
	v_mfma_f32_16x16x32_bf16 v[112:115], v[208:211], v[212:215], v[112:115]
	s_waitcnt vmcnt(11)
	ds_write_b128 v152, v[172:175]
	s_waitcnt lgkmcnt(7)
	v_mfma_f32_16x16x32_bf16 v[108:111], v[196:199], v[216:219], v[108:111]
	v_mfma_f32_16x16x32_bf16 v[104:107], v[200:203], v[216:219], v[104:107]
	v_mfma_f32_16x16x32_bf16 v[100:103], v[204:207], v[216:219], v[100:103]
	v_mfma_f32_16x16x32_bf16 v[96:99], v[208:211], v[216:219], v[96:99]
	s_waitcnt vmcnt(10)
	ds_write_b128 v152, v[176:179] offset:4096
	s_waitcnt lgkmcnt(7)
	v_mfma_f32_16x16x32_bf16 v[92:95], v[196:199], v[222:225], v[92:95]
	v_mfma_f32_16x16x32_bf16 v[88:91], v[200:203], v[222:225], v[88:91]
	v_mfma_f32_16x16x32_bf16 v[84:87], v[204:207], v[222:225], v[84:87]
	v_mfma_f32_16x16x32_bf16 v[80:83], v[208:211], v[222:225], v[80:83]
	s_waitcnt vmcnt(9)
	ds_write_b128 v152, v[180:183] offset:8192
	s_waitcnt lgkmcnt(7)
	v_mfma_f32_16x16x32_bf16 v[76:79], v[196:199], v[226:229], v[76:79]
	v_mfma_f32_16x16x32_bf16 v[72:75], v[200:203], v[226:229], v[72:75]
	v_mfma_f32_16x16x32_bf16 v[68:71], v[204:207], v[226:229], v[68:71]
	v_mfma_f32_16x16x32_bf16 v[64:67], v[208:211], v[226:229], v[64:67]
	s_waitcnt vmcnt(8)
	ds_write_b128 v152, v[184:187] offset:12288
	s_waitcnt lgkmcnt(7)
	v_mfma_f32_16x16x32_bf16 v[60:63], v[196:199], v[230:233], v[60:63]
	v_mfma_f32_16x16x32_bf16 v[56:59], v[200:203], v[230:233], v[56:59]
	v_mfma_f32_16x16x32_bf16 v[52:55], v[204:207], v[230:233], v[52:55]
	v_mfma_f32_16x16x32_bf16 v[48:51], v[208:211], v[230:233], v[48:51]
	s_waitcnt vmcnt(7)
	ds_write_b128 v152, v[188:191] offset:32768
	s_waitcnt lgkmcnt(7)
	v_mfma_f32_16x16x32_bf16 v[44:47], v[196:199], v[234:237], v[44:47]
	v_mfma_f32_16x16x32_bf16 v[40:43], v[200:203], v[234:237], v[40:43]
	v_mfma_f32_16x16x32_bf16 v[36:39], v[204:207], v[234:237], v[36:39]
	v_mfma_f32_16x16x32_bf16 v[32:35], v[208:211], v[234:237], v[32:35]
	s_waitcnt vmcnt(6)
	ds_write_b128 v152, v[192:195] offset:36864
	s_waitcnt lgkmcnt(7)
	v_mfma_f32_16x16x32_bf16 v[28:31], v[196:199], v[238:241], v[28:31]
	v_mfma_f32_16x16x32_bf16 v[24:27], v[200:203], v[238:241], v[24:27]
	v_mfma_f32_16x16x32_bf16 v[20:23], v[204:207], v[238:241], v[20:23]
	v_mfma_f32_16x16x32_bf16 v[16:19], v[208:211], v[238:241], v[16:19]
	s_waitcnt lgkmcnt(6)
	v_mfma_f32_16x16x32_bf16 v[12:15], v[196:199], v[242:245], v[12:15]
	v_mfma_f32_16x16x32_bf16 v[8:11], v[200:203], v[242:245], v[8:11]
	v_mfma_f32_16x16x32_bf16 v[4:7], v[204:207], v[242:245], v[4:7]
	v_mfma_f32_16x16x32_bf16 v[0:3], v[208:211], v[242:245], v[0:3]
	s_setprio 0
	s_add_i32 s21, s21, 2
	s_mov_b32 s25, s26
	s_add_i32 s26, s25, 64
	s_min_u32 s12, s26, 0x3e0
	s_lshl_b32 s12, s12, 1
	v_lshl_add_u64 v[172:173], v[154:155], 0, s[12:13]
	v_lshl_add_u64 v[176:177], v[158:159], 0, s[12:13]
	v_lshl_add_u64 v[180:181], v[160:161], 0, s[12:13]
	v_lshl_add_u64 v[184:185], v[162:163], 0, s[12:13]
	v_lshl_add_u64 v[188:189], v[156:157], 0, s[12:13]
	v_lshl_add_u64 v[192:193], v[164:165], 0, s[12:13]
	s_cmp_lt_u32 s21, 30
	s_waitcnt lgkmcnt(0)
	s_cbranch_scc1 .Lrot_0
	s_barrier
	s_waitcnt vmcnt(5)
	v_mov_b32_e32 v120, v220
	s_nop 0
	v_and_b32_e32 v122, 0xffffff80, v120
	v_add_u32_e32 v122, s20, v122
	v_and_b32_e32 v121, 64, v120
	v_and_or_b32 v122, v120, 15, v122
	v_lshrrev_b32_e32 v120, 2, v120
	v_and_b32_e32 v120, 12, v120
	v_or3_b32 v120, v121, v120, s24
	v_ashrrev_i32_e32 v121, 31, v120
	v_ashrrev_i32_e32 v123, 31, v122
	v_lshl_add_u64 v[120:121], v[120:121], 1, s[10:11]
	s_waitcnt vmcnt(3)
	v_lshl_add_u64 v[124:125], v[122:123], 2, s[0:1]
	v_lshlrev_b64 v[126:127], 12, v[122:123]
	v_lshl_add_u64 v[162:163], v[120:121], 0, v[126:127]
	global_load_dword v152, v[124:125], off
	global_load_dwordx2 v[168:169], v[162:163], off
	global_load_dwordx2 v[170:171], v[162:163], off offset:32
	global_load_dwordx2 v[172:173], v[162:163], off offset:64
	v_or_b32_e32 v124, 16, v122
	v_ashrrev_i32_e32 v125, 31, v124
	v_lshl_add_u64 v[126:127], v[124:125], 2, s[0:1]
	v_lshlrev_b64 v[124:125], 12, v[124:125]
	s_waitcnt vmcnt(4)
	v_lshl_add_u64 v[142:143], v[120:121], 0, v[124:125]
	v_or_b32_e32 v124, 32, v122
	v_ashrrev_i32_e32 v125, 31, v124
	global_load_dwordx2 v[174:175], v[162:163], off offset:96
	global_load_dword v176, v[126:127], off
	global_load_dwordx2 v[164:165], v[142:143], off
	global_load_dwordx2 v[160:161], v[142:143], off offset:32
	v_lshl_add_u64 v[126:127], v[124:125], 2, s[0:1]
	v_lshlrev_b64 v[124:125], 12, v[124:125]
	v_lshl_add_u64 v[132:133], v[120:121], 0, v[124:125]
	v_or_b32_e32 v124, 48, v122
	v_ashrrev_i32_e32 v125, 31, v124
	global_load_dwordx2 v[158:159], v[142:143], off offset:64
	global_load_dwordx2 v[156:157], v[142:143], off offset:96
	global_load_dword v177, v[126:127], off
	global_load_dwordx2 v[154:155], v[132:133], off
	v_lshl_add_u64 v[126:127], v[124:125], 2, s[0:1]
	v_lshlrev_b64 v[124:125], 12, v[124:125]
	v_lshl_add_u64 v[124:125], v[120:121], 0, v[124:125]
	global_load_dwordx2 v[140:141], v[132:133], off offset:32
	global_load_dwordx2 v[138:139], v[132:133], off offset:64
	global_load_dwordx2 v[136:137], v[132:133], off offset:96
	global_load_dword v123, v[126:127], off
	global_load_dwordx2 v[134:135], v[124:125], off
	global_load_dwordx2 v[130:131], v[124:125], off offset:32
	global_load_dwordx2 v[128:129], v[124:125], off offset:64
	s_nop 0
	global_load_dwordx2 v[126:127], v[124:125], off offset:96
	s_waitcnt vmcnt(19)
	v_fmamk_f32 v152, v152, 0x3a800000, v167
	v_mul_f32_e32 v178, 0x4b800000, v152
	v_cmp_gt_f32_e32 vcc, s22, v152
	s_nop 1
	v_cndmask_b32_e32 v152, v152, v178, vcc
	v_rsq_f32_e32 v152, v152
	s_waitcnt vmcnt(18)
	v_lshlrev_b32_e32 v178, 16, v168
	v_and_b32_e32 v168, 0xffff0000, v168
	v_mul_f32_e32 v179, 0x45800000, v152
	v_cndmask_b32_e32 v152, v152, v179, vcc
	v_mul_f32_e32 v148, v148, v152
	v_mul_f32_e32 v180, 0xbfb8aa3b, v148
	v_exp_f32_e32 v180, v180
	v_mul_f32_e32 v149, v149, v152
	v_mul_f32_e32 v181, 0xbfb8aa3b, v149
	v_exp_f32_e32 v181, v181
	v_add_f32_e32 v180, 1.0, v180
	v_rcp_f32_e32 v180, v180
	v_mul_f32_e32 v150, v150, v152
	v_mul_f32_e32 v151, v151, v152
	v_lshlrev_b32_e32 v179, 16, v169
	v_mul_f32_e32 v148, v148, v180
	v_mul_f32_e32 v148, v148, v178
	v_add_f32_e32 v178, 1.0, v181
	v_mul_f32_e32 v180, 0xbfb8aa3b, v150
	v_mul_f32_e32 v181, 0xbfb8aa3b, v151
	v_rcp_f32_e32 v178, v178
	v_exp_f32_e32 v180, v180
	v_exp_f32_e32 v181, v181
	v_and_b32_e32 v169, 0xffff0000, v169
	v_mul_f32_e32 v149, v149, v178
	v_add_f32_e32 v178, 1.0, v180
	v_add_f32_e32 v180, 1.0, v181
	v_rcp_f32_e32 v180, v180
	v_rcp_f32_e32 v178, v178
	v_mul_f32_e32 v149, v149, v168
	v_mul_f32_e32 v144, v144, v152
	v_mul_f32_e32 v151, v151, v180
	v_mul_f32_e32 v150, v150, v178
	v_mul_f32_e32 v151, v151, v169
	v_mul_f32_e32 v150, v150, v179
	v_cvt_pk_bf16_f32 v148, v148, v149
	v_cvt_pk_bf16_f32 v149, v150, v151
	v_mul_f32_e32 v151, 0xbfb8aa3b, v144
	v_exp_f32_e32 v151, v151
	v_mul_f32_e32 v145, v145, v152
	v_mul_f32_e32 v169, 0xbfb8aa3b, v145
	v_exp_f32_e32 v169, v169
	v_add_f32_e32 v151, 1.0, v151
	v_rcp_f32_e32 v151, v151
	global_store_dwordx2 v[162:163], v[148:149], off
	s_waitcnt vmcnt(18)
	v_lshlrev_b32_e32 v148, 16, v170
	v_mul_f32_e32 v146, v146, v152
	v_mul_f32_e32 v147, v147, v152
	v_mul_f32_e32 v144, v144, v151
	v_mul_f32_e32 v144, v144, v148
	v_add_f32_e32 v148, 1.0, v169
	v_mul_f32_e32 v151, 0xbfb8aa3b, v146
	v_mul_f32_e32 v169, 0xbfb8aa3b, v147
	v_rcp_f32_e32 v148, v148
	v_exp_f32_e32 v151, v151
	v_exp_f32_e32 v169, v169
	v_and_b32_e32 v149, 0xffff0000, v170
	v_mul_f32_e32 v145, v145, v148
	v_add_f32_e32 v148, 1.0, v151
	v_add_f32_e32 v151, 1.0, v169
	v_rcp_f32_e32 v151, v151
	v_rcp_f32_e32 v148, v148
	v_and_b32_e32 v168, 0xffff0000, v171
	v_lshlrev_b32_e32 v150, 16, v171
	v_mul_f32_e32 v147, v147, v151
	v_mul_f32_e32 v145, v145, v149
	v_mul_f32_e32 v146, v146, v148
	v_mul_f32_e32 v147, v147, v168
	v_mul_f32_e32 v116, v116, v152
	v_mul_f32_e32 v146, v146, v150
	v_cvt_pk_bf16_f32 v144, v144, v145
	v_cvt_pk_bf16_f32 v145, v146, v147
	v_mul_f32_e32 v147, 0xbfb8aa3b, v116
	v_exp_f32_e32 v147, v147
	v_mul_f32_e32 v117, v117, v152
	v_mul_f32_e32 v149, 0xbfb8aa3b, v117
	v_exp_f32_e32 v149, v149
	v_add_f32_e32 v147, 1.0, v147
	v_rcp_f32_e32 v147, v147
	global_store_dwordx2 v[162:163], v[144:145], off offset:32
	s_waitcnt vmcnt(18)
	v_lshlrev_b32_e32 v144, 16, v172
	v_mul_f32_e32 v118, v118, v152
	v_mul_f32_e32 v119, v119, v152
	v_mul_f32_e32 v116, v116, v147
	v_mul_f32_e32 v116, v116, v144
	v_add_f32_e32 v144, 1.0, v149
	v_mul_f32_e32 v147, 0xbfb8aa3b, v118
	v_mul_f32_e32 v149, 0xbfb8aa3b, v119
	v_rcp_f32_e32 v144, v144
	v_exp_f32_e32 v147, v147
	v_exp_f32_e32 v149, v149
	v_and_b32_e32 v145, 0xffff0000, v172
	v_mul_f32_e32 v117, v117, v144
	v_add_f32_e32 v144, 1.0, v147
	v_add_f32_e32 v147, 1.0, v149
	v_rcp_f32_e32 v147, v147
	v_rcp_f32_e32 v144, v144
	v_and_b32_e32 v148, 0xffff0000, v173
	v_lshlrev_b32_e32 v146, 16, v173
	v_mul_f32_e32 v119, v119, v147
	v_mul_f32_e32 v117, v117, v145
	v_mul_f32_e32 v118, v118, v144
	v_mul_f32_e32 v119, v119, v148
	v_mul_f32_e32 v112, v112, v152
	v_mul_f32_e32 v118, v118, v146
	v_cvt_pk_bf16_f32 v116, v116, v117
	v_cvt_pk_bf16_f32 v117, v118, v119
	v_mul_f32_e32 v119, 0xbfb8aa3b, v112
	v_exp_f32_e32 v119, v119
	v_mul_f32_e32 v113, v113, v152
	v_mul_f32_e32 v145, 0xbfb8aa3b, v113
	v_exp_f32_e32 v145, v145
	v_add_f32_e32 v119, 1.0, v119
	v_rcp_f32_e32 v119, v119
	global_store_dwordx2 v[162:163], v[116:117], off offset:64
	s_waitcnt vmcnt(18)
	v_lshlrev_b32_e32 v116, 16, v174
	v_mul_f32_e32 v114, v114, v152
	v_mul_f32_e32 v112, v112, v119
	v_mul_f32_e32 v112, v112, v116
	v_add_f32_e32 v116, 1.0, v145
	v_mul_f32_e32 v119, 0xbfb8aa3b, v114
	v_rcp_f32_e32 v116, v116
	v_exp_f32_e32 v119, v119
	v_mul_f32_e32 v115, v115, v152
	v_mul_f32_e32 v145, 0xbfb8aa3b, v115
	v_mul_f32_e32 v113, v113, v116
	v_add_f32_e32 v116, 1.0, v119
	v_rcp_f32_e32 v116, v116
	v_exp_f32_e32 v145, v145
	v_and_b32_e32 v117, 0xffff0000, v174
	v_mul_f32_e32 v113, v113, v117
	v_mul_f32_e32 v114, v114, v116
	s_waitcnt vmcnt(17)
	v_fmamk_f32 v116, v176, 0x3a800000, v167
	v_add_f32_e32 v119, 1.0, v145
	v_mul_f32_e32 v117, 0x4b800000, v116
	v_cmp_gt_f32_e32 vcc, s22, v116
	v_rcp_f32_e32 v119, v119
	v_lshlrev_b32_e32 v118, 16, v175
	v_cndmask_b32_e32 v116, v116, v117, vcc
	v_rsq_f32_e32 v116, v116
	v_and_b32_e32 v144, 0xffff0000, v175
	v_mul_f32_e32 v115, v115, v119
	v_cvt_pk_bf16_f32 v112, v112, v113
	v_mul_f32_e32 v114, v114, v118
	v_mul_f32_e32 v115, v115, v144
	v_cvt_pk_bf16_f32 v113, v114, v115
	global_store_dwordx2 v[162:163], v[112:113], off offset:96
	v_mul_f32_e32 v112, 0x45800000, v116
	v_cndmask_b32_e32 v112, v116, v112, vcc
	v_mul_f32_e32 v108, v108, v112
	v_mul_f32_e32 v116, 0xbfb8aa3b, v108
	v_exp_f32_e32 v116, v116
	v_mul_f32_e32 v109, v109, v112
	v_mul_f32_e32 v118, 0xbfb8aa3b, v109
	v_exp_f32_e32 v118, v118
	v_add_f32_e32 v116, 1.0, v116
	v_rcp_f32_e32 v116, v116
	s_waitcnt vmcnt(17)
	v_lshlrev_b32_e32 v113, 16, v164
	v_mul_f32_e32 v110, v110, v112
	v_mul_f32_e32 v111, v111, v112
	v_mul_f32_e32 v108, v108, v116
	v_mul_f32_e32 v108, v108, v113
	v_add_f32_e32 v113, 1.0, v118
	v_mul_f32_e32 v116, 0xbfb8aa3b, v110
	v_mul_f32_e32 v118, 0xbfb8aa3b, v111
	v_rcp_f32_e32 v113, v113
	v_exp_f32_e32 v116, v116
	v_exp_f32_e32 v118, v118
	v_and_b32_e32 v114, 0xffff0000, v164
	v_mul_f32_e32 v109, v109, v113
	v_add_f32_e32 v113, 1.0, v116
	v_add_f32_e32 v116, 1.0, v118
	v_rcp_f32_e32 v116, v116
	v_rcp_f32_e32 v113, v113
	v_and_b32_e32 v117, 0xffff0000, v165
	v_lshlrev_b32_e32 v115, 16, v165
	v_mul_f32_e32 v111, v111, v116
	v_mul_f32_e32 v109, v109, v114
	v_mul_f32_e32 v110, v110, v113
	v_mul_f32_e32 v111, v111, v117
	v_mul_f32_e32 v104, v104, v112
	v_mul_f32_e32 v110, v110, v115
	v_cvt_pk_bf16_f32 v108, v108, v109
	v_cvt_pk_bf16_f32 v109, v110, v111
	v_mul_f32_e32 v111, 0xbfb8aa3b, v104
	v_exp_f32_e32 v111, v111
	v_mul_f32_e32 v105, v105, v112
	v_mul_f32_e32 v114, 0xbfb8aa3b, v105
	v_exp_f32_e32 v114, v114
	v_add_f32_e32 v111, 1.0, v111
	v_rcp_f32_e32 v111, v111
	global_store_dwordx2 v[142:143], v[108:109], off
	s_waitcnt vmcnt(17)
	v_lshlrev_b32_e32 v108, 16, v160
	v_mul_f32_e32 v106, v106, v112
	v_mul_f32_e32 v107, v107, v112
	v_mul_f32_e32 v104, v104, v111
	v_mul_f32_e32 v104, v104, v108
	v_add_f32_e32 v108, 1.0, v114
	v_mul_f32_e32 v111, 0xbfb8aa3b, v106
	v_mul_f32_e32 v114, 0xbfb8aa3b, v107
	v_rcp_f32_e32 v108, v108
	v_exp_f32_e32 v111, v111
	v_exp_f32_e32 v114, v114
	v_and_b32_e32 v109, 0xffff0000, v160
	v_mul_f32_e32 v105, v105, v108
	v_add_f32_e32 v108, 1.0, v111
	v_add_f32_e32 v111, 1.0, v114
	v_rcp_f32_e32 v111, v111
	v_rcp_f32_e32 v108, v108
	v_and_b32_e32 v113, 0xffff0000, v161
	v_lshlrev_b32_e32 v110, 16, v161
	v_mul_f32_e32 v107, v107, v111
	v_mul_f32_e32 v105, v105, v109
	v_mul_f32_e32 v106, v106, v108
	v_mul_f32_e32 v107, v107, v113
	v_mul_f32_e32 v100, v100, v112
	v_mul_f32_e32 v106, v106, v110
	v_cvt_pk_bf16_f32 v104, v104, v105
	v_cvt_pk_bf16_f32 v105, v106, v107
	v_mul_f32_e32 v107, 0xbfb8aa3b, v100
	v_exp_f32_e32 v107, v107
	v_mul_f32_e32 v101, v101, v112
	v_mul_f32_e32 v109, 0xbfb8aa3b, v101
	v_exp_f32_e32 v109, v109
	v_add_f32_e32 v107, 1.0, v107
	v_rcp_f32_e32 v107, v107
	global_store_dwordx2 v[142:143], v[104:105], off offset:32
	s_waitcnt vmcnt(17)
	v_lshlrev_b32_e32 v104, 16, v158
	v_mul_f32_e32 v102, v102, v112
	v_mul_f32_e32 v103, v103, v112
	v_mul_f32_e32 v100, v100, v107
	v_mul_f32_e32 v100, v100, v104
	v_add_f32_e32 v104, 1.0, v109
	v_mul_f32_e32 v107, 0xbfb8aa3b, v102
	v_mul_f32_e32 v109, 0xbfb8aa3b, v103
	v_rcp_f32_e32 v104, v104
	v_exp_f32_e32 v107, v107
	v_exp_f32_e32 v109, v109
	v_and_b32_e32 v105, 0xffff0000, v158
	v_mul_f32_e32 v101, v101, v104
	v_add_f32_e32 v104, 1.0, v107
	v_add_f32_e32 v107, 1.0, v109
	v_rcp_f32_e32 v107, v107
	v_rcp_f32_e32 v104, v104
	v_and_b32_e32 v108, 0xffff0000, v159
	v_lshlrev_b32_e32 v106, 16, v159
	v_mul_f32_e32 v103, v103, v107
	v_mul_f32_e32 v101, v101, v105
	v_mul_f32_e32 v102, v102, v104
	v_mul_f32_e32 v103, v103, v108
	v_mul_f32_e32 v96, v96, v112
	v_mul_f32_e32 v102, v102, v106
	v_cvt_pk_bf16_f32 v100, v100, v101
	v_cvt_pk_bf16_f32 v101, v102, v103
	v_mul_f32_e32 v103, 0xbfb8aa3b, v96
	v_exp_f32_e32 v103, v103
	v_mul_f32_e32 v97, v97, v112
	v_mul_f32_e32 v105, 0xbfb8aa3b, v97
	v_exp_f32_e32 v105, v105
	v_add_f32_e32 v103, 1.0, v103
	v_rcp_f32_e32 v103, v103
	global_store_dwordx2 v[142:143], v[100:101], off offset:64
	s_waitcnt vmcnt(17)
	v_lshlrev_b32_e32 v100, 16, v156
	v_mul_f32_e32 v98, v98, v112
	v_mul_f32_e32 v96, v96, v103
	v_mul_f32_e32 v96, v96, v100
	v_add_f32_e32 v100, 1.0, v105
	v_mul_f32_e32 v103, 0xbfb8aa3b, v98
	v_rcp_f32_e32 v100, v100
	v_exp_f32_e32 v103, v103
	v_mul_f32_e32 v99, v99, v112
	v_mul_f32_e32 v105, 0xbfb8aa3b, v99
	v_mul_f32_e32 v97, v97, v100
	v_add_f32_e32 v100, 1.0, v103
	v_rcp_f32_e32 v100, v100
	v_exp_f32_e32 v105, v105
	v_and_b32_e32 v101, 0xffff0000, v156
	v_mul_f32_e32 v97, v97, v101
	v_mul_f32_e32 v98, v98, v100
	s_waitcnt vmcnt(16)
	v_fmamk_f32 v100, v177, 0x3a800000, v167
	v_add_f32_e32 v103, 1.0, v105
	v_mul_f32_e32 v101, 0x4b800000, v100
	v_cmp_gt_f32_e32 vcc, s22, v100
	v_rcp_f32_e32 v103, v103
	v_lshlrev_b32_e32 v102, 16, v157
	v_cndmask_b32_e32 v100, v100, v101, vcc
	v_rsq_f32_e32 v100, v100
	v_and_b32_e32 v104, 0xffff0000, v157
	v_mul_f32_e32 v99, v99, v103
	v_cvt_pk_bf16_f32 v96, v96, v97
	v_mul_f32_e32 v98, v98, v102
	v_mul_f32_e32 v99, v99, v104
	v_cvt_pk_bf16_f32 v97, v98, v99
	global_store_dwordx2 v[142:143], v[96:97], off offset:96
	v_mul_f32_e32 v96, 0x45800000, v100
	v_cndmask_b32_e32 v96, v100, v96, vcc
	v_mul_f32_e32 v92, v92, v96
	v_mul_f32_e32 v100, 0xbfb8aa3b, v92
	v_exp_f32_e32 v100, v100
	v_mul_f32_e32 v93, v93, v96
	v_mul_f32_e32 v102, 0xbfb8aa3b, v93
	v_exp_f32_e32 v102, v102
	v_add_f32_e32 v100, 1.0, v100
	v_rcp_f32_e32 v100, v100
	s_waitcnt vmcnt(16)
	v_lshlrev_b32_e32 v97, 16, v154
	v_mul_f32_e32 v94, v94, v96
	v_mul_f32_e32 v95, v95, v96
	v_mul_f32_e32 v92, v92, v100
	v_mul_f32_e32 v92, v92, v97
	v_add_f32_e32 v97, 1.0, v102
	v_mul_f32_e32 v100, 0xbfb8aa3b, v94
	v_mul_f32_e32 v102, 0xbfb8aa3b, v95
	v_rcp_f32_e32 v97, v97
	v_exp_f32_e32 v100, v100
	v_exp_f32_e32 v102, v102
	v_and_b32_e32 v98, 0xffff0000, v154
	v_mul_f32_e32 v93, v93, v97
	v_add_f32_e32 v97, 1.0, v100
	v_add_f32_e32 v100, 1.0, v102
	v_rcp_f32_e32 v100, v100
	v_rcp_f32_e32 v97, v97
	v_and_b32_e32 v101, 0xffff0000, v155
	v_lshlrev_b32_e32 v99, 16, v155
	v_mul_f32_e32 v95, v95, v100
	v_mul_f32_e32 v93, v93, v98
	v_mul_f32_e32 v94, v94, v97
	v_mul_f32_e32 v95, v95, v101
	v_mul_f32_e32 v88, v88, v96
	v_mul_f32_e32 v94, v94, v99
	v_cvt_pk_bf16_f32 v92, v92, v93
	v_cvt_pk_bf16_f32 v93, v94, v95
	v_mul_f32_e32 v95, 0xbfb8aa3b, v88
	v_exp_f32_e32 v95, v95
	v_mul_f32_e32 v89, v89, v96
	v_mul_f32_e32 v98, 0xbfb8aa3b, v89
	v_exp_f32_e32 v98, v98
	v_add_f32_e32 v95, 1.0, v95
	v_rcp_f32_e32 v95, v95
	global_store_dwordx2 v[132:133], v[92:93], off
	s_waitcnt vmcnt(16)
	v_lshlrev_b32_e32 v92, 16, v140
	v_mul_f32_e32 v90, v90, v96
	v_mul_f32_e32 v91, v91, v96
	v_mul_f32_e32 v88, v88, v95
	v_mul_f32_e32 v88, v88, v92
	v_add_f32_e32 v92, 1.0, v98
	v_mul_f32_e32 v95, 0xbfb8aa3b, v90
	v_mul_f32_e32 v98, 0xbfb8aa3b, v91
	v_rcp_f32_e32 v92, v92
	v_exp_f32_e32 v95, v95
	v_exp_f32_e32 v98, v98
	v_and_b32_e32 v93, 0xffff0000, v140
	v_mul_f32_e32 v89, v89, v92
	v_add_f32_e32 v92, 1.0, v95
	v_add_f32_e32 v95, 1.0, v98
	v_rcp_f32_e32 v95, v95
	v_rcp_f32_e32 v92, v92
	v_and_b32_e32 v97, 0xffff0000, v141
	v_lshlrev_b32_e32 v94, 16, v141
	v_mul_f32_e32 v91, v91, v95
	v_mul_f32_e32 v89, v89, v93
	v_mul_f32_e32 v90, v90, v92
	v_mul_f32_e32 v91, v91, v97
	v_mul_f32_e32 v84, v84, v96
	v_mul_f32_e32 v90, v90, v94
	v_cvt_pk_bf16_f32 v88, v88, v89
	v_cvt_pk_bf16_f32 v89, v90, v91
	v_mul_f32_e32 v91, 0xbfb8aa3b, v84
	v_exp_f32_e32 v91, v91
	v_mul_f32_e32 v85, v85, v96
	v_mul_f32_e32 v93, 0xbfb8aa3b, v85
	v_exp_f32_e32 v93, v93
	v_add_f32_e32 v91, 1.0, v91
	v_rcp_f32_e32 v91, v91
	global_store_dwordx2 v[132:133], v[88:89], off offset:32
	s_waitcnt vmcnt(16)
	v_lshlrev_b32_e32 v88, 16, v138
	v_mul_f32_e32 v86, v86, v96
	v_mul_f32_e32 v87, v87, v96
	v_mul_f32_e32 v84, v84, v91
	v_mul_f32_e32 v84, v84, v88
	v_add_f32_e32 v88, 1.0, v93
	v_mul_f32_e32 v91, 0xbfb8aa3b, v86
	v_mul_f32_e32 v93, 0xbfb8aa3b, v87
	v_rcp_f32_e32 v88, v88
	v_exp_f32_e32 v91, v91
	v_exp_f32_e32 v93, v93
	v_and_b32_e32 v89, 0xffff0000, v138
	v_mul_f32_e32 v85, v85, v88
	v_add_f32_e32 v88, 1.0, v91
	v_add_f32_e32 v91, 1.0, v93
	v_rcp_f32_e32 v91, v91
	v_rcp_f32_e32 v88, v88
	v_and_b32_e32 v92, 0xffff0000, v139
	v_lshlrev_b32_e32 v90, 16, v139
	v_mul_f32_e32 v87, v87, v91
	v_mul_f32_e32 v85, v85, v89
	v_mul_f32_e32 v86, v86, v88
	v_mul_f32_e32 v87, v87, v92
	v_mul_f32_e32 v80, v80, v96
	v_mul_f32_e32 v86, v86, v90
	v_cvt_pk_bf16_f32 v84, v84, v85
	v_cvt_pk_bf16_f32 v85, v86, v87
	v_mul_f32_e32 v87, 0xbfb8aa3b, v80
	v_exp_f32_e32 v87, v87
	v_mul_f32_e32 v81, v81, v96
	v_mul_f32_e32 v89, 0xbfb8aa3b, v81
	v_exp_f32_e32 v89, v89
	v_add_f32_e32 v87, 1.0, v87
	v_rcp_f32_e32 v87, v87
	global_store_dwordx2 v[132:133], v[84:85], off offset:64
	s_waitcnt vmcnt(16)
	v_lshlrev_b32_e32 v84, 16, v136
	v_mul_f32_e32 v82, v82, v96
	v_mul_f32_e32 v80, v80, v87
	v_mul_f32_e32 v80, v80, v84
	v_add_f32_e32 v84, 1.0, v89
	v_mul_f32_e32 v87, 0xbfb8aa3b, v82
	v_rcp_f32_e32 v84, v84
	v_exp_f32_e32 v87, v87
	v_mul_f32_e32 v83, v83, v96
	v_mul_f32_e32 v89, 0xbfb8aa3b, v83
	v_mul_f32_e32 v81, v81, v84
	v_add_f32_e32 v84, 1.0, v87
	v_rcp_f32_e32 v84, v84
	v_exp_f32_e32 v89, v89
	v_and_b32_e32 v85, 0xffff0000, v136
	v_mul_f32_e32 v81, v81, v85
	v_mul_f32_e32 v82, v82, v84
	s_waitcnt vmcnt(15)
	v_fmamk_f32 v84, v123, 0x3a800000, v167
	v_add_f32_e32 v87, 1.0, v89
	v_mul_f32_e32 v85, 0x4b800000, v84
	v_cmp_gt_f32_e32 vcc, s22, v84
	v_rcp_f32_e32 v87, v87
	v_lshlrev_b32_e32 v86, 16, v137
	v_cndmask_b32_e32 v84, v84, v85, vcc
	v_rsq_f32_e32 v84, v84
	v_and_b32_e32 v88, 0xffff0000, v137
	v_mul_f32_e32 v83, v83, v87
	v_cvt_pk_bf16_f32 v80, v80, v81
	v_mul_f32_e32 v82, v82, v86
	v_mul_f32_e32 v83, v83, v88
	v_cvt_pk_bf16_f32 v81, v82, v83
	global_store_dwordx2 v[132:133], v[80:81], off offset:96
	v_mul_f32_e32 v80, 0x45800000, v84
	v_cndmask_b32_e32 v80, v84, v80, vcc
	v_mul_f32_e32 v76, v76, v80
	v_mul_f32_e32 v84, 0xbfb8aa3b, v76
	v_exp_f32_e32 v84, v84
	v_mul_f32_e32 v77, v77, v80
	v_mul_f32_e32 v86, 0xbfb8aa3b, v77
	v_exp_f32_e32 v86, v86
	v_add_f32_e32 v84, 1.0, v84
	v_rcp_f32_e32 v84, v84
	s_waitcnt vmcnt(15)
	v_lshlrev_b32_e32 v81, 16, v134
	v_mul_f32_e32 v78, v78, v80
	v_mul_f32_e32 v79, v79, v80
	v_mul_f32_e32 v76, v76, v84
	v_mul_f32_e32 v76, v76, v81
	v_add_f32_e32 v81, 1.0, v86
	v_mul_f32_e32 v84, 0xbfb8aa3b, v78
	v_mul_f32_e32 v86, 0xbfb8aa3b, v79
	v_rcp_f32_e32 v81, v81
	v_exp_f32_e32 v84, v84
	v_exp_f32_e32 v86, v86
	v_and_b32_e32 v82, 0xffff0000, v134
	v_mul_f32_e32 v77, v77, v81
	v_add_f32_e32 v81, 1.0, v84
	v_add_f32_e32 v84, 1.0, v86
	v_rcp_f32_e32 v84, v84
	v_rcp_f32_e32 v81, v81
	v_and_b32_e32 v85, 0xffff0000, v135
	v_lshlrev_b32_e32 v83, 16, v135
	v_mul_f32_e32 v79, v79, v84
	v_mul_f32_e32 v77, v77, v82
	v_mul_f32_e32 v78, v78, v81
	v_mul_f32_e32 v79, v79, v85
	v_mul_f32_e32 v72, v72, v80
	v_mul_f32_e32 v78, v78, v83
	v_cvt_pk_bf16_f32 v76, v76, v77
	v_cvt_pk_bf16_f32 v77, v78, v79
	v_mul_f32_e32 v79, 0xbfb8aa3b, v72
	v_exp_f32_e32 v79, v79
	v_mul_f32_e32 v73, v73, v80
	v_mul_f32_e32 v82, 0xbfb8aa3b, v73
	v_exp_f32_e32 v82, v82
	v_add_f32_e32 v79, 1.0, v79
	v_rcp_f32_e32 v79, v79
	global_store_dwordx2 v[124:125], v[76:77], off
	s_waitcnt vmcnt(15)
	v_lshlrev_b32_e32 v76, 16, v130
	v_mul_f32_e32 v74, v74, v80
	v_mul_f32_e32 v75, v75, v80
	v_mul_f32_e32 v72, v72, v79
	v_mul_f32_e32 v72, v72, v76
	v_add_f32_e32 v76, 1.0, v82
	v_mul_f32_e32 v79, 0xbfb8aa3b, v74
	v_mul_f32_e32 v82, 0xbfb8aa3b, v75
	v_rcp_f32_e32 v76, v76
	v_exp_f32_e32 v79, v79
	v_exp_f32_e32 v82, v82
	v_and_b32_e32 v77, 0xffff0000, v130
	v_mul_f32_e32 v73, v73, v76
	v_add_f32_e32 v76, 1.0, v79
	v_add_f32_e32 v79, 1.0, v82
	v_rcp_f32_e32 v79, v79
	v_rcp_f32_e32 v76, v76
	v_and_b32_e32 v81, 0xffff0000, v131
	v_lshlrev_b32_e32 v78, 16, v131
	v_mul_f32_e32 v75, v75, v79
	v_mul_f32_e32 v73, v73, v77
	v_mul_f32_e32 v74, v74, v76
	v_mul_f32_e32 v75, v75, v81
	v_mul_f32_e32 v68, v68, v80
	v_mul_f32_e32 v74, v74, v78
	v_cvt_pk_bf16_f32 v72, v72, v73
	v_cvt_pk_bf16_f32 v73, v74, v75
	v_mul_f32_e32 v75, 0xbfb8aa3b, v68
	v_exp_f32_e32 v75, v75
	v_mul_f32_e32 v69, v69, v80
	v_mul_f32_e32 v77, 0xbfb8aa3b, v69
	v_exp_f32_e32 v77, v77
	v_add_f32_e32 v75, 1.0, v75
	v_rcp_f32_e32 v75, v75
	global_store_dwordx2 v[124:125], v[72:73], off offset:32
	s_waitcnt vmcnt(15)
	v_lshlrev_b32_e32 v72, 16, v128
	v_mul_f32_e32 v70, v70, v80
	v_mul_f32_e32 v71, v71, v80
	v_mul_f32_e32 v68, v68, v75
	v_mul_f32_e32 v68, v68, v72
	v_add_f32_e32 v72, 1.0, v77
	v_mul_f32_e32 v75, 0xbfb8aa3b, v70
	v_mul_f32_e32 v77, 0xbfb8aa3b, v71
	v_rcp_f32_e32 v72, v72
	v_exp_f32_e32 v75, v75
	v_exp_f32_e32 v77, v77
	v_and_b32_e32 v73, 0xffff0000, v128
	v_mul_f32_e32 v69, v69, v72
	v_add_f32_e32 v72, 1.0, v75
	v_add_f32_e32 v75, 1.0, v77
	v_rcp_f32_e32 v75, v75
	v_rcp_f32_e32 v72, v72
	v_and_b32_e32 v76, 0xffff0000, v129
	v_lshlrev_b32_e32 v74, 16, v129
	v_mul_f32_e32 v71, v71, v75
	v_mul_f32_e32 v69, v69, v73
	v_mul_f32_e32 v70, v70, v72
	v_mul_f32_e32 v71, v71, v76
	v_mul_f32_e32 v64, v64, v80
	v_mul_f32_e32 v70, v70, v74
	v_cvt_pk_bf16_f32 v68, v68, v69
	v_cvt_pk_bf16_f32 v69, v70, v71
	v_mul_f32_e32 v71, 0xbfb8aa3b, v64
	v_exp_f32_e32 v71, v71
	v_mul_f32_e32 v65, v65, v80
	v_mul_f32_e32 v73, 0xbfb8aa3b, v65
	v_exp_f32_e32 v73, v73
	v_add_f32_e32 v71, 1.0, v71
	v_rcp_f32_e32 v71, v71
	global_store_dwordx2 v[124:125], v[68:69], off offset:64
	s_waitcnt vmcnt(15)
	v_lshlrev_b32_e32 v68, 16, v126
	v_mul_f32_e32 v66, v66, v80
	v_mul_f32_e32 v67, v67, v80
	v_mul_f32_e32 v64, v64, v71
	v_mul_f32_e32 v64, v64, v68
	v_add_f32_e32 v68, 1.0, v73
	v_mul_f32_e32 v71, 0xbfb8aa3b, v66
	v_mul_f32_e32 v73, 0xbfb8aa3b, v67
	v_rcp_f32_e32 v68, v68
	v_exp_f32_e32 v71, v71
	v_exp_f32_e32 v73, v73
	v_and_b32_e32 v69, 0xffff0000, v126
	v_mul_f32_e32 v65, v65, v68
	v_add_f32_e32 v68, 1.0, v71
	v_add_f32_e32 v71, 1.0, v73
	v_rcp_f32_e32 v68, v68
	v_rcp_f32_e32 v71, v71
	v_lshlrev_b32_e32 v70, 16, v127
	v_and_b32_e32 v72, 0xffff0000, v127
	v_mul_f32_e32 v65, v65, v69
	v_mul_f32_e32 v66, v66, v68
	v_mul_f32_e32 v67, v67, v71
	v_mul_f32_e32 v66, v66, v70
	v_mul_f32_e32 v67, v67, v72
	v_cvt_pk_bf16_f32 v64, v64, v65
	v_cvt_pk_bf16_f32 v65, v66, v67
	global_store_dwordx2 v[124:125], v[64:65], off offset:96
	v_or_b32_e32 v64, 64, v122
	v_ashrrev_i32_e32 v65, 31, v64
	v_lshl_add_u64 v[66:67], v[64:65], 2, s[0:1]
	v_lshlrev_b64 v[64:65], 12, v[64:65]
	v_lshl_add_u64 v[92:93], v[120:121], 0, v[64:65]
	v_or_b32_e32 v64, 0x50, v122
	v_ashrrev_i32_e32 v65, 31, v64
	global_load_dword v97, v[66:67], off
	global_load_dwordx2 v[98:99], v[92:93], off
	global_load_dwordx2 v[100:101], v[92:93], off offset:32
	global_load_dwordx2 v[102:103], v[92:93], off offset:64
	v_lshl_add_u64 v[66:67], v[64:65], 2, s[0:1]
	v_lshlrev_b64 v[64:65], 12, v[64:65]
	v_lshl_add_u64 v[82:83], v[120:121], 0, v[64:65]
	v_or_b32_e32 v64, 0x60, v122
	v_ashrrev_i32_e32 v65, 31, v64
	global_load_dwordx2 v[104:105], v[92:93], off offset:96
	global_load_dword v106, v[66:67], off
	global_load_dwordx2 v[94:95], v[82:83], off
	global_load_dwordx2 v[90:91], v[82:83], off offset:32
	v_lshl_add_u64 v[66:67], v[64:65], 2, s[0:1]
	v_lshlrev_b64 v[64:65], 12, v[64:65]
	v_lshl_add_u64 v[72:73], v[120:121], 0, v[64:65]
	v_or_b32_e32 v64, 0x70, v122
	v_ashrrev_i32_e32 v65, 31, v64
	global_load_dwordx2 v[88:89], v[82:83], off offset:64
	global_load_dwordx2 v[86:87], v[82:83], off offset:96
	global_load_dword v107, v[66:67], off
	global_load_dwordx2 v[84:85], v[72:73], off
	v_lshl_add_u64 v[66:67], v[64:65], 2, s[0:1]
	v_lshlrev_b64 v[64:65], 12, v[64:65]
	v_lshl_add_u64 v[64:65], v[120:121], 0, v[64:65]
	global_load_dwordx2 v[80:81], v[72:73], off offset:32
	global_load_dwordx2 v[78:79], v[72:73], off offset:64
	global_load_dwordx2 v[76:77], v[72:73], off offset:96
	global_load_dword v96, v[66:67], off
	global_load_dwordx2 v[74:75], v[64:65], off
	global_load_dwordx2 v[70:71], v[64:65], off offset:32
	global_load_dwordx2 v[68:69], v[64:65], off offset:64
	s_nop 0
	global_load_dwordx2 v[66:67], v[64:65], off offset:96
	s_waitcnt vmcnt(19)
	v_fmamk_f32 v97, v97, 0x3a800000, v167
	v_mul_f32_e32 v108, 0x4b800000, v97
	v_cmp_gt_f32_e32 vcc, s22, v97
	s_nop 1
	v_cndmask_b32_e32 v97, v97, v108, vcc
	v_rsq_f32_e32 v97, v97
	s_waitcnt vmcnt(18)
	v_lshlrev_b32_e32 v108, 16, v98
	v_and_b32_e32 v98, 0xffff0000, v98
	v_mul_f32_e32 v109, 0x45800000, v97
	v_cndmask_b32_e32 v97, v97, v109, vcc
	v_mul_f32_e32 v60, v60, v97
	v_mul_f32_e32 v110, 0xbfb8aa3b, v60
	v_exp_f32_e32 v110, v110
	v_mul_f32_e32 v61, v61, v97
	v_mul_f32_e32 v111, 0xbfb8aa3b, v61
	v_exp_f32_e32 v111, v111
	v_add_f32_e32 v110, 1.0, v110
	v_rcp_f32_e32 v110, v110
	v_mul_f32_e32 v62, v62, v97
	v_mul_f32_e32 v63, v63, v97
	v_lshlrev_b32_e32 v109, 16, v99
	v_mul_f32_e32 v60, v60, v110
	v_mul_f32_e32 v60, v60, v108
	v_add_f32_e32 v108, 1.0, v111
	v_mul_f32_e32 v110, 0xbfb8aa3b, v62
	v_mul_f32_e32 v111, 0xbfb8aa3b, v63
	v_rcp_f32_e32 v108, v108
	v_exp_f32_e32 v110, v110
	v_exp_f32_e32 v111, v111
	v_and_b32_e32 v99, 0xffff0000, v99
	v_mul_f32_e32 v61, v61, v108
	v_add_f32_e32 v108, 1.0, v110
	v_add_f32_e32 v110, 1.0, v111
	v_rcp_f32_e32 v110, v110
	v_rcp_f32_e32 v108, v108
	v_mul_f32_e32 v61, v61, v98
	v_mul_f32_e32 v56, v56, v97
	v_mul_f32_e32 v63, v63, v110
	v_mul_f32_e32 v62, v62, v108
	v_mul_f32_e32 v63, v63, v99
	v_mul_f32_e32 v62, v62, v109
	v_cvt_pk_bf16_f32 v60, v60, v61
	v_cvt_pk_bf16_f32 v61, v62, v63
	v_mul_f32_e32 v63, 0xbfb8aa3b, v56
	v_exp_f32_e32 v63, v63
	v_mul_f32_e32 v57, v57, v97
	v_mul_f32_e32 v99, 0xbfb8aa3b, v57
	v_exp_f32_e32 v99, v99
	v_add_f32_e32 v63, 1.0, v63
	v_rcp_f32_e32 v63, v63
	global_store_dwordx2 v[92:93], v[60:61], off
	s_waitcnt vmcnt(18)
	v_lshlrev_b32_e32 v60, 16, v100
	v_mul_f32_e32 v58, v58, v97
	v_mul_f32_e32 v59, v59, v97
	v_mul_f32_e32 v56, v56, v63
	v_mul_f32_e32 v56, v56, v60
	v_add_f32_e32 v60, 1.0, v99
	v_mul_f32_e32 v63, 0xbfb8aa3b, v58
	v_mul_f32_e32 v99, 0xbfb8aa3b, v59
	v_rcp_f32_e32 v60, v60
	v_exp_f32_e32 v63, v63
	v_exp_f32_e32 v99, v99
	v_and_b32_e32 v61, 0xffff0000, v100
	v_mul_f32_e32 v57, v57, v60
	v_add_f32_e32 v60, 1.0, v63
	v_add_f32_e32 v63, 1.0, v99
	v_rcp_f32_e32 v63, v63
	v_rcp_f32_e32 v60, v60
	v_and_b32_e32 v98, 0xffff0000, v101
	v_lshlrev_b32_e32 v62, 16, v101
	v_mul_f32_e32 v59, v59, v63
	v_mul_f32_e32 v57, v57, v61
	v_mul_f32_e32 v58, v58, v60
	v_mul_f32_e32 v59, v59, v98
	v_mul_f32_e32 v52, v52, v97
	v_mul_f32_e32 v58, v58, v62
	v_cvt_pk_bf16_f32 v56, v56, v57
	v_cvt_pk_bf16_f32 v57, v58, v59
	v_mul_f32_e32 v59, 0xbfb8aa3b, v52
	v_exp_f32_e32 v59, v59
	v_mul_f32_e32 v53, v53, v97
	v_mul_f32_e32 v61, 0xbfb8aa3b, v53
	v_exp_f32_e32 v61, v61
	v_add_f32_e32 v59, 1.0, v59
	v_rcp_f32_e32 v59, v59
	global_store_dwordx2 v[92:93], v[56:57], off offset:32
	s_waitcnt vmcnt(18)
	v_lshlrev_b32_e32 v56, 16, v102
	v_mul_f32_e32 v54, v54, v97
	v_mul_f32_e32 v55, v55, v97
	v_mul_f32_e32 v52, v52, v59
	v_mul_f32_e32 v52, v52, v56
	v_add_f32_e32 v56, 1.0, v61
	v_mul_f32_e32 v59, 0xbfb8aa3b, v54
	v_mul_f32_e32 v61, 0xbfb8aa3b, v55
	v_rcp_f32_e32 v56, v56
	v_exp_f32_e32 v59, v59
	v_exp_f32_e32 v61, v61
	v_and_b32_e32 v57, 0xffff0000, v102
	v_mul_f32_e32 v53, v53, v56
	v_add_f32_e32 v56, 1.0, v59
	v_add_f32_e32 v59, 1.0, v61
	v_rcp_f32_e32 v59, v59
	v_rcp_f32_e32 v56, v56
	v_and_b32_e32 v60, 0xffff0000, v103
	v_lshlrev_b32_e32 v58, 16, v103
	v_mul_f32_e32 v55, v55, v59
	v_mul_f32_e32 v53, v53, v57
	v_mul_f32_e32 v54, v54, v56
	v_mul_f32_e32 v55, v55, v60
	v_mul_f32_e32 v48, v48, v97
	v_mul_f32_e32 v54, v54, v58
	v_cvt_pk_bf16_f32 v52, v52, v53
	v_cvt_pk_bf16_f32 v53, v54, v55
	v_mul_f32_e32 v55, 0xbfb8aa3b, v48
	v_exp_f32_e32 v55, v55
	v_mul_f32_e32 v49, v49, v97
	v_mul_f32_e32 v57, 0xbfb8aa3b, v49
	v_exp_f32_e32 v57, v57
	v_add_f32_e32 v55, 1.0, v55
	v_rcp_f32_e32 v55, v55
	global_store_dwordx2 v[92:93], v[52:53], off offset:64
	s_waitcnt vmcnt(18)
	v_lshlrev_b32_e32 v52, 16, v104
	v_mul_f32_e32 v50, v50, v97
	v_mul_f32_e32 v48, v48, v55
	v_mul_f32_e32 v48, v48, v52
	v_add_f32_e32 v52, 1.0, v57
	v_mul_f32_e32 v55, 0xbfb8aa3b, v50
	v_rcp_f32_e32 v52, v52
	v_exp_f32_e32 v55, v55
	v_mul_f32_e32 v51, v51, v97
	v_mul_f32_e32 v57, 0xbfb8aa3b, v51
	v_mul_f32_e32 v49, v49, v52
	v_add_f32_e32 v52, 1.0, v55
	v_rcp_f32_e32 v52, v52
	v_exp_f32_e32 v57, v57
	v_and_b32_e32 v53, 0xffff0000, v104
	v_mul_f32_e32 v49, v49, v53
	v_mul_f32_e32 v50, v50, v52
	s_waitcnt vmcnt(17)
	v_fmamk_f32 v52, v106, 0x3a800000, v167
	v_add_f32_e32 v55, 1.0, v57
	v_mul_f32_e32 v53, 0x4b800000, v52
	v_cmp_gt_f32_e32 vcc, s22, v52
	v_rcp_f32_e32 v55, v55
	v_lshlrev_b32_e32 v54, 16, v105
	v_cndmask_b32_e32 v52, v52, v53, vcc
	v_rsq_f32_e32 v52, v52
	v_and_b32_e32 v56, 0xffff0000, v105
	v_mul_f32_e32 v51, v51, v55
	v_cvt_pk_bf16_f32 v48, v48, v49
	v_mul_f32_e32 v50, v50, v54
	v_mul_f32_e32 v51, v51, v56
	v_cvt_pk_bf16_f32 v49, v50, v51
	global_store_dwordx2 v[92:93], v[48:49], off offset:96
	v_mul_f32_e32 v48, 0x45800000, v52
	v_cndmask_b32_e32 v48, v52, v48, vcc
	v_mul_f32_e32 v44, v44, v48
	v_mul_f32_e32 v52, 0xbfb8aa3b, v44
	v_exp_f32_e32 v52, v52
	v_mul_f32_e32 v45, v45, v48
	v_mul_f32_e32 v54, 0xbfb8aa3b, v45
	v_exp_f32_e32 v54, v54
	v_add_f32_e32 v52, 1.0, v52
	v_rcp_f32_e32 v52, v52
	s_waitcnt vmcnt(17)
	v_lshlrev_b32_e32 v49, 16, v94
	v_mul_f32_e32 v46, v46, v48
	v_mul_f32_e32 v47, v47, v48
	v_mul_f32_e32 v44, v44, v52
	v_mul_f32_e32 v44, v44, v49
	v_add_f32_e32 v49, 1.0, v54
	v_mul_f32_e32 v52, 0xbfb8aa3b, v46
	v_mul_f32_e32 v54, 0xbfb8aa3b, v47
	v_rcp_f32_e32 v49, v49
	v_exp_f32_e32 v52, v52
	v_exp_f32_e32 v54, v54
	v_and_b32_e32 v50, 0xffff0000, v94
	v_mul_f32_e32 v45, v45, v49
	v_add_f32_e32 v49, 1.0, v52
	v_add_f32_e32 v52, 1.0, v54
	v_rcp_f32_e32 v52, v52
	v_rcp_f32_e32 v49, v49
	v_and_b32_e32 v53, 0xffff0000, v95
	v_lshlrev_b32_e32 v51, 16, v95
	v_mul_f32_e32 v47, v47, v52
	v_mul_f32_e32 v45, v45, v50
	v_mul_f32_e32 v46, v46, v49
	v_mul_f32_e32 v47, v47, v53
	v_mul_f32_e32 v40, v40, v48
	v_mul_f32_e32 v46, v46, v51
	v_cvt_pk_bf16_f32 v44, v44, v45
	v_cvt_pk_bf16_f32 v45, v46, v47
	v_mul_f32_e32 v47, 0xbfb8aa3b, v40
	v_exp_f32_e32 v47, v47
	v_mul_f32_e32 v41, v41, v48
	v_mul_f32_e32 v50, 0xbfb8aa3b, v41
	v_exp_f32_e32 v50, v50
	v_add_f32_e32 v47, 1.0, v47
	v_rcp_f32_e32 v47, v47
	global_store_dwordx2 v[82:83], v[44:45], off
	s_waitcnt vmcnt(17)
	v_lshlrev_b32_e32 v44, 16, v90
	v_mul_f32_e32 v42, v42, v48
	v_mul_f32_e32 v43, v43, v48
	v_mul_f32_e32 v40, v40, v47
	v_mul_f32_e32 v40, v40, v44
	v_add_f32_e32 v44, 1.0, v50
	v_mul_f32_e32 v47, 0xbfb8aa3b, v42
	v_mul_f32_e32 v50, 0xbfb8aa3b, v43
	v_rcp_f32_e32 v44, v44
	v_exp_f32_e32 v47, v47
	v_exp_f32_e32 v50, v50
	v_and_b32_e32 v45, 0xffff0000, v90
	v_mul_f32_e32 v41, v41, v44
	v_add_f32_e32 v44, 1.0, v47
	v_add_f32_e32 v47, 1.0, v50
	v_rcp_f32_e32 v47, v47
	v_rcp_f32_e32 v44, v44
	v_and_b32_e32 v49, 0xffff0000, v91
	v_lshlrev_b32_e32 v46, 16, v91
	v_mul_f32_e32 v43, v43, v47
	v_mul_f32_e32 v41, v41, v45
	v_mul_f32_e32 v42, v42, v44
	v_mul_f32_e32 v43, v43, v49
	v_mul_f32_e32 v36, v36, v48
	v_mul_f32_e32 v42, v42, v46
	v_cvt_pk_bf16_f32 v40, v40, v41
	v_cvt_pk_bf16_f32 v41, v42, v43
	v_mul_f32_e32 v43, 0xbfb8aa3b, v36
	v_exp_f32_e32 v43, v43
	v_mul_f32_e32 v37, v37, v48
	v_mul_f32_e32 v45, 0xbfb8aa3b, v37
	v_exp_f32_e32 v45, v45
	v_add_f32_e32 v43, 1.0, v43
	v_rcp_f32_e32 v43, v43
	global_store_dwordx2 v[82:83], v[40:41], off offset:32
	s_waitcnt vmcnt(17)
	v_lshlrev_b32_e32 v40, 16, v88
	v_mul_f32_e32 v38, v38, v48
	v_mul_f32_e32 v39, v39, v48
	v_mul_f32_e32 v36, v36, v43
	v_mul_f32_e32 v36, v36, v40
	v_add_f32_e32 v40, 1.0, v45
	v_mul_f32_e32 v43, 0xbfb8aa3b, v38
	v_mul_f32_e32 v45, 0xbfb8aa3b, v39
	v_rcp_f32_e32 v40, v40
	v_exp_f32_e32 v43, v43
	v_exp_f32_e32 v45, v45
	v_and_b32_e32 v41, 0xffff0000, v88
	v_mul_f32_e32 v37, v37, v40
	v_add_f32_e32 v40, 1.0, v43
	v_add_f32_e32 v43, 1.0, v45
	v_rcp_f32_e32 v43, v43
	v_rcp_f32_e32 v40, v40
	v_and_b32_e32 v44, 0xffff0000, v89
	v_lshlrev_b32_e32 v42, 16, v89
	v_mul_f32_e32 v39, v39, v43
	v_mul_f32_e32 v37, v37, v41
	v_mul_f32_e32 v38, v38, v40
	v_mul_f32_e32 v39, v39, v44
	v_mul_f32_e32 v32, v32, v48
	v_mul_f32_e32 v38, v38, v42
	v_cvt_pk_bf16_f32 v36, v36, v37
	v_cvt_pk_bf16_f32 v37, v38, v39
	v_mul_f32_e32 v39, 0xbfb8aa3b, v32
	v_exp_f32_e32 v39, v39
	v_mul_f32_e32 v33, v33, v48
	v_mul_f32_e32 v41, 0xbfb8aa3b, v33
	v_exp_f32_e32 v41, v41
	v_add_f32_e32 v39, 1.0, v39
	v_rcp_f32_e32 v39, v39
	global_store_dwordx2 v[82:83], v[36:37], off offset:64
	s_waitcnt vmcnt(17)
	v_lshlrev_b32_e32 v36, 16, v86
	v_mul_f32_e32 v34, v34, v48
	v_mul_f32_e32 v32, v32, v39
	v_mul_f32_e32 v32, v32, v36
	v_add_f32_e32 v36, 1.0, v41
	v_mul_f32_e32 v39, 0xbfb8aa3b, v34
	v_rcp_f32_e32 v36, v36
	v_exp_f32_e32 v39, v39
	v_mul_f32_e32 v35, v35, v48
	v_mul_f32_e32 v41, 0xbfb8aa3b, v35
	v_mul_f32_e32 v33, v33, v36
	v_add_f32_e32 v36, 1.0, v39
	v_rcp_f32_e32 v36, v36
	v_exp_f32_e32 v41, v41
	v_and_b32_e32 v37, 0xffff0000, v86
	v_mul_f32_e32 v33, v33, v37
	v_mul_f32_e32 v34, v34, v36
	s_waitcnt vmcnt(16)
	v_fmamk_f32 v36, v107, 0x3a800000, v167
	v_add_f32_e32 v39, 1.0, v41
	v_mul_f32_e32 v37, 0x4b800000, v36
	v_cmp_gt_f32_e32 vcc, s22, v36
	v_rcp_f32_e32 v39, v39
	v_lshlrev_b32_e32 v38, 16, v87
	v_cndmask_b32_e32 v36, v36, v37, vcc
	v_rsq_f32_e32 v36, v36
	v_and_b32_e32 v40, 0xffff0000, v87
	v_mul_f32_e32 v35, v35, v39
	v_cvt_pk_bf16_f32 v32, v32, v33
	v_mul_f32_e32 v34, v34, v38
	v_mul_f32_e32 v35, v35, v40
	v_cvt_pk_bf16_f32 v33, v34, v35
	global_store_dwordx2 v[82:83], v[32:33], off offset:96
	v_mul_f32_e32 v32, 0x45800000, v36
	v_cndmask_b32_e32 v32, v36, v32, vcc
	v_mul_f32_e32 v28, v28, v32
	v_mul_f32_e32 v36, 0xbfb8aa3b, v28
	v_exp_f32_e32 v36, v36
	v_mul_f32_e32 v29, v29, v32
	v_mul_f32_e32 v38, 0xbfb8aa3b, v29
	v_exp_f32_e32 v38, v38
	v_add_f32_e32 v36, 1.0, v36
	v_rcp_f32_e32 v36, v36
	s_waitcnt vmcnt(16)
	v_lshlrev_b32_e32 v33, 16, v84
	v_mul_f32_e32 v30, v30, v32
	v_mul_f32_e32 v31, v31, v32
	v_mul_f32_e32 v28, v28, v36
	v_mul_f32_e32 v28, v28, v33
	v_add_f32_e32 v33, 1.0, v38
	v_mul_f32_e32 v36, 0xbfb8aa3b, v30
	v_mul_f32_e32 v38, 0xbfb8aa3b, v31
	v_rcp_f32_e32 v33, v33
	v_exp_f32_e32 v36, v36
	v_exp_f32_e32 v38, v38
	v_and_b32_e32 v34, 0xffff0000, v84
	v_mul_f32_e32 v29, v29, v33
	v_add_f32_e32 v33, 1.0, v36
	v_add_f32_e32 v36, 1.0, v38
	v_rcp_f32_e32 v36, v36
	v_rcp_f32_e32 v33, v33
	v_and_b32_e32 v37, 0xffff0000, v85
	v_lshlrev_b32_e32 v35, 16, v85
	v_mul_f32_e32 v31, v31, v36
	v_mul_f32_e32 v29, v29, v34
	v_mul_f32_e32 v30, v30, v33
	v_mul_f32_e32 v31, v31, v37
	v_mul_f32_e32 v24, v24, v32
	v_mul_f32_e32 v30, v30, v35
	v_cvt_pk_bf16_f32 v28, v28, v29
	v_cvt_pk_bf16_f32 v29, v30, v31
	v_mul_f32_e32 v31, 0xbfb8aa3b, v24
	v_exp_f32_e32 v31, v31
	v_mul_f32_e32 v25, v25, v32
	v_mul_f32_e32 v34, 0xbfb8aa3b, v25
	v_exp_f32_e32 v34, v34
	v_add_f32_e32 v31, 1.0, v31
	v_rcp_f32_e32 v31, v31
	global_store_dwordx2 v[72:73], v[28:29], off
	s_waitcnt vmcnt(16)
	v_lshlrev_b32_e32 v28, 16, v80
	v_mul_f32_e32 v26, v26, v32
	v_mul_f32_e32 v27, v27, v32
	v_mul_f32_e32 v24, v24, v31
	v_mul_f32_e32 v24, v24, v28
	v_add_f32_e32 v28, 1.0, v34
	v_mul_f32_e32 v31, 0xbfb8aa3b, v26
	v_mul_f32_e32 v34, 0xbfb8aa3b, v27
	v_rcp_f32_e32 v28, v28
	v_exp_f32_e32 v31, v31
	v_exp_f32_e32 v34, v34
	v_and_b32_e32 v29, 0xffff0000, v80
	v_mul_f32_e32 v25, v25, v28
	v_add_f32_e32 v28, 1.0, v31
	v_add_f32_e32 v31, 1.0, v34
	v_rcp_f32_e32 v31, v31
	v_rcp_f32_e32 v28, v28
	v_and_b32_e32 v33, 0xffff0000, v81
	v_lshlrev_b32_e32 v30, 16, v81
	v_mul_f32_e32 v27, v27, v31
	v_mul_f32_e32 v25, v25, v29
	v_mul_f32_e32 v26, v26, v28
	v_mul_f32_e32 v27, v27, v33
	v_mul_f32_e32 v20, v20, v32
	v_mul_f32_e32 v26, v26, v30
	v_cvt_pk_bf16_f32 v24, v24, v25
	v_cvt_pk_bf16_f32 v25, v26, v27
	v_mul_f32_e32 v27, 0xbfb8aa3b, v20
	v_exp_f32_e32 v27, v27
	v_mul_f32_e32 v21, v21, v32
	v_mul_f32_e32 v29, 0xbfb8aa3b, v21
	v_exp_f32_e32 v29, v29
	v_add_f32_e32 v27, 1.0, v27
	v_rcp_f32_e32 v27, v27
	global_store_dwordx2 v[72:73], v[24:25], off offset:32
	s_waitcnt vmcnt(16)
	v_lshlrev_b32_e32 v24, 16, v78
	v_mul_f32_e32 v22, v22, v32
	v_mul_f32_e32 v23, v23, v32
	v_mul_f32_e32 v20, v20, v27
	v_mul_f32_e32 v20, v20, v24
	v_add_f32_e32 v24, 1.0, v29
	v_mul_f32_e32 v27, 0xbfb8aa3b, v22
	v_mul_f32_e32 v29, 0xbfb8aa3b, v23
	v_rcp_f32_e32 v24, v24
	v_exp_f32_e32 v27, v27
	v_exp_f32_e32 v29, v29
	v_and_b32_e32 v25, 0xffff0000, v78
	v_mul_f32_e32 v21, v21, v24
	v_add_f32_e32 v24, 1.0, v27
	v_add_f32_e32 v27, 1.0, v29
	v_rcp_f32_e32 v27, v27
	v_rcp_f32_e32 v24, v24
	v_and_b32_e32 v28, 0xffff0000, v79
	v_lshlrev_b32_e32 v26, 16, v79
	v_mul_f32_e32 v23, v23, v27
	v_mul_f32_e32 v21, v21, v25
	v_mul_f32_e32 v22, v22, v24
	v_mul_f32_e32 v23, v23, v28
	v_mul_f32_e32 v16, v16, v32
	v_mul_f32_e32 v22, v22, v26
	v_cvt_pk_bf16_f32 v20, v20, v21
	v_cvt_pk_bf16_f32 v21, v22, v23
	v_mul_f32_e32 v23, 0xbfb8aa3b, v16
	v_exp_f32_e32 v23, v23
	v_mul_f32_e32 v17, v17, v32
	v_mul_f32_e32 v25, 0xbfb8aa3b, v17
	v_exp_f32_e32 v25, v25
	v_add_f32_e32 v23, 1.0, v23
	v_rcp_f32_e32 v23, v23
	global_store_dwordx2 v[72:73], v[20:21], off offset:64
	s_waitcnt vmcnt(16)
	v_lshlrev_b32_e32 v20, 16, v76
	v_mul_f32_e32 v18, v18, v32
	v_mul_f32_e32 v16, v16, v23
	v_mul_f32_e32 v16, v16, v20
	v_add_f32_e32 v20, 1.0, v25
	v_mul_f32_e32 v23, 0xbfb8aa3b, v18
	v_rcp_f32_e32 v20, v20
	v_exp_f32_e32 v23, v23
	v_mul_f32_e32 v19, v19, v32
	v_mul_f32_e32 v25, 0xbfb8aa3b, v19
	v_mul_f32_e32 v17, v17, v20
	v_add_f32_e32 v20, 1.0, v23
	v_rcp_f32_e32 v20, v20
	v_exp_f32_e32 v25, v25
	v_and_b32_e32 v21, 0xffff0000, v76
	v_mul_f32_e32 v17, v17, v21
	v_mul_f32_e32 v18, v18, v20
	s_waitcnt vmcnt(15)
	v_fmamk_f32 v20, v96, 0x3a800000, v167
	v_add_f32_e32 v23, 1.0, v25
	v_mul_f32_e32 v21, 0x4b800000, v20
	v_cmp_gt_f32_e32 vcc, s22, v20
	v_rcp_f32_e32 v23, v23
	v_lshlrev_b32_e32 v22, 16, v77
	v_cndmask_b32_e32 v20, v20, v21, vcc
	v_rsq_f32_e32 v20, v20
	v_and_b32_e32 v24, 0xffff0000, v77
	v_mul_f32_e32 v19, v19, v23
	v_cvt_pk_bf16_f32 v16, v16, v17
	v_mul_f32_e32 v18, v18, v22
	v_mul_f32_e32 v19, v19, v24
	v_cvt_pk_bf16_f32 v17, v18, v19
	global_store_dwordx2 v[72:73], v[16:17], off offset:96
	v_mul_f32_e32 v16, 0x45800000, v20
	v_cndmask_b32_e32 v16, v20, v16, vcc
	v_mul_f32_e32 v12, v12, v16
	v_mul_f32_e32 v20, 0xbfb8aa3b, v12
	v_exp_f32_e32 v20, v20
	v_mul_f32_e32 v13, v13, v16
	v_mul_f32_e32 v22, 0xbfb8aa3b, v13
	v_exp_f32_e32 v22, v22
	v_add_f32_e32 v20, 1.0, v20
	v_rcp_f32_e32 v20, v20
	s_waitcnt vmcnt(15)
	v_lshlrev_b32_e32 v17, 16, v74
	v_mul_f32_e32 v14, v14, v16
	v_mul_f32_e32 v15, v15, v16
	v_mul_f32_e32 v12, v12, v20
	v_mul_f32_e32 v12, v12, v17
	v_add_f32_e32 v17, 1.0, v22
	v_mul_f32_e32 v20, 0xbfb8aa3b, v14
	v_mul_f32_e32 v22, 0xbfb8aa3b, v15
	v_rcp_f32_e32 v17, v17
	v_exp_f32_e32 v20, v20
	v_exp_f32_e32 v22, v22
	v_and_b32_e32 v18, 0xffff0000, v74
	v_mul_f32_e32 v13, v13, v17
	v_add_f32_e32 v17, 1.0, v20
	v_add_f32_e32 v20, 1.0, v22
	v_rcp_f32_e32 v20, v20
	v_rcp_f32_e32 v17, v17
	v_and_b32_e32 v21, 0xffff0000, v75
	v_lshlrev_b32_e32 v19, 16, v75
	v_mul_f32_e32 v15, v15, v20
	v_mul_f32_e32 v13, v13, v18
	v_mul_f32_e32 v14, v14, v17
	v_mul_f32_e32 v15, v15, v21
	v_mul_f32_e32 v8, v8, v16
	v_mul_f32_e32 v14, v14, v19
	v_cvt_pk_bf16_f32 v12, v12, v13
	v_cvt_pk_bf16_f32 v13, v14, v15
	v_mul_f32_e32 v15, 0xbfb8aa3b, v8
	v_exp_f32_e32 v15, v15
	v_mul_f32_e32 v9, v9, v16
	v_mul_f32_e32 v18, 0xbfb8aa3b, v9
	v_exp_f32_e32 v18, v18
	v_add_f32_e32 v15, 1.0, v15
	v_rcp_f32_e32 v15, v15
	global_store_dwordx2 v[64:65], v[12:13], off
	s_waitcnt vmcnt(15)
	v_lshlrev_b32_e32 v12, 16, v70
	v_mul_f32_e32 v10, v10, v16
	v_mul_f32_e32 v11, v11, v16
	v_mul_f32_e32 v8, v8, v15
	v_mul_f32_e32 v8, v8, v12
	v_add_f32_e32 v12, 1.0, v18
	v_mul_f32_e32 v15, 0xbfb8aa3b, v10
	v_mul_f32_e32 v18, 0xbfb8aa3b, v11
	v_rcp_f32_e32 v12, v12
	v_exp_f32_e32 v15, v15
	v_exp_f32_e32 v18, v18
	v_and_b32_e32 v13, 0xffff0000, v70
	v_mul_f32_e32 v9, v9, v12
	v_add_f32_e32 v12, 1.0, v15
	v_add_f32_e32 v15, 1.0, v18
	v_rcp_f32_e32 v15, v15
	v_rcp_f32_e32 v12, v12
	v_and_b32_e32 v17, 0xffff0000, v71
	v_lshlrev_b32_e32 v14, 16, v71
	v_mul_f32_e32 v11, v11, v15
	v_mul_f32_e32 v9, v9, v13
	v_mul_f32_e32 v10, v10, v12
	v_mul_f32_e32 v11, v11, v17
	v_mul_f32_e32 v4, v4, v16
	v_mul_f32_e32 v10, v10, v14
	v_cvt_pk_bf16_f32 v8, v8, v9
	v_cvt_pk_bf16_f32 v9, v10, v11
	v_mul_f32_e32 v11, 0xbfb8aa3b, v4
	v_exp_f32_e32 v11, v11
	v_mul_f32_e32 v5, v5, v16
	v_mul_f32_e32 v13, 0xbfb8aa3b, v5
	v_exp_f32_e32 v13, v13
	v_add_f32_e32 v11, 1.0, v11
	v_rcp_f32_e32 v11, v11
	global_store_dwordx2 v[64:65], v[8:9], off offset:32
	s_waitcnt vmcnt(15)
	v_lshlrev_b32_e32 v8, 16, v68
	v_mul_f32_e32 v6, v6, v16
	v_mul_f32_e32 v7, v7, v16
	v_mul_f32_e32 v4, v4, v11
	v_mul_f32_e32 v4, v4, v8
	v_add_f32_e32 v8, 1.0, v13
	v_mul_f32_e32 v11, 0xbfb8aa3b, v6
	v_mul_f32_e32 v13, 0xbfb8aa3b, v7
	v_rcp_f32_e32 v8, v8
	v_exp_f32_e32 v11, v11
	v_exp_f32_e32 v13, v13
	v_and_b32_e32 v9, 0xffff0000, v68
	v_mul_f32_e32 v5, v5, v8
	v_add_f32_e32 v8, 1.0, v11
	v_add_f32_e32 v11, 1.0, v13
	v_rcp_f32_e32 v11, v11
	v_rcp_f32_e32 v8, v8
	v_and_b32_e32 v12, 0xffff0000, v69
	v_lshlrev_b32_e32 v10, 16, v69
	v_mul_f32_e32 v7, v7, v11
	v_mul_f32_e32 v5, v5, v9
	v_mul_f32_e32 v6, v6, v8
	v_mul_f32_e32 v7, v7, v12
	v_mul_f32_e32 v0, v0, v16
	v_mul_f32_e32 v6, v6, v10
	v_cvt_pk_bf16_f32 v4, v4, v5
	v_cvt_pk_bf16_f32 v5, v6, v7
	v_mul_f32_e32 v7, 0xbfb8aa3b, v0
	v_exp_f32_e32 v7, v7
	v_mul_f32_e32 v1, v1, v16
	v_mul_f32_e32 v9, 0xbfb8aa3b, v1
	v_exp_f32_e32 v9, v9
	v_add_f32_e32 v7, 1.0, v7
	v_rcp_f32_e32 v7, v7
	global_store_dwordx2 v[64:65], v[4:5], off offset:64
	s_waitcnt vmcnt(15)
	v_lshlrev_b32_e32 v4, 16, v66
	v_mul_f32_e32 v2, v2, v16
	v_mul_f32_e32 v3, v3, v16
	v_mul_f32_e32 v0, v0, v7
	v_mul_f32_e32 v0, v0, v4
	v_add_f32_e32 v4, 1.0, v9
	v_mul_f32_e32 v7, 0xbfb8aa3b, v2
	v_mul_f32_e32 v9, 0xbfb8aa3b, v3
	v_rcp_f32_e32 v4, v4
	v_exp_f32_e32 v7, v7
	v_exp_f32_e32 v9, v9
	v_and_b32_e32 v5, 0xffff0000, v66
	v_mul_f32_e32 v1, v1, v4
	v_add_f32_e32 v4, 1.0, v7
	v_add_f32_e32 v7, 1.0, v9
	v_rcp_f32_e32 v4, v4
	v_rcp_f32_e32 v7, v7
	v_lshlrev_b32_e32 v6, 16, v67
	v_and_b32_e32 v8, 0xffff0000, v67
	v_mul_f32_e32 v1, v1, v5
	v_mul_f32_e32 v2, v2, v4
	v_mul_f32_e32 v3, v3, v7
	v_mul_f32_e32 v2, v2, v6
	v_mul_f32_e32 v3, v3, v8
	v_cvt_pk_bf16_f32 v0, v0, v1
	v_cvt_pk_bf16_f32 v1, v2, v3
	global_store_dwordx2 v[64:65], v[0:1], off offset:96
	s_add_i32 s23, s23, s74
	s_cmpk_lt_i32 s23, 0x800
	s_cbranch_scc1 .LBB0_1736
